# GEMM K loops (14): loop-counter / pointer / exit-test SALU moved in front of the loop-back s_barrier; only the branch follows the barrier
# speedup vs baseline: 1.0001x; 1.0001x over previous
; #define PG8_STAGE(bufoff, gbase, voff) do { _Pragma("unroll") for (int _i = 0; _i < 2; ++_i) \
;         __builtin_amdgcn_global_load_lds((const unsigned*)((const char*)(gbase) + (voff)[_i]), (LAS unsigned*)(lds + (bufoff) + ldsw + _i * 8192), 16, 0, 0); } while (0)
; #define PG8_LDA(dst, b, h) do { _Pragma("unroll") for (int m = 0; m < 4; ++m) _Pragma("unroll") for (int k = 0; k < 2; ++k) dst[m][k] = *(const LAS bf16x8*)(lds + PG8_SA(b, h) + aoff + m * 2048 + k * 1024); } while (0)
; #define PG8_LDB(dst, b, h) do { _Pragma("unroll") for (int n = 0; n < 2; ++n) _Pragma("unroll") for (int k = 0; k < 2; ++k) dst[n][k] = *(const LAS bf16x8*)(lds + PG8_SB(b, h) + boff + n * 2048 + k * 1024); } while (0)
; #define PG8_MMA(ai, bj, At, Bt) do { __builtin_amdgcn_s_setprio(1); _Pragma("unroll") for (int m = 0; m < 4; ++m) _Pragma("unroll") for (int n = 0; n < 2; ++n) _Pragma("unroll") for (int k = 0; k < 2; ++k) \
;         acc[ai][bj][m][n] = __builtin_amdgcn_mfma_f32_16x16x32_bf16(Bt[n][k], At[m][k], acc[ai][bj][m][n], 0, 0, 0); __builtin_amdgcn_s_setprio(0); } while (0)
; #define PG8_WAIT_V(n) asm volatile("s_waitcnt vmcnt(" #n ")" ::: "memory")
; #define PG8_WAIT_L(n) asm volatile("s_waitcnt lgkmcnt(" #n ")" ::: "memory")
; #define PG8_BAR __builtin_amdgcn_s_barrier()
; #define PG8_SCHED __builtin_amdgcn_sched_barrier(0)
; template <class Epi>
; __device__ __forceinline__ void gemm_phase(LAS unsigned char* lds, const Gemm g, const Sched& S, const Epi& E) {
;     ...
;             PG8_LDB(B0, 0, 0); PG8_LDB(B1, 0, 1); PG8_SCHED; PG8_LDA(At, 0, 0); PG8_STAGE(PG8_SA(1, 1), a1 + hstepA, voffA);
;             PG8_WAIT_V(8); PG8_WAIT_L(0); PG8_BAR; PG8_MMA(0, 0, At, B0); PG8_MMA(0, 1, At, B1); PG8_BAR; PG8_SCHED;
;             PG8_LDA(At, 0, 1); PG8_STAGE(PG8_SB(0, 0), b2, voffB); PG8_STAGE(PG8_SB(0, 1), b2 + hstepB, voffB); PG8_STAGE(PG8_SA(0, 0), a2, voffA);
;             PG8_WAIT_V(8); PG8_WAIT_L(0); PG8_BAR; PG8_MMA(1, 0, At, B0); PG8_MMA(1, 1, At, B1); PG8_BAR; PG8_SCHED;
.LBB0_163:
	ds_read_b128 v[148:151], v145
	ds_read_b128 v[152:155], v145 offset:1024
	ds_read_b128 v[156:159], v145 offset:2048
	ds_read_b128 v[160:163], v145 offset:3072
	ds_read_b128 v[164:167], v146
	ds_read_b128 v[168:171], v146 offset:1024
	ds_read_b128 v[172:175], v146 offset:2048
	ds_read_b128 v[176:179], v146 offset:3072
	s_add_u32 s44, s40, 0xfffc0080
	s_addc_u32 s45, s41, -1
	s_cmp_eq_u32 s67, 12
	s_cselect_b32 s47, s21, s45
	s_cselect_b32 s46, s27, s44
	s_cselect_b32 s45, s15, s66
	s_cselect_b32 s44, s64, s65
	v_lshl_add_u64 v[140:141], s[40:41], 0, v[136:137]
	s_add_i32 m0, s29, 0xc000
	ds_read_b128 v[180:183], v147
	ds_read_b128 v[184:187], v147 offset:1024
	ds_read_b128 v[188:191], v147 offset:2048
	ds_read_b128 v[192:195], v147 offset:3072
	ds_read_b128 v[196:199], v147 offset:4096
	ds_read_b128 v[204:207], v147 offset:5120
	ds_read_b128 v[208:211], v147 offset:6144
	ds_read_b128 v[212:215], v147 offset:7168
	global_load_lds_dwordx4 v[140:141], off
	v_lshl_add_u64 v[140:141], s[40:41], 0, v[138:139]
	s_add_i32 m0, s29, 0xe000
	s_nop 0
	global_load_lds_dwordx4 v[140:141], off
	s_waitcnt vmcnt(8)
	s_waitcnt lgkmcnt(0)
	s_barrier
	s_waitcnt lgkmcnt(0)
	v_mfma_f32_16x16x32_bf16 v[116:119], v[148:151], v[180:183], v[116:119]
	v_mfma_f32_16x16x32_bf16 v[124:127], v[156:159], v[180:183], v[124:127]
	v_mfma_f32_16x16x32_bf16 v[100:103], v[148:151], v[188:191], v[100:103]
	v_mfma_f32_16x16x32_bf16 v[108:111], v[156:159], v[188:191], v[108:111]
	v_mfma_f32_16x16x32_bf16 v[84:87], v[148:151], v[196:199], v[84:87]
	v_mfma_f32_16x16x32_bf16 v[92:95], v[156:159], v[196:199], v[92:95]
	v_mfma_f32_16x16x32_bf16 v[68:71], v[148:151], v[208:211], v[68:71]
	v_mfma_f32_16x16x32_bf16 v[76:79], v[156:159], v[208:211], v[76:79]
	v_mfma_f32_16x16x32_bf16 v[116:119], v[152:155], v[184:187], v[116:119]
	v_mfma_f32_16x16x32_bf16 v[124:127], v[160:163], v[184:187], v[124:127]
	v_mfma_f32_16x16x32_bf16 v[100:103], v[152:155], v[192:195], v[100:103]
	v_mfma_f32_16x16x32_bf16 v[108:111], v[160:163], v[192:195], v[108:111]
	v_mfma_f32_16x16x32_bf16 v[84:87], v[152:155], v[204:207], v[84:87]
	v_mfma_f32_16x16x32_bf16 v[92:95], v[160:163], v[204:207], v[92:95]
	v_mfma_f32_16x16x32_bf16 v[68:71], v[152:155], v[212:215], v[68:71]
	v_mfma_f32_16x16x32_bf16 v[76:79], v[160:163], v[212:215], v[76:79]
	v_mfma_f32_16x16x32_bf16 v[112:115], v[164:167], v[180:183], v[112:115]
	v_mfma_f32_16x16x32_bf16 v[120:123], v[172:175], v[180:183], v[120:123]
	v_mfma_f32_16x16x32_bf16 v[96:99], v[164:167], v[188:191], v[96:99]
	v_mfma_f32_16x16x32_bf16 v[104:107], v[172:175], v[188:191], v[104:107]
	v_mfma_f32_16x16x32_bf16 v[80:83], v[164:167], v[196:199], v[80:83]
	v_mfma_f32_16x16x32_bf16 v[88:91], v[172:175], v[196:199], v[88:91]
	v_mfma_f32_16x16x32_bf16 v[64:67], v[164:167], v[208:211], v[64:67]
	v_mfma_f32_16x16x32_bf16 v[72:75], v[172:175], v[208:211], v[72:75]
	v_mfma_f32_16x16x32_bf16 v[112:115], v[168:171], v[184:187], v[112:115]
	v_mfma_f32_16x16x32_bf16 v[120:123], v[176:179], v[184:187], v[120:123]
	v_mfma_f32_16x16x32_bf16 v[96:99], v[168:171], v[192:195], v[96:99]
	v_mfma_f32_16x16x32_bf16 v[104:107], v[176:179], v[192:195], v[104:107]
	v_mfma_f32_16x16x32_bf16 v[80:83], v[168:171], v[204:207], v[80:83]
	v_mfma_f32_16x16x32_bf16 v[88:91], v[176:179], v[204:207], v[88:91]
	v_mfma_f32_16x16x32_bf16 v[64:67], v[168:171], v[212:215], v[64:67]
	v_mfma_f32_16x16x32_bf16 v[72:75], v[176:179], v[212:215], v[72:75]
	s_barrier
	s_add_i32 s78, s60, s53
	v_lshl_add_u64 v[140:141], s[44:45], 0, v[130:131]
	s_mov_b32 m0, s78
	ds_read_b128 v[180:183], v147 offset:16384
	ds_read_b128 v[184:187], v147 offset:17408
	ds_read_b128 v[188:191], v147 offset:18432
	ds_read_b128 v[192:195], v147 offset:19456
	ds_read_b128 v[196:199], v147 offset:20480
	ds_read_b128 v[204:207], v147 offset:21504
	ds_read_b128 v[208:211], v147 offset:22528
	ds_read_b128 v[212:215], v147 offset:23552
	global_load_lds_dwordx4 v[140:141], off
	s_add_i32 m0, s78, 0x2000
	s_add_u32 s78, s44, 0x40000
	v_lshl_add_u64 v[200:201], s[44:45], 0, v[134:135]
	s_addc_u32 s79, s45, 0
	s_add_i32 s82, s61, s53
	global_load_lds_dwordx4 v[200:201], off
	v_lshl_add_u64 v[216:217], s[78:79], 0, v[130:131]
	s_mov_b32 m0, s82
	v_lshl_add_u64 v[218:219], s[46:47], 0, v[132:133]
	global_load_lds_dwordx4 v[216:217], off
	v_lshl_add_u64 v[216:217], s[78:79], 0, v[134:135]
	s_add_i32 m0, s82, 0x2000
	s_nop 0
	global_load_lds_dwordx4 v[216:217], off
	v_lshl_add_u64 v[216:217], s[46:47], 0, v[128:129]
	s_mov_b32 m0, s29
	s_nop 0
	global_load_lds_dwordx4 v[216:217], off
	s_mov_b32 m0, s54
	s_nop 0
	global_load_lds_dwordx4 v[218:219], off
	s_waitcnt vmcnt(8)
	s_waitcnt lgkmcnt(0)
	s_barrier
; #define PG8_STAGE(bufoff, gbase, voff) do { _Pragma("unroll") for (int _i = 0; _i < 2; ++_i) \
;         __builtin_amdgcn_global_load_lds((const unsigned*)((const char*)(gbase) + (voff)[_i]), (LAS unsigned*)(lds + (bufoff) + ldsw + _i * 8192), 16, 0, 0); } while (0)
; #define PG8_LDA(dst, b, h) do { _Pragma("unroll") for (int m = 0; m < 4; ++m) _Pragma("unroll") for (int k = 0; k < 2; ++k) dst[m][k] = *(const LAS bf16x8*)(lds + PG8_SA(b, h) + aoff + m * 2048 + k * 1024); } while (0)
; #define PG8_LDB(dst, b, h) do { _Pragma("unroll") for (int n = 0; n < 2; ++n) _Pragma("unroll") for (int k = 0; k < 2; ++k) dst[n][k] = *(const LAS bf16x8*)(lds + PG8_SB(b, h) + boff + n * 2048 + k * 1024); } while (0)
; #define PG8_MMA(ai, bj, At, Bt) do { __builtin_amdgcn_s_setprio(1); _Pragma("unroll") for (int m = 0; m < 4; ++m) _Pragma("unroll") for (int n = 0; n < 2; ++n) _Pragma("unroll") for (int k = 0; k < 2; ++k) \
;         acc[ai][bj][m][n] = __builtin_amdgcn_mfma_f32_16x16x32_bf16(Bt[n][k], At[m][k], acc[ai][bj][m][n], 0, 0, 0); __builtin_amdgcn_s_setprio(0); } while (0)
; #define PG8_WAIT_V(n) asm volatile("s_waitcnt vmcnt(" #n ")" ::: "memory")
; #define PG8_WAIT_L(n) asm volatile("s_waitcnt lgkmcnt(" #n ")" ::: "memory")
; #define PG8_BAR __builtin_amdgcn_s_barrier()
; #define PG8_SCHED __builtin_amdgcn_sched_barrier(0)
; template <class Epi>
; __device__ __forceinline__ void gemm_phase(LAS unsigned char* lds, const Gemm g, const Sched& S, const Epi& E) {
;     ...
;             PG8_WAIT_V(8); PG8_WAIT_L(0); PG8_BAR; PG8_MMA(1, 0, At, B0); PG8_MMA(1, 1, At, B1); PG8_BAR; PG8_SCHED;
;             PG8_LDB(B0, 1, 0); PG8_LDB(B1, 1, 1); PG8_SCHED; PG8_LDA(At, 1, 0); PG8_STAGE(PG8_SA(0, 1), a2 + hstepA, voffA);
;             PG8_WAIT_V(8); PG8_WAIT_L(0); PG8_BAR; PG8_MMA(0, 0, At, B0); PG8_MMA(0, 1, At, B1); PG8_BAR; PG8_SCHED;
;             PG8_LDA(At, 1, 1); PG8_STAGE(PG8_SB(1, 0), b3, voffB); PG8_STAGE(PG8_SB(1, 1), b3 + hstepB, voffB); PG8_STAGE(PG8_SA(1, 0), a3, voffA);
	s_waitcnt lgkmcnt(0)
	v_mfma_f32_16x16x32_bf16 v[52:55], v[148:151], v[180:183], v[52:55]
	v_mfma_f32_16x16x32_bf16 v[60:63], v[156:159], v[180:183], v[60:63]
	v_mfma_f32_16x16x32_bf16 v[36:39], v[148:151], v[188:191], v[36:39]
	v_mfma_f32_16x16x32_bf16 v[44:47], v[156:159], v[188:191], v[44:47]
	v_mfma_f32_16x16x32_bf16 v[20:23], v[148:151], v[196:199], v[20:23]
	v_mfma_f32_16x16x32_bf16 v[28:31], v[156:159], v[196:199], v[28:31]
	v_mfma_f32_16x16x32_bf16 v[4:7], v[148:151], v[208:211], v[4:7]
	v_mfma_f32_16x16x32_bf16 v[12:15], v[156:159], v[208:211], v[12:15]
	v_mfma_f32_16x16x32_bf16 v[52:55], v[152:155], v[184:187], v[52:55]
	v_mfma_f32_16x16x32_bf16 v[60:63], v[160:163], v[184:187], v[60:63]
	v_mfma_f32_16x16x32_bf16 v[36:39], v[152:155], v[192:195], v[36:39]
	v_mfma_f32_16x16x32_bf16 v[44:47], v[160:163], v[192:195], v[44:47]
	v_mfma_f32_16x16x32_bf16 v[20:23], v[152:155], v[204:207], v[20:23]
	v_mfma_f32_16x16x32_bf16 v[28:31], v[160:163], v[204:207], v[28:31]
	v_mfma_f32_16x16x32_bf16 v[4:7], v[152:155], v[212:215], v[4:7]
	v_mfma_f32_16x16x32_bf16 v[12:15], v[160:163], v[212:215], v[12:15]
	v_mfma_f32_16x16x32_bf16 v[48:51], v[164:167], v[180:183], v[48:51]
	v_mfma_f32_16x16x32_bf16 v[56:59], v[172:175], v[180:183], v[56:59]
	v_mfma_f32_16x16x32_bf16 v[32:35], v[164:167], v[188:191], v[32:35]
	v_mfma_f32_16x16x32_bf16 v[40:43], v[172:175], v[188:191], v[40:43]
	v_mfma_f32_16x16x32_bf16 v[16:19], v[164:167], v[196:199], v[16:19]
	v_mfma_f32_16x16x32_bf16 v[24:27], v[172:175], v[196:199], v[24:27]
	v_mfma_f32_16x16x32_bf16 v[0:3], v[164:167], v[208:211], v[0:3]
	v_mfma_f32_16x16x32_bf16 v[8:11], v[172:175], v[208:211], v[8:11]
	v_mfma_f32_16x16x32_bf16 v[48:51], v[168:171], v[184:187], v[48:51]
	v_mfma_f32_16x16x32_bf16 v[56:59], v[176:179], v[184:187], v[56:59]
	v_mfma_f32_16x16x32_bf16 v[32:35], v[168:171], v[192:195], v[32:35]
	v_mfma_f32_16x16x32_bf16 v[40:43], v[176:179], v[192:195], v[40:43]
	v_mfma_f32_16x16x32_bf16 v[16:19], v[168:171], v[204:207], v[16:19]
	v_mfma_f32_16x16x32_bf16 v[24:27], v[176:179], v[204:207], v[24:27]
	v_mfma_f32_16x16x32_bf16 v[0:3], v[168:171], v[212:215], v[0:3]
	v_mfma_f32_16x16x32_bf16 v[8:11], v[176:179], v[212:215], v[8:11]
	s_barrier
	s_add_i32 s78, 0, 0x18000
	s_add_i32 s79, 0, 0x1c000
	v_add_u32_e32 v160, s78, v143
	v_add_u32_e32 v176, s79, v143
	ds_read_b128 v[148:151], v160
	ds_read_b128 v[152:155], v160 offset:1024
	ds_read_b128 v[156:159], v160 offset:2048
	ds_read_b128 v[160:163], v160 offset:3072
	ds_read_b128 v[164:167], v176
	ds_read_b128 v[168:171], v176 offset:1024
	ds_read_b128 v[172:175], v176 offset:2048
	ds_read_b128 v[176:179], v176 offset:3072
	s_add_u32 s46, s46, 0x40000
	s_addc_u32 s47, s47, 0
	s_mov_b32 m0, s55
	v_lshl_add_u64 v[220:221], s[46:47], 0, v[128:129]
	ds_read_b128 v[180:183], v147 offset:32768
	ds_read_b128 v[184:187], v147 offset:33792
	ds_read_b128 v[188:191], v147 offset:34816
	ds_read_b128 v[192:195], v147 offset:35840
	ds_read_b128 v[196:199], v147 offset:36864
	ds_read_b128 v[204:207], v147 offset:37888
	ds_read_b128 v[208:211], v147 offset:38912
	ds_read_b128 v[212:215], v147 offset:39936
	global_load_lds_dwordx4 v[220:221], off
	v_lshl_add_u64 v[220:221], s[46:47], 0, v[132:133]
	s_mov_b32 m0, s56
	s_nop 0
	global_load_lds_dwordx4 v[220:221], off
	s_waitcnt vmcnt(8)
	s_waitcnt lgkmcnt(0)
	s_barrier
	s_waitcnt lgkmcnt(0)
	v_mfma_f32_16x16x32_bf16 v[116:119], v[148:151], v[180:183], v[116:119]
	v_mfma_f32_16x16x32_bf16 v[124:127], v[156:159], v[180:183], v[124:127]
	v_mfma_f32_16x16x32_bf16 v[100:103], v[148:151], v[188:191], v[100:103]
	v_mfma_f32_16x16x32_bf16 v[108:111], v[156:159], v[188:191], v[108:111]
	v_mfma_f32_16x16x32_bf16 v[84:87], v[148:151], v[196:199], v[84:87]
	v_mfma_f32_16x16x32_bf16 v[92:95], v[156:159], v[196:199], v[92:95]
	v_mfma_f32_16x16x32_bf16 v[68:71], v[148:151], v[208:211], v[68:71]
	v_mfma_f32_16x16x32_bf16 v[76:79], v[156:159], v[208:211], v[76:79]
	v_mfma_f32_16x16x32_bf16 v[116:119], v[152:155], v[184:187], v[116:119]
	v_mfma_f32_16x16x32_bf16 v[124:127], v[160:163], v[184:187], v[124:127]
	v_mfma_f32_16x16x32_bf16 v[100:103], v[152:155], v[192:195], v[100:103]
	v_mfma_f32_16x16x32_bf16 v[108:111], v[160:163], v[192:195], v[108:111]
	v_mfma_f32_16x16x32_bf16 v[84:87], v[152:155], v[204:207], v[84:87]
	v_mfma_f32_16x16x32_bf16 v[92:95], v[160:163], v[204:207], v[92:95]
	v_mfma_f32_16x16x32_bf16 v[68:71], v[152:155], v[212:215], v[68:71]
	v_mfma_f32_16x16x32_bf16 v[76:79], v[160:163], v[212:215], v[76:79]
	v_mfma_f32_16x16x32_bf16 v[112:115], v[164:167], v[180:183], v[112:115]
	v_mfma_f32_16x16x32_bf16 v[120:123], v[172:175], v[180:183], v[120:123]
	v_mfma_f32_16x16x32_bf16 v[96:99], v[164:167], v[188:191], v[96:99]
	v_mfma_f32_16x16x32_bf16 v[104:107], v[172:175], v[188:191], v[104:107]
	v_mfma_f32_16x16x32_bf16 v[80:83], v[164:167], v[196:199], v[80:83]
	v_mfma_f32_16x16x32_bf16 v[88:91], v[172:175], v[196:199], v[88:91]
	v_mfma_f32_16x16x32_bf16 v[64:67], v[164:167], v[208:211], v[64:67]
	v_mfma_f32_16x16x32_bf16 v[72:75], v[172:175], v[208:211], v[72:75]
	v_mfma_f32_16x16x32_bf16 v[112:115], v[168:171], v[184:187], v[112:115]
	v_mfma_f32_16x16x32_bf16 v[120:123], v[176:179], v[184:187], v[120:123]
	v_mfma_f32_16x16x32_bf16 v[96:99], v[168:171], v[192:195], v[96:99]
	v_mfma_f32_16x16x32_bf16 v[104:107], v[176:179], v[192:195], v[104:107]
	v_mfma_f32_16x16x32_bf16 v[80:83], v[168:171], v[204:207], v[80:83]
	v_mfma_f32_16x16x32_bf16 v[88:91], v[176:179], v[204:207], v[88:91]
	v_mfma_f32_16x16x32_bf16 v[64:67], v[168:171], v[212:215], v[64:67]
	v_mfma_f32_16x16x32_bf16 v[72:75], v[176:179], v[212:215], v[72:75]
	s_barrier
; #define PG8_STAGE(bufoff, gbase, voff) do { _Pragma("unroll") for (int _i = 0; _i < 2; ++_i) \
;         __builtin_amdgcn_global_load_lds((const unsigned*)((const char*)(gbase) + (voff)[_i]), (LAS unsigned*)(lds + (bufoff) + ldsw + _i * 8192), 16, 0, 0); } while (0)
; #define PG8_LDA(dst, b, h) do { _Pragma("unroll") for (int m = 0; m < 4; ++m) _Pragma("unroll") for (int k = 0; k < 2; ++k) dst[m][k] = *(const LAS bf16x8*)(lds + PG8_SA(b, h) + aoff + m * 2048 + k * 1024); } while (0)
; #define PG8_MMA(ai, bj, At, Bt) do { __builtin_amdgcn_s_setprio(1); _Pragma("unroll") for (int m = 0; m < 4; ++m) _Pragma("unroll") for (int n = 0; n < 2; ++n) _Pragma("unroll") for (int k = 0; k < 2; ++k) \
;         acc[ai][bj][m][n] = __builtin_amdgcn_mfma_f32_16x16x32_bf16(Bt[n][k], At[m][k], acc[ai][bj][m][n], 0, 0, 0); __builtin_amdgcn_s_setprio(0); } while (0)
; #define PG8_WAIT_V(n) asm volatile("s_waitcnt vmcnt(" #n ")" ::: "memory")
; #define PG8_WAIT_L(n) asm volatile("s_waitcnt lgkmcnt(" #n ")" ::: "memory")
; #define PG8_BAR __builtin_amdgcn_s_barrier()
; #define PG8_SCHED __builtin_amdgcn_sched_barrier(0)
; template <class Epi>
; __device__ __forceinline__ void gemm_phase(LAS unsigned char* lds, const Gemm g, const Sched& S, const Epi& E) {
;     ...
;             PG8_LDA(At, 1, 1); PG8_STAGE(PG8_SB(1, 0), b3, voffB); PG8_STAGE(PG8_SB(1, 1), b3 + hstepB, voffB); PG8_STAGE(PG8_SA(1, 0), a3, voffA);
;             PG8_WAIT_V(8); PG8_WAIT_L(0); PG8_BAR; PG8_MMA(1, 0, At, B0); PG8_MMA(1, 1, At, B1); PG8_BAR; PG8_SCHED;
;         }
;         if (wr == 0) PG8_BAR;
	s_add_i32 s46, s78, s53
	v_lshl_add_u64 v[140:141], v[140:141], 0, s[4:5]
	s_mov_b32 m0, s46
	ds_read_b128 v[180:183], v147 offset:49152
	ds_read_b128 v[184:187], v147 offset:50176
	ds_read_b128 v[188:191], v147 offset:51200
	ds_read_b128 v[192:195], v147 offset:52224
	ds_read_b128 v[196:199], v147 offset:53248
	ds_read_b128 v[204:207], v147 offset:54272
	ds_read_b128 v[208:211], v147 offset:55296
	ds_read_b128 v[212:215], v147 offset:56320
	global_load_lds_dwordx4 v[140:141], off
	s_add_i32 m0, s46, 0x2000
	s_add_u32 s44, s44, 0x40080
	v_lshl_add_u64 v[140:141], v[200:201], 0, s[4:5]
	s_addc_u32 s45, s45, 0
	s_add_i32 s46, s79, s53
	global_load_lds_dwordx4 v[140:141], off
	v_lshl_add_u64 v[140:141], s[44:45], 0, v[130:131]
	s_mov_b32 m0, s46
	s_nop 0
	global_load_lds_dwordx4 v[140:141], off
	v_lshl_add_u64 v[140:141], s[44:45], 0, v[134:135]
	s_add_i32 m0, s46, 0x2000
	s_nop 0
	global_load_lds_dwordx4 v[140:141], off
	v_lshl_add_u64 v[140:141], v[216:217], 0, s[4:5]
	s_mov_b32 m0, s58
	s_nop 0
	global_load_lds_dwordx4 v[140:141], off
	v_lshl_add_u64 v[140:141], v[218:219], 0, s[4:5]
	s_mov_b32 m0, s59
	s_nop 0
	global_load_lds_dwordx4 v[140:141], off
	s_waitcnt vmcnt(8)
	s_waitcnt lgkmcnt(0)
	s_barrier
	s_waitcnt lgkmcnt(0)
	v_mfma_f32_16x16x32_bf16 v[52:55], v[148:151], v[180:183], v[52:55]
	v_mfma_f32_16x16x32_bf16 v[60:63], v[156:159], v[180:183], v[60:63]
	v_mfma_f32_16x16x32_bf16 v[36:39], v[148:151], v[188:191], v[36:39]
	v_mfma_f32_16x16x32_bf16 v[44:47], v[156:159], v[188:191], v[44:47]
	v_mfma_f32_16x16x32_bf16 v[20:23], v[148:151], v[196:199], v[20:23]
	v_mfma_f32_16x16x32_bf16 v[28:31], v[156:159], v[196:199], v[28:31]
	v_mfma_f32_16x16x32_bf16 v[4:7], v[148:151], v[208:211], v[4:7]
	v_mfma_f32_16x16x32_bf16 v[12:15], v[156:159], v[208:211], v[12:15]
	v_mfma_f32_16x16x32_bf16 v[52:55], v[152:155], v[184:187], v[52:55]
	v_mfma_f32_16x16x32_bf16 v[60:63], v[160:163], v[184:187], v[60:63]
	v_mfma_f32_16x16x32_bf16 v[36:39], v[152:155], v[192:195], v[36:39]
	v_mfma_f32_16x16x32_bf16 v[44:47], v[160:163], v[192:195], v[44:47]
	v_mfma_f32_16x16x32_bf16 v[20:23], v[152:155], v[204:207], v[20:23]
	v_mfma_f32_16x16x32_bf16 v[28:31], v[160:163], v[204:207], v[28:31]
	v_mfma_f32_16x16x32_bf16 v[4:7], v[152:155], v[212:215], v[4:7]
	v_mfma_f32_16x16x32_bf16 v[12:15], v[160:163], v[212:215], v[12:15]
	v_mfma_f32_16x16x32_bf16 v[48:51], v[164:167], v[180:183], v[48:51]
	v_mfma_f32_16x16x32_bf16 v[56:59], v[172:175], v[180:183], v[56:59]
	v_mfma_f32_16x16x32_bf16 v[32:35], v[164:167], v[188:191], v[32:35]
	v_mfma_f32_16x16x32_bf16 v[40:43], v[172:175], v[188:191], v[40:43]
	v_mfma_f32_16x16x32_bf16 v[16:19], v[164:167], v[196:199], v[16:19]
	v_mfma_f32_16x16x32_bf16 v[24:27], v[172:175], v[196:199], v[24:27]
	v_mfma_f32_16x16x32_bf16 v[0:3], v[164:167], v[208:211], v[0:3]
	v_mfma_f32_16x16x32_bf16 v[8:11], v[172:175], v[208:211], v[8:11]
	v_mfma_f32_16x16x32_bf16 v[48:51], v[168:171], v[184:187], v[48:51]
	v_mfma_f32_16x16x32_bf16 v[56:59], v[176:179], v[184:187], v[56:59]
	v_mfma_f32_16x16x32_bf16 v[32:35], v[168:171], v[192:195], v[32:35]
	v_mfma_f32_16x16x32_bf16 v[40:43], v[176:179], v[192:195], v[40:43]
	v_mfma_f32_16x16x32_bf16 v[16:19], v[168:171], v[204:207], v[16:19]
	v_mfma_f32_16x16x32_bf16 v[24:27], v[176:179], v[204:207], v[24:27]
	v_mfma_f32_16x16x32_bf16 v[0:3], v[168:171], v[212:215], v[0:3]
	v_mfma_f32_16x16x32_bf16 v[8:11], v[176:179], v[212:215], v[8:11]
	s_add_i32 s67, s67, 2
	s_add_u32 s40, s40, 0x100
	s_addc_u32 s41, s41, 0
	s_add_u32 s65, s65, 0x100
	s_addc_u32 s66, s66, 0
	s_cmp_gt_u32 s67, 13
	s_barrier
	s_cbranch_scc0 .LBB0_163
	s_and_b64 vcc, exec, s[6:7]
	s_cbranch_vccz .LBB0_166
	s_barrier

; #define PG8_STAGE(bufoff, gbase, voff) do { _Pragma("unroll") for (int _i = 0; _i < 2; ++_i) \
;         __builtin_amdgcn_global_load_lds((const unsigned*)((const char*)(gbase) + (voff)[_i]), (LAS unsigned*)(lds + (bufoff) + ldsw + _i * 8192), 16, 0, 0); } while (0)
; #define PG8_LDA(dst, b, h) do { _Pragma("unroll") for (int m = 0; m < 4; ++m) _Pragma("unroll") for (int k = 0; k < 2; ++k) dst[m][k] = *(const LAS bf16x8*)(lds + PG8_SA(b, h) + aoff + m * 2048 + k * 1024); } while (0)
; #define PG8_LDB(dst, b, h) do { _Pragma("unroll") for (int n = 0; n < 2; ++n) _Pragma("unroll") for (int k = 0; k < 2; ++k) dst[n][k] = *(const LAS bf16x8*)(lds + PG8_SB(b, h) + boff + n * 2048 + k * 1024); } while (0)
; #define PG8_MMA(ai, bj, At, Bt) do { __builtin_amdgcn_s_setprio(1); _Pragma("unroll") for (int m = 0; m < 4; ++m) _Pragma("unroll") for (int n = 0; n < 2; ++n) _Pragma("unroll") for (int k = 0; k < 2; ++k) \
;         acc[ai][bj][m][n] = __builtin_amdgcn_mfma_f32_16x16x32_bf16(Bt[n][k], At[m][k], acc[ai][bj][m][n], 0, 0, 0); __builtin_amdgcn_s_setprio(0); } while (0)
; #define PG8_WAIT_V(n) asm volatile("s_waitcnt vmcnt(" #n ")" ::: "memory")
; #define PG8_WAIT_L(n) asm volatile("s_waitcnt lgkmcnt(" #n ")" ::: "memory")
; #define PG8_BAR __builtin_amdgcn_s_barrier()
; #define PG8_SCHED __builtin_amdgcn_sched_barrier(0)
; template <class Epi>
; __device__ __forceinline__ void gemm_phase(LAS unsigned char* lds, const Gemm g, const Sched& S, const Epi& E) {
;     ...
;             PG8_LDB(B0, 0, 0); PG8_LDB(B1, 0, 1); PG8_SCHED; PG8_LDA(At, 0, 0); PG8_STAGE(PG8_SA(1, 1), a1 + hstepA, voffA);
;             PG8_WAIT_V(8); PG8_WAIT_L(0); PG8_BAR; PG8_MMA(0, 0, At, B0); PG8_MMA(0, 1, At, B1); PG8_BAR; PG8_SCHED;
;             PG8_LDA(At, 0, 1); PG8_STAGE(PG8_SB(0, 0), b2, voffB); PG8_STAGE(PG8_SB(0, 1), b2 + hstepB, voffB); PG8_STAGE(PG8_SA(0, 0), a2, voffA);
;             PG8_WAIT_V(8); PG8_WAIT_L(0); PG8_BAR; PG8_MMA(1, 0, At, B0); PG8_MMA(1, 1, At, B1); PG8_BAR; PG8_SCHED;
.LBB0_205:
	ds_read_b128 v[136:139], v145
	ds_read_b128 v[148:151], v145 offset:1024
	ds_read_b128 v[152:155], v145 offset:2048
	ds_read_b128 v[156:159], v145 offset:3072
	ds_read_b128 v[160:163], v146
	ds_read_b128 v[164:167], v146 offset:1024
	ds_read_b128 v[168:171], v146 offset:2048
	ds_read_b128 v[172:175], v146 offset:3072
	s_add_u32 s44, s40, 0xfffc0080
	s_addc_u32 s45, s41, -1
	s_cmp_eq_u32 s66, 12
	s_cselect_b32 s47, s15, s45
	s_cselect_b32 s46, s27, s44
	s_cselect_b32 s45, s21, s65
	s_cselect_b32 s44, s63, s64
	v_lshl_add_u64 v[140:141], s[40:41], 0, v[132:133]
	s_add_i32 m0, s29, 0xc000
	ds_read_b128 v[176:179], v147
	ds_read_b128 v[180:183], v147 offset:1024
	ds_read_b128 v[184:187], v147 offset:2048
	ds_read_b128 v[188:191], v147 offset:3072
	ds_read_b128 v[192:195], v147 offset:4096
	ds_read_b128 v[196:199], v147 offset:5120
	ds_read_b128 v[204:207], v147 offset:6144
	ds_read_b128 v[208:211], v147 offset:7168
	global_load_lds_dwordx4 v[140:141], off
	v_lshl_add_u64 v[140:141], s[40:41], 0, v[134:135]
	s_add_i32 m0, s29, 0xe000
	s_nop 0
	global_load_lds_dwordx4 v[140:141], off
	s_waitcnt vmcnt(8)
	s_waitcnt lgkmcnt(0)
	s_barrier
	s_waitcnt lgkmcnt(0)
	v_mfma_f32_16x16x32_bf16 v[124:127], v[136:139], v[176:179], v[124:127]
	v_mfma_f32_16x16x32_bf16 v[120:123], v[152:155], v[176:179], v[120:123]
	v_mfma_f32_16x16x32_bf16 v[108:111], v[136:139], v[184:187], v[108:111]
	v_mfma_f32_16x16x32_bf16 v[104:107], v[152:155], v[184:187], v[104:107]
	v_mfma_f32_16x16x32_bf16 v[92:95], v[136:139], v[192:195], v[92:95]
	v_mfma_f32_16x16x32_bf16 v[88:91], v[152:155], v[192:195], v[88:91]
	v_mfma_f32_16x16x32_bf16 v[76:79], v[136:139], v[204:207], v[76:79]
	v_mfma_f32_16x16x32_bf16 v[72:75], v[152:155], v[204:207], v[72:75]
	v_mfma_f32_16x16x32_bf16 v[124:127], v[148:151], v[180:183], v[124:127]
	v_mfma_f32_16x16x32_bf16 v[120:123], v[156:159], v[180:183], v[120:123]
	v_mfma_f32_16x16x32_bf16 v[108:111], v[148:151], v[188:191], v[108:111]
	v_mfma_f32_16x16x32_bf16 v[104:107], v[156:159], v[188:191], v[104:107]
	v_mfma_f32_16x16x32_bf16 v[92:95], v[148:151], v[196:199], v[92:95]
	v_mfma_f32_16x16x32_bf16 v[88:91], v[156:159], v[196:199], v[88:91]
	v_mfma_f32_16x16x32_bf16 v[76:79], v[148:151], v[208:211], v[76:79]
	v_mfma_f32_16x16x32_bf16 v[72:75], v[156:159], v[208:211], v[72:75]
	v_mfma_f32_16x16x32_bf16 v[116:119], v[160:163], v[176:179], v[116:119]
	v_mfma_f32_16x16x32_bf16 v[112:115], v[168:171], v[176:179], v[112:115]
	v_mfma_f32_16x16x32_bf16 v[100:103], v[160:163], v[184:187], v[100:103]
	v_mfma_f32_16x16x32_bf16 v[96:99], v[168:171], v[184:187], v[96:99]
	v_mfma_f32_16x16x32_bf16 v[84:87], v[160:163], v[192:195], v[84:87]
	v_mfma_f32_16x16x32_bf16 v[80:83], v[168:171], v[192:195], v[80:83]
	v_mfma_f32_16x16x32_bf16 v[68:71], v[160:163], v[204:207], v[68:71]
	v_mfma_f32_16x16x32_bf16 v[64:67], v[168:171], v[204:207], v[64:67]
	v_mfma_f32_16x16x32_bf16 v[116:119], v[164:167], v[180:183], v[116:119]
	v_mfma_f32_16x16x32_bf16 v[112:115], v[172:175], v[180:183], v[112:115]
	v_mfma_f32_16x16x32_bf16 v[100:103], v[164:167], v[188:191], v[100:103]
	v_mfma_f32_16x16x32_bf16 v[96:99], v[172:175], v[188:191], v[96:99]
	v_mfma_f32_16x16x32_bf16 v[84:87], v[164:167], v[196:199], v[84:87]
	v_mfma_f32_16x16x32_bf16 v[80:83], v[172:175], v[196:199], v[80:83]
	v_mfma_f32_16x16x32_bf16 v[68:71], v[164:167], v[208:211], v[68:71]
	v_mfma_f32_16x16x32_bf16 v[64:67], v[172:175], v[208:211], v[64:67]
	s_barrier
	s_add_i32 s67, s61, s52
	v_lshl_add_u64 v[140:141], s[44:45], 0, v[128:129]
	s_mov_b32 m0, s67
	ds_read_b128 v[176:179], v147 offset:16384
	ds_read_b128 v[180:183], v147 offset:17408
	ds_read_b128 v[184:187], v147 offset:18432
	ds_read_b128 v[188:191], v147 offset:19456
	ds_read_b128 v[192:195], v147 offset:20480
	ds_read_b128 v[196:199], v147 offset:21504
	ds_read_b128 v[204:207], v147 offset:22528
	ds_read_b128 v[208:211], v147 offset:23552
	global_load_lds_dwordx4 v[140:141], off
	s_add_i32 m0, s67, 0x2000
	s_add_u32 s78, s44, 0x40000
	v_lshl_add_u64 v[200:201], s[44:45], 0, v[130:131]
	s_addc_u32 s79, s45, 0
	s_add_i32 s67, s62, s52
	global_load_lds_dwordx4 v[200:201], off
	v_lshl_add_u64 v[212:213], s[78:79], 0, v[128:129]
	s_mov_b32 m0, s67
	v_lshl_add_u64 v[214:215], s[46:47], 0, v[130:131]
	global_load_lds_dwordx4 v[212:213], off
	v_lshl_add_u64 v[212:213], s[78:79], 0, v[130:131]
	s_add_i32 m0, s67, 0x2000
	s_nop 0
	global_load_lds_dwordx4 v[212:213], off
	v_lshl_add_u64 v[212:213], s[46:47], 0, v[128:129]
	s_mov_b32 m0, s29
	s_nop 0
	global_load_lds_dwordx4 v[212:213], off
	s_mov_b32 m0, s55
	s_nop 0
	global_load_lds_dwordx4 v[214:215], off
	s_waitcnt vmcnt(8)
	s_waitcnt lgkmcnt(0)
	s_barrier
; #define PG8_STAGE(bufoff, gbase, voff) do { _Pragma("unroll") for (int _i = 0; _i < 2; ++_i) \
;         __builtin_amdgcn_global_load_lds((const unsigned*)((const char*)(gbase) + (voff)[_i]), (LAS unsigned*)(lds + (bufoff) + ldsw + _i * 8192), 16, 0, 0); } while (0)
; #define PG8_LDA(dst, b, h) do { _Pragma("unroll") for (int m = 0; m < 4; ++m) _Pragma("unroll") for (int k = 0; k < 2; ++k) dst[m][k] = *(const LAS bf16x8*)(lds + PG8_SA(b, h) + aoff + m * 2048 + k * 1024); } while (0)
; #define PG8_LDB(dst, b, h) do { _Pragma("unroll") for (int n = 0; n < 2; ++n) _Pragma("unroll") for (int k = 0; k < 2; ++k) dst[n][k] = *(const LAS bf16x8*)(lds + PG8_SB(b, h) + boff + n * 2048 + k * 1024); } while (0)
; #define PG8_MMA(ai, bj, At, Bt) do { __builtin_amdgcn_s_setprio(1); _Pragma("unroll") for (int m = 0; m < 4; ++m) _Pragma("unroll") for (int n = 0; n < 2; ++n) _Pragma("unroll") for (int k = 0; k < 2; ++k) \
;         acc[ai][bj][m][n] = __builtin_amdgcn_mfma_f32_16x16x32_bf16(Bt[n][k], At[m][k], acc[ai][bj][m][n], 0, 0, 0); __builtin_amdgcn_s_setprio(0); } while (0)
; #define PG8_WAIT_V(n) asm volatile("s_waitcnt vmcnt(" #n ")" ::: "memory")
; #define PG8_WAIT_L(n) asm volatile("s_waitcnt lgkmcnt(" #n ")" ::: "memory")
; #define PG8_BAR __builtin_amdgcn_s_barrier()
; #define PG8_SCHED __builtin_amdgcn_sched_barrier(0)
; template <class Epi>
; __device__ __forceinline__ void gemm_phase(LAS unsigned char* lds, const Gemm g, const Sched& S, const Epi& E) {
;     ...
;             PG8_WAIT_V(8); PG8_WAIT_L(0); PG8_BAR; PG8_MMA(1, 0, At, B0); PG8_MMA(1, 1, At, B1); PG8_BAR; PG8_SCHED;
;             PG8_LDB(B0, 1, 0); PG8_LDB(B1, 1, 1); PG8_SCHED; PG8_LDA(At, 1, 0); PG8_STAGE(PG8_SA(0, 1), a2 + hstepA, voffA);
;             PG8_WAIT_V(8); PG8_WAIT_L(0); PG8_BAR; PG8_MMA(0, 0, At, B0); PG8_MMA(0, 1, At, B1); PG8_BAR; PG8_SCHED;
	s_waitcnt lgkmcnt(0)
	v_mfma_f32_16x16x32_bf16 v[60:63], v[136:139], v[176:179], v[60:63]
	v_mfma_f32_16x16x32_bf16 v[56:59], v[152:155], v[176:179], v[56:59]
	v_mfma_f32_16x16x32_bf16 v[44:47], v[136:139], v[184:187], v[44:47]
	v_mfma_f32_16x16x32_bf16 v[40:43], v[152:155], v[184:187], v[40:43]
	v_mfma_f32_16x16x32_bf16 v[28:31], v[136:139], v[192:195], v[28:31]
	v_mfma_f32_16x16x32_bf16 v[24:27], v[152:155], v[192:195], v[24:27]
	v_mfma_f32_16x16x32_bf16 v[12:15], v[136:139], v[204:207], v[12:15]
	v_mfma_f32_16x16x32_bf16 v[8:11], v[152:155], v[204:207], v[8:11]
	v_mfma_f32_16x16x32_bf16 v[60:63], v[148:151], v[180:183], v[60:63]
	v_mfma_f32_16x16x32_bf16 v[56:59], v[156:159], v[180:183], v[56:59]
	v_mfma_f32_16x16x32_bf16 v[44:47], v[148:151], v[188:191], v[44:47]
	v_mfma_f32_16x16x32_bf16 v[40:43], v[156:159], v[188:191], v[40:43]
	v_mfma_f32_16x16x32_bf16 v[28:31], v[148:151], v[196:199], v[28:31]
	v_mfma_f32_16x16x32_bf16 v[24:27], v[156:159], v[196:199], v[24:27]
	v_mfma_f32_16x16x32_bf16 v[12:15], v[148:151], v[208:211], v[12:15]
	v_mfma_f32_16x16x32_bf16 v[8:11], v[156:159], v[208:211], v[8:11]
	v_mfma_f32_16x16x32_bf16 v[52:55], v[160:163], v[176:179], v[52:55]
	v_mfma_f32_16x16x32_bf16 v[48:51], v[168:171], v[176:179], v[48:51]
	v_mfma_f32_16x16x32_bf16 v[36:39], v[160:163], v[184:187], v[36:39]
	v_mfma_f32_16x16x32_bf16 v[32:35], v[168:171], v[184:187], v[32:35]
	v_mfma_f32_16x16x32_bf16 v[20:23], v[160:163], v[192:195], v[20:23]
	v_mfma_f32_16x16x32_bf16 v[16:19], v[168:171], v[192:195], v[16:19]
	v_mfma_f32_16x16x32_bf16 v[4:7], v[160:163], v[204:207], v[4:7]
	v_mfma_f32_16x16x32_bf16 v[0:3], v[168:171], v[204:207], v[0:3]
	v_mfma_f32_16x16x32_bf16 v[52:55], v[164:167], v[180:183], v[52:55]
	v_mfma_f32_16x16x32_bf16 v[48:51], v[172:175], v[180:183], v[48:51]
	v_mfma_f32_16x16x32_bf16 v[36:39], v[164:167], v[188:191], v[36:39]
	v_mfma_f32_16x16x32_bf16 v[32:35], v[172:175], v[188:191], v[32:35]
	v_mfma_f32_16x16x32_bf16 v[20:23], v[164:167], v[196:199], v[20:23]
	v_mfma_f32_16x16x32_bf16 v[16:19], v[172:175], v[196:199], v[16:19]
	v_mfma_f32_16x16x32_bf16 v[4:7], v[164:167], v[208:211], v[4:7]
	v_mfma_f32_16x16x32_bf16 v[0:3], v[172:175], v[208:211], v[0:3]
	s_barrier
	s_add_i32 s67, 0, 0x18000
	s_add_i32 s78, 0, 0x1c000
	v_add_u32_e32 v156, s67, v143
	v_add_u32_e32 v172, s78, v143
	ds_read_b128 v[136:139], v156
	ds_read_b128 v[148:151], v156 offset:1024
	ds_read_b128 v[152:155], v156 offset:2048
	ds_read_b128 v[156:159], v156 offset:3072
	ds_read_b128 v[160:163], v172
	ds_read_b128 v[164:167], v172 offset:1024
	ds_read_b128 v[168:171], v172 offset:2048
	ds_read_b128 v[172:175], v172 offset:3072
	s_add_u32 s46, s46, 0x40000
	s_addc_u32 s47, s47, 0
	s_mov_b32 m0, s56
	v_lshl_add_u64 v[216:217], s[46:47], 0, v[128:129]
	ds_read_b128 v[176:179], v147 offset:32768
	ds_read_b128 v[180:183], v147 offset:33792
	ds_read_b128 v[184:187], v147 offset:34816
	ds_read_b128 v[188:191], v147 offset:35840
	ds_read_b128 v[192:195], v147 offset:36864
	ds_read_b128 v[196:199], v147 offset:37888
	ds_read_b128 v[204:207], v147 offset:38912
	ds_read_b128 v[208:211], v147 offset:39936
	global_load_lds_dwordx4 v[216:217], off
	v_lshl_add_u64 v[216:217], s[46:47], 0, v[130:131]
	s_mov_b32 m0, s57
	s_nop 0
	global_load_lds_dwordx4 v[216:217], off
	s_waitcnt vmcnt(8)
	s_waitcnt lgkmcnt(0)
	s_barrier
	s_waitcnt lgkmcnt(0)
	v_mfma_f32_16x16x32_bf16 v[124:127], v[136:139], v[176:179], v[124:127]
	v_mfma_f32_16x16x32_bf16 v[120:123], v[152:155], v[176:179], v[120:123]
	v_mfma_f32_16x16x32_bf16 v[108:111], v[136:139], v[184:187], v[108:111]
	v_mfma_f32_16x16x32_bf16 v[104:107], v[152:155], v[184:187], v[104:107]
	v_mfma_f32_16x16x32_bf16 v[92:95], v[136:139], v[192:195], v[92:95]
	v_mfma_f32_16x16x32_bf16 v[88:91], v[152:155], v[192:195], v[88:91]
	v_mfma_f32_16x16x32_bf16 v[76:79], v[136:139], v[204:207], v[76:79]
	v_mfma_f32_16x16x32_bf16 v[72:75], v[152:155], v[204:207], v[72:75]
	v_mfma_f32_16x16x32_bf16 v[124:127], v[148:151], v[180:183], v[124:127]
	v_mfma_f32_16x16x32_bf16 v[120:123], v[156:159], v[180:183], v[120:123]
	v_mfma_f32_16x16x32_bf16 v[108:111], v[148:151], v[188:191], v[108:111]
	v_mfma_f32_16x16x32_bf16 v[104:107], v[156:159], v[188:191], v[104:107]
	v_mfma_f32_16x16x32_bf16 v[92:95], v[148:151], v[196:199], v[92:95]
	v_mfma_f32_16x16x32_bf16 v[88:91], v[156:159], v[196:199], v[88:91]
	v_mfma_f32_16x16x32_bf16 v[76:79], v[148:151], v[208:211], v[76:79]
	v_mfma_f32_16x16x32_bf16 v[72:75], v[156:159], v[208:211], v[72:75]
	v_mfma_f32_16x16x32_bf16 v[116:119], v[160:163], v[176:179], v[116:119]
	v_mfma_f32_16x16x32_bf16 v[112:115], v[168:171], v[176:179], v[112:115]
	v_mfma_f32_16x16x32_bf16 v[100:103], v[160:163], v[184:187], v[100:103]
	v_mfma_f32_16x16x32_bf16 v[96:99], v[168:171], v[184:187], v[96:99]
	v_mfma_f32_16x16x32_bf16 v[84:87], v[160:163], v[192:195], v[84:87]
	v_mfma_f32_16x16x32_bf16 v[80:83], v[168:171], v[192:195], v[80:83]
	v_mfma_f32_16x16x32_bf16 v[68:71], v[160:163], v[204:207], v[68:71]
	v_mfma_f32_16x16x32_bf16 v[64:67], v[168:171], v[204:207], v[64:67]
	v_mfma_f32_16x16x32_bf16 v[116:119], v[164:167], v[180:183], v[116:119]
	v_mfma_f32_16x16x32_bf16 v[112:115], v[172:175], v[180:183], v[112:115]
	v_mfma_f32_16x16x32_bf16 v[100:103], v[164:167], v[188:191], v[100:103]
	v_mfma_f32_16x16x32_bf16 v[96:99], v[172:175], v[188:191], v[96:99]
	v_mfma_f32_16x16x32_bf16 v[84:87], v[164:167], v[196:199], v[84:87]
	v_mfma_f32_16x16x32_bf16 v[80:83], v[172:175], v[196:199], v[80:83]
	v_mfma_f32_16x16x32_bf16 v[68:71], v[164:167], v[208:211], v[68:71]
	v_mfma_f32_16x16x32_bf16 v[64:67], v[172:175], v[208:211], v[64:67]
	s_barrier
; #define PG8_STAGE(bufoff, gbase, voff) do { _Pragma("unroll") for (int _i = 0; _i < 2; ++_i) \
;         __builtin_amdgcn_global_load_lds((const unsigned*)((const char*)(gbase) + (voff)[_i]), (LAS unsigned*)(lds + (bufoff) + ldsw + _i * 8192), 16, 0, 0); } while (0)
; #define PG8_LDA(dst, b, h) do { _Pragma("unroll") for (int m = 0; m < 4; ++m) _Pragma("unroll") for (int k = 0; k < 2; ++k) dst[m][k] = *(const LAS bf16x8*)(lds + PG8_SA(b, h) + aoff + m * 2048 + k * 1024); } while (0)
; #define PG8_MMA(ai, bj, At, Bt) do { __builtin_amdgcn_s_setprio(1); _Pragma("unroll") for (int m = 0; m < 4; ++m) _Pragma("unroll") for (int n = 0; n < 2; ++n) _Pragma("unroll") for (int k = 0; k < 2; ++k) \
;         acc[ai][bj][m][n] = __builtin_amdgcn_mfma_f32_16x16x32_bf16(Bt[n][k], At[m][k], acc[ai][bj][m][n], 0, 0, 0); __builtin_amdgcn_s_setprio(0); } while (0)
; #define PG8_WAIT_V(n) asm volatile("s_waitcnt vmcnt(" #n ")" ::: "memory")
; #define PG8_WAIT_L(n) asm volatile("s_waitcnt lgkmcnt(" #n ")" ::: "memory")
; #define PG8_BAR __builtin_amdgcn_s_barrier()
; #define PG8_SCHED __builtin_amdgcn_sched_barrier(0)
; template <class Epi>
; __device__ __forceinline__ void gemm_phase(LAS unsigned char* lds, const Gemm g, const Sched& S, const Epi& E) {
;     ...
;             PG8_LDA(At, 1, 1); PG8_STAGE(PG8_SB(1, 0), b3, voffB); PG8_STAGE(PG8_SB(1, 1), b3 + hstepB, voffB); PG8_STAGE(PG8_SA(1, 0), a3, voffA);
;             PG8_WAIT_V(8); PG8_WAIT_L(0); PG8_BAR; PG8_MMA(1, 0, At, B0); PG8_MMA(1, 1, At, B1); PG8_BAR; PG8_SCHED;
;         }
;         if (wr == 0) PG8_BAR;
	s_add_i32 s46, s67, s52
	v_lshl_add_u64 v[140:141], v[140:141], 0, s[4:5]
	s_mov_b32 m0, s46
	ds_read_b128 v[176:179], v147 offset:49152
	ds_read_b128 v[180:183], v147 offset:50176
	ds_read_b128 v[184:187], v147 offset:51200
	ds_read_b128 v[188:191], v147 offset:52224
	ds_read_b128 v[192:195], v147 offset:53248
	ds_read_b128 v[196:199], v147 offset:54272
	ds_read_b128 v[204:207], v147 offset:55296
	ds_read_b128 v[208:211], v147 offset:56320
	global_load_lds_dwordx4 v[140:141], off
	s_add_i32 m0, s46, 0x2000
	s_add_u32 s44, s44, 0x40080
	v_lshl_add_u64 v[140:141], v[200:201], 0, s[4:5]
	s_addc_u32 s45, s45, 0
	s_add_i32 s46, s78, s52
	global_load_lds_dwordx4 v[140:141], off
	v_lshl_add_u64 v[140:141], s[44:45], 0, v[128:129]
	s_mov_b32 m0, s46
	s_nop 0
	global_load_lds_dwordx4 v[140:141], off
	v_lshl_add_u64 v[140:141], s[44:45], 0, v[130:131]
	s_add_i32 m0, s46, 0x2000
	s_nop 0
	global_load_lds_dwordx4 v[140:141], off
	v_lshl_add_u64 v[140:141], v[212:213], 0, s[4:5]
	s_mov_b32 m0, s59
	s_nop 0
	global_load_lds_dwordx4 v[140:141], off
	v_lshl_add_u64 v[140:141], v[214:215], 0, s[4:5]
	s_mov_b32 m0, s60
	s_nop 0
	global_load_lds_dwordx4 v[140:141], off
	s_waitcnt vmcnt(8)
	s_waitcnt lgkmcnt(0)
	s_barrier
	s_waitcnt lgkmcnt(0)
	v_mfma_f32_16x16x32_bf16 v[60:63], v[136:139], v[176:179], v[60:63]
	v_mfma_f32_16x16x32_bf16 v[56:59], v[152:155], v[176:179], v[56:59]
	v_mfma_f32_16x16x32_bf16 v[44:47], v[136:139], v[184:187], v[44:47]
	v_mfma_f32_16x16x32_bf16 v[40:43], v[152:155], v[184:187], v[40:43]
	v_mfma_f32_16x16x32_bf16 v[28:31], v[136:139], v[192:195], v[28:31]
	v_mfma_f32_16x16x32_bf16 v[24:27], v[152:155], v[192:195], v[24:27]
	v_mfma_f32_16x16x32_bf16 v[12:15], v[136:139], v[204:207], v[12:15]
	v_mfma_f32_16x16x32_bf16 v[8:11], v[152:155], v[204:207], v[8:11]
	v_mfma_f32_16x16x32_bf16 v[60:63], v[148:151], v[180:183], v[60:63]
	v_mfma_f32_16x16x32_bf16 v[56:59], v[156:159], v[180:183], v[56:59]
	v_mfma_f32_16x16x32_bf16 v[44:47], v[148:151], v[188:191], v[44:47]
	v_mfma_f32_16x16x32_bf16 v[40:43], v[156:159], v[188:191], v[40:43]
	v_mfma_f32_16x16x32_bf16 v[28:31], v[148:151], v[196:199], v[28:31]
	v_mfma_f32_16x16x32_bf16 v[24:27], v[156:159], v[196:199], v[24:27]
	v_mfma_f32_16x16x32_bf16 v[12:15], v[148:151], v[208:211], v[12:15]
	v_mfma_f32_16x16x32_bf16 v[8:11], v[156:159], v[208:211], v[8:11]
	v_mfma_f32_16x16x32_bf16 v[52:55], v[160:163], v[176:179], v[52:55]
	v_mfma_f32_16x16x32_bf16 v[48:51], v[168:171], v[176:179], v[48:51]
	v_mfma_f32_16x16x32_bf16 v[36:39], v[160:163], v[184:187], v[36:39]
	v_mfma_f32_16x16x32_bf16 v[32:35], v[168:171], v[184:187], v[32:35]
	v_mfma_f32_16x16x32_bf16 v[20:23], v[160:163], v[192:195], v[20:23]
	v_mfma_f32_16x16x32_bf16 v[16:19], v[168:171], v[192:195], v[16:19]
	v_mfma_f32_16x16x32_bf16 v[4:7], v[160:163], v[204:207], v[4:7]
	v_mfma_f32_16x16x32_bf16 v[0:3], v[168:171], v[204:207], v[0:3]
	v_mfma_f32_16x16x32_bf16 v[52:55], v[164:167], v[180:183], v[52:55]
	v_mfma_f32_16x16x32_bf16 v[48:51], v[172:175], v[180:183], v[48:51]
	v_mfma_f32_16x16x32_bf16 v[36:39], v[164:167], v[188:191], v[36:39]
	v_mfma_f32_16x16x32_bf16 v[32:35], v[172:175], v[188:191], v[32:35]
	v_mfma_f32_16x16x32_bf16 v[20:23], v[164:167], v[196:199], v[20:23]
	v_mfma_f32_16x16x32_bf16 v[16:19], v[172:175], v[196:199], v[16:19]
	v_mfma_f32_16x16x32_bf16 v[4:7], v[164:167], v[208:211], v[4:7]
	v_mfma_f32_16x16x32_bf16 v[0:3], v[172:175], v[208:211], v[0:3]
	s_add_i32 s66, s66, 2
	s_add_u32 s40, s40, 0x100
	s_addc_u32 s41, s41, 0
	s_add_u32 s64, s64, 0x100
	s_addc_u32 s65, s65, 0
	s_cmp_gt_u32 s66, 13
	s_barrier
	s_cbranch_scc0 .LBB0_205
	s_and_b64 vcc, exec, s[6:7]
	s_cbranch_vccz .LBB0_208
	s_barrier

; #define PG8_STAGE(bufoff, gbase, voff) do { _Pragma("unroll") for (int _i = 0; _i < 2; ++_i) \
;         __builtin_amdgcn_global_load_lds((const unsigned*)((const char*)(gbase) + (voff)[_i]), (LAS unsigned*)(lds + (bufoff) + ldsw + _i * 8192), 16, 0, 0); } while (0)
; #define PG8_LDA(dst, b, h) do { _Pragma("unroll") for (int m = 0; m < 4; ++m) _Pragma("unroll") for (int k = 0; k < 2; ++k) dst[m][k] = *(const LAS bf16x8*)(lds + PG8_SA(b, h) + aoff + m * 2048 + k * 1024); } while (0)
; #define PG8_LDB(dst, b, h) do { _Pragma("unroll") for (int n = 0; n < 2; ++n) _Pragma("unroll") for (int k = 0; k < 2; ++k) dst[n][k] = *(const LAS bf16x8*)(lds + PG8_SB(b, h) + boff + n * 2048 + k * 1024); } while (0)
; #define PG8_MMA(ai, bj, At, Bt) do { __builtin_amdgcn_s_setprio(1); _Pragma("unroll") for (int m = 0; m < 4; ++m) _Pragma("unroll") for (int n = 0; n < 2; ++n) _Pragma("unroll") for (int k = 0; k < 2; ++k) \
;         acc[ai][bj][m][n] = __builtin_amdgcn_mfma_f32_16x16x32_bf16(Bt[n][k], At[m][k], acc[ai][bj][m][n], 0, 0, 0); __builtin_amdgcn_s_setprio(0); } while (0)
; #define PG8_WAIT_V(n) asm volatile("s_waitcnt vmcnt(" #n ")" ::: "memory")
; #define PG8_WAIT_L(n) asm volatile("s_waitcnt lgkmcnt(" #n ")" ::: "memory")
; #define PG8_BAR __builtin_amdgcn_s_barrier()
; #define PG8_SCHED __builtin_amdgcn_sched_barrier(0)
; template <class Epi>
; __device__ __forceinline__ void gemm_phase(LAS unsigned char* lds, const Gemm g, const Sched& S, const Epi& E) {
;     ...
;         for (int t = 0; t < nt; t += 2) {
;             const bool last = (t == nt - 2);
;             const char* a1 = cA + (size_t)(t + 1) * kstep;
;             const char* a2 = last ? nA : cA + (size_t)(t + 2) * kstep; const char* b2 = last ? nB : cB + (size_t)(t + 2) * kstep;
;             const char* a3 = a2 + kstep; const char* b3 = b2 + kstep;
;             PG8_LDB(B0, 0, 0); PG8_LDB(B1, 0, 1); PG8_SCHED; PG8_LDA(At, 0, 0); PG8_STAGE(PG8_SA(1, 1), a1 + hstepA, voffA);
;             PG8_WAIT_V(8); PG8_WAIT_L(0); PG8_BAR; PG8_MMA(0, 0, At, B0); PG8_MMA(0, 1, At, B1); PG8_BAR; PG8_SCHED;
;             PG8_LDA(At, 0, 1); PG8_STAGE(PG8_SB(0, 0), b2, voffB); PG8_STAGE(PG8_SB(0, 1), b2 + hstepB, voffB); PG8_STAGE(PG8_SA(0, 0), a2, voffA);
;             PG8_WAIT_V(8); PG8_WAIT_L(0); PG8_BAR; PG8_MMA(1, 0, At, B0); PG8_MMA(1, 1, At, B1); PG8_BAR; PG8_SCHED;
.LBB0_293:
	ds_read_b128 v[146:149], v143
	ds_read_b128 v[150:153], v143 offset:1024
	ds_read_b128 v[154:157], v143 offset:2048
	ds_read_b128 v[158:161], v143 offset:3072
	ds_read_b128 v[162:165], v144
	ds_read_b128 v[166:169], v144 offset:1024
	ds_read_b128 v[170:173], v144 offset:2048
	ds_read_b128 v[174:177], v144 offset:3072
	s_add_u32 s40, s28, 0xfffc0080
	s_addc_u32 s41, s29, -1
	s_cmp_eq_u32 s66, 12
	s_cselect_b32 s45, s23, s41
	s_cselect_b32 s44, s62, s40
	s_cselect_b32 s41, s15, s65
	s_cselect_b32 s40, s63, s64
	v_lshl_add_u64 v[212:213], s[28:29], 0, v[136:137]
	s_add_i32 m0, s21, 0xc000
	ds_read_b128 v[178:181], v145
	ds_read_b128 v[182:185], v145 offset:1024
	ds_read_b128 v[186:189], v145 offset:2048
	ds_read_b128 v[190:193], v145 offset:3072
	ds_read_b128 v[194:197], v145 offset:4096
	ds_read_b128 v[198:201], v145 offset:5120
	ds_read_b128 v[204:207], v145 offset:6144
	ds_read_b128 v[208:211], v145 offset:7168
	global_load_lds_dwordx4 v[212:213], off
	v_lshl_add_u64 v[212:213], s[28:29], 0, v[138:139]
	s_add_i32 m0, s21, 0xe000
	s_nop 0
	global_load_lds_dwordx4 v[212:213], off
	s_waitcnt vmcnt(8)
	s_waitcnt lgkmcnt(0)
	s_barrier
	s_waitcnt lgkmcnt(0)
	v_mfma_f32_16x16x32_bf16 v[124:127], v[146:149], v[178:181], v[124:127]
	v_mfma_f32_16x16x32_bf16 v[120:123], v[154:157], v[178:181], v[120:123]
	v_mfma_f32_16x16x32_bf16 v[116:119], v[146:149], v[186:189], v[116:119]
	v_mfma_f32_16x16x32_bf16 v[112:115], v[154:157], v[186:189], v[112:115]
	v_mfma_f32_16x16x32_bf16 v[100:103], v[146:149], v[194:197], v[100:103]
	v_mfma_f32_16x16x32_bf16 v[96:99], v[154:157], v[194:197], v[96:99]
	v_mfma_f32_16x16x32_bf16 v[84:87], v[146:149], v[204:207], v[84:87]
	v_mfma_f32_16x16x32_bf16 v[80:83], v[154:157], v[204:207], v[80:83]
	v_mfma_f32_16x16x32_bf16 v[124:127], v[150:153], v[182:185], v[124:127]
	v_mfma_f32_16x16x32_bf16 v[120:123], v[158:161], v[182:185], v[120:123]
	v_mfma_f32_16x16x32_bf16 v[116:119], v[150:153], v[190:193], v[116:119]
	v_mfma_f32_16x16x32_bf16 v[112:115], v[158:161], v[190:193], v[112:115]
	v_mfma_f32_16x16x32_bf16 v[100:103], v[150:153], v[198:201], v[100:103]
	v_mfma_f32_16x16x32_bf16 v[96:99], v[158:161], v[198:201], v[96:99]
	v_mfma_f32_16x16x32_bf16 v[84:87], v[150:153], v[208:211], v[84:87]
	v_mfma_f32_16x16x32_bf16 v[80:83], v[158:161], v[208:211], v[80:83]
	v_mfma_f32_16x16x32_bf16 v[108:111], v[162:165], v[178:181], v[108:111]
	v_mfma_f32_16x16x32_bf16 v[104:107], v[170:173], v[178:181], v[104:107]
	v_mfma_f32_16x16x32_bf16 v[92:95], v[162:165], v[186:189], v[92:95]
	v_mfma_f32_16x16x32_bf16 v[88:91], v[170:173], v[186:189], v[88:91]
	v_mfma_f32_16x16x32_bf16 v[76:79], v[162:165], v[194:197], v[76:79]
	v_mfma_f32_16x16x32_bf16 v[72:75], v[170:173], v[194:197], v[72:75]
	v_mfma_f32_16x16x32_bf16 v[68:71], v[162:165], v[204:207], v[68:71]
	v_mfma_f32_16x16x32_bf16 v[64:67], v[170:173], v[204:207], v[64:67]
	v_mfma_f32_16x16x32_bf16 v[108:111], v[166:169], v[182:185], v[108:111]
	v_mfma_f32_16x16x32_bf16 v[104:107], v[174:177], v[182:185], v[104:107]
	v_mfma_f32_16x16x32_bf16 v[92:95], v[166:169], v[190:193], v[92:95]
	v_mfma_f32_16x16x32_bf16 v[88:91], v[174:177], v[190:193], v[88:91]
	v_mfma_f32_16x16x32_bf16 v[76:79], v[166:169], v[198:201], v[76:79]
	v_mfma_f32_16x16x32_bf16 v[72:75], v[174:177], v[198:201], v[72:75]
	v_mfma_f32_16x16x32_bf16 v[68:71], v[166:169], v[208:211], v[68:71]
	v_mfma_f32_16x16x32_bf16 v[64:67], v[174:177], v[208:211], v[64:67]
	s_barrier
	s_add_i32 s67, s59, s52
	v_lshl_add_u64 v[212:213], s[40:41], 0, v[130:131]
	s_mov_b32 m0, s67
	ds_read_b128 v[178:181], v145 offset:16384
	ds_read_b128 v[182:185], v145 offset:17408
	ds_read_b128 v[186:189], v145 offset:18432
	ds_read_b128 v[190:193], v145 offset:19456
	ds_read_b128 v[194:197], v145 offset:20480
	ds_read_b128 v[198:201], v145 offset:21504
	ds_read_b128 v[204:207], v145 offset:22528
	ds_read_b128 v[208:211], v145 offset:23552
	global_load_lds_dwordx4 v[212:213], off
	s_add_i32 m0, s67, 0x2000
	s_add_u32 s78, s40, 0x40000
	v_lshl_add_u64 v[214:215], s[40:41], 0, v[134:135]
	s_addc_u32 s79, s41, 0
	s_add_i32 s67, s60, s52
	global_load_lds_dwordx4 v[214:215], off
	v_lshl_add_u64 v[216:217], s[78:79], 0, v[130:131]
	s_mov_b32 m0, s67
	v_lshl_add_u64 v[218:219], s[44:45], 0, v[132:133]
	global_load_lds_dwordx4 v[216:217], off
	v_lshl_add_u64 v[216:217], s[78:79], 0, v[134:135]
	s_add_i32 m0, s67, 0x2000
	s_nop 0
	global_load_lds_dwordx4 v[216:217], off
	v_lshl_add_u64 v[216:217], s[44:45], 0, v[128:129]
	s_mov_b32 m0, s21
	s_nop 0
	global_load_lds_dwordx4 v[216:217], off
	s_mov_b32 m0, s53
	s_nop 0
	global_load_lds_dwordx4 v[218:219], off
	s_waitcnt vmcnt(8)
	s_waitcnt lgkmcnt(0)
	s_barrier
; #define PG8_STAGE(bufoff, gbase, voff) do { _Pragma("unroll") for (int _i = 0; _i < 2; ++_i) \
;         __builtin_amdgcn_global_load_lds((const unsigned*)((const char*)(gbase) + (voff)[_i]), (LAS unsigned*)(lds + (bufoff) + ldsw + _i * 8192), 16, 0, 0); } while (0)
; #define PG8_LDA(dst, b, h) do { _Pragma("unroll") for (int m = 0; m < 4; ++m) _Pragma("unroll") for (int k = 0; k < 2; ++k) dst[m][k] = *(const LAS bf16x8*)(lds + PG8_SA(b, h) + aoff + m * 2048 + k * 1024); } while (0)
; #define PG8_LDB(dst, b, h) do { _Pragma("unroll") for (int n = 0; n < 2; ++n) _Pragma("unroll") for (int k = 0; k < 2; ++k) dst[n][k] = *(const LAS bf16x8*)(lds + PG8_SB(b, h) + boff + n * 2048 + k * 1024); } while (0)
; #define PG8_MMA(ai, bj, At, Bt) do { __builtin_amdgcn_s_setprio(1); _Pragma("unroll") for (int m = 0; m < 4; ++m) _Pragma("unroll") for (int n = 0; n < 2; ++n) _Pragma("unroll") for (int k = 0; k < 2; ++k) \
;         acc[ai][bj][m][n] = __builtin_amdgcn_mfma_f32_16x16x32_bf16(Bt[n][k], At[m][k], acc[ai][bj][m][n], 0, 0, 0); __builtin_amdgcn_s_setprio(0); } while (0)
; #define PG8_WAIT_V(n) asm volatile("s_waitcnt vmcnt(" #n ")" ::: "memory")
; #define PG8_WAIT_L(n) asm volatile("s_waitcnt lgkmcnt(" #n ")" ::: "memory")
; #define PG8_BAR __builtin_amdgcn_s_barrier()
; #define PG8_SCHED __builtin_amdgcn_sched_barrier(0)
; template <class Epi>
; __device__ __forceinline__ void gemm_phase(LAS unsigned char* lds, const Gemm g, const Sched& S, const Epi& E) {
;     ...
;             PG8_WAIT_V(8); PG8_WAIT_L(0); PG8_BAR; PG8_MMA(1, 0, At, B0); PG8_MMA(1, 1, At, B1); PG8_BAR; PG8_SCHED;
;             PG8_LDB(B0, 1, 0); PG8_LDB(B1, 1, 1); PG8_SCHED; PG8_LDA(At, 1, 0); PG8_STAGE(PG8_SA(0, 1), a2 + hstepA, voffA);
;             PG8_WAIT_V(8); PG8_WAIT_L(0); PG8_BAR; PG8_MMA(0, 0, At, B0); PG8_MMA(0, 1, At, B1); PG8_BAR; PG8_SCHED;
	s_waitcnt lgkmcnt(0)
	v_mfma_f32_16x16x32_bf16 v[60:63], v[146:149], v[178:181], v[60:63]
	v_mfma_f32_16x16x32_bf16 v[56:59], v[154:157], v[178:181], v[56:59]
	v_mfma_f32_16x16x32_bf16 v[52:55], v[146:149], v[186:189], v[52:55]
	v_mfma_f32_16x16x32_bf16 v[48:51], v[154:157], v[186:189], v[48:51]
	v_mfma_f32_16x16x32_bf16 v[36:39], v[146:149], v[194:197], v[36:39]
	v_mfma_f32_16x16x32_bf16 v[32:35], v[154:157], v[194:197], v[32:35]
	v_mfma_f32_16x16x32_bf16 v[20:23], v[146:149], v[204:207], v[20:23]
	v_mfma_f32_16x16x32_bf16 v[16:19], v[154:157], v[204:207], v[16:19]
	v_mfma_f32_16x16x32_bf16 v[60:63], v[150:153], v[182:185], v[60:63]
	v_mfma_f32_16x16x32_bf16 v[56:59], v[158:161], v[182:185], v[56:59]
	v_mfma_f32_16x16x32_bf16 v[52:55], v[150:153], v[190:193], v[52:55]
	v_mfma_f32_16x16x32_bf16 v[48:51], v[158:161], v[190:193], v[48:51]
	v_mfma_f32_16x16x32_bf16 v[36:39], v[150:153], v[198:201], v[36:39]
	v_mfma_f32_16x16x32_bf16 v[32:35], v[158:161], v[198:201], v[32:35]
	v_mfma_f32_16x16x32_bf16 v[20:23], v[150:153], v[208:211], v[20:23]
	v_mfma_f32_16x16x32_bf16 v[16:19], v[158:161], v[208:211], v[16:19]
	v_mfma_f32_16x16x32_bf16 v[44:47], v[162:165], v[178:181], v[44:47]
	v_mfma_f32_16x16x32_bf16 v[40:43], v[170:173], v[178:181], v[40:43]
	v_mfma_f32_16x16x32_bf16 v[28:31], v[162:165], v[186:189], v[28:31]
	v_mfma_f32_16x16x32_bf16 v[24:27], v[170:173], v[186:189], v[24:27]
	v_mfma_f32_16x16x32_bf16 v[12:15], v[162:165], v[194:197], v[12:15]
	v_mfma_f32_16x16x32_bf16 v[8:11], v[170:173], v[194:197], v[8:11]
	v_mfma_f32_16x16x32_bf16 v[4:7], v[162:165], v[204:207], v[4:7]
	v_mfma_f32_16x16x32_bf16 v[0:3], v[170:173], v[204:207], v[0:3]
	v_mfma_f32_16x16x32_bf16 v[44:47], v[166:169], v[182:185], v[44:47]
	v_mfma_f32_16x16x32_bf16 v[40:43], v[174:177], v[182:185], v[40:43]
	v_mfma_f32_16x16x32_bf16 v[28:31], v[166:169], v[190:193], v[28:31]
	v_mfma_f32_16x16x32_bf16 v[24:27], v[174:177], v[190:193], v[24:27]
	v_mfma_f32_16x16x32_bf16 v[12:15], v[166:169], v[198:201], v[12:15]
	v_mfma_f32_16x16x32_bf16 v[8:11], v[174:177], v[198:201], v[8:11]
	v_mfma_f32_16x16x32_bf16 v[4:7], v[166:169], v[208:211], v[4:7]
	v_mfma_f32_16x16x32_bf16 v[0:3], v[174:177], v[208:211], v[0:3]
	s_barrier
	s_add_i32 s67, 0, 0x18000
	s_add_i32 s78, 0, 0x1c000
	v_add_u32_e32 v158, s67, v141
	v_add_u32_e32 v174, s78, v141
	ds_read_b128 v[146:149], v158
	ds_read_b128 v[150:153], v158 offset:1024
	ds_read_b128 v[154:157], v158 offset:2048
	ds_read_b128 v[158:161], v158 offset:3072
	ds_read_b128 v[162:165], v174
	ds_read_b128 v[166:169], v174 offset:1024
	ds_read_b128 v[170:173], v174 offset:2048
	ds_read_b128 v[174:177], v174 offset:3072
	s_add_u32 s44, s44, 0x40000
	s_addc_u32 s45, s45, 0
	s_mov_b32 m0, s54
	v_lshl_add_u64 v[220:221], s[44:45], 0, v[128:129]
	ds_read_b128 v[178:181], v145 offset:32768
	ds_read_b128 v[182:185], v145 offset:33792
	ds_read_b128 v[186:189], v145 offset:34816
	ds_read_b128 v[190:193], v145 offset:35840
	ds_read_b128 v[194:197], v145 offset:36864
	ds_read_b128 v[198:201], v145 offset:37888
	ds_read_b128 v[204:207], v145 offset:38912
	ds_read_b128 v[208:211], v145 offset:39936
	global_load_lds_dwordx4 v[220:221], off
	v_lshl_add_u64 v[220:221], s[44:45], 0, v[132:133]
	s_mov_b32 m0, s55
	s_nop 0
	global_load_lds_dwordx4 v[220:221], off
	s_waitcnt vmcnt(8)
	s_waitcnt lgkmcnt(0)
	s_barrier
	s_waitcnt lgkmcnt(0)
	v_mfma_f32_16x16x32_bf16 v[124:127], v[146:149], v[178:181], v[124:127]
	v_mfma_f32_16x16x32_bf16 v[120:123], v[154:157], v[178:181], v[120:123]
	v_mfma_f32_16x16x32_bf16 v[116:119], v[146:149], v[186:189], v[116:119]
	v_mfma_f32_16x16x32_bf16 v[112:115], v[154:157], v[186:189], v[112:115]
	v_mfma_f32_16x16x32_bf16 v[100:103], v[146:149], v[194:197], v[100:103]
	v_mfma_f32_16x16x32_bf16 v[96:99], v[154:157], v[194:197], v[96:99]
	v_mfma_f32_16x16x32_bf16 v[84:87], v[146:149], v[204:207], v[84:87]
	v_mfma_f32_16x16x32_bf16 v[80:83], v[154:157], v[204:207], v[80:83]
	v_mfma_f32_16x16x32_bf16 v[124:127], v[150:153], v[182:185], v[124:127]
	v_mfma_f32_16x16x32_bf16 v[120:123], v[158:161], v[182:185], v[120:123]
	v_mfma_f32_16x16x32_bf16 v[116:119], v[150:153], v[190:193], v[116:119]
	v_mfma_f32_16x16x32_bf16 v[112:115], v[158:161], v[190:193], v[112:115]
	v_mfma_f32_16x16x32_bf16 v[100:103], v[150:153], v[198:201], v[100:103]
	v_mfma_f32_16x16x32_bf16 v[96:99], v[158:161], v[198:201], v[96:99]
	v_mfma_f32_16x16x32_bf16 v[84:87], v[150:153], v[208:211], v[84:87]
	v_mfma_f32_16x16x32_bf16 v[80:83], v[158:161], v[208:211], v[80:83]
	v_mfma_f32_16x16x32_bf16 v[108:111], v[162:165], v[178:181], v[108:111]
	v_mfma_f32_16x16x32_bf16 v[104:107], v[170:173], v[178:181], v[104:107]
	v_mfma_f32_16x16x32_bf16 v[92:95], v[162:165], v[186:189], v[92:95]
	v_mfma_f32_16x16x32_bf16 v[88:91], v[170:173], v[186:189], v[88:91]
	v_mfma_f32_16x16x32_bf16 v[76:79], v[162:165], v[194:197], v[76:79]
	v_mfma_f32_16x16x32_bf16 v[72:75], v[170:173], v[194:197], v[72:75]
	v_mfma_f32_16x16x32_bf16 v[68:71], v[162:165], v[204:207], v[68:71]
	v_mfma_f32_16x16x32_bf16 v[64:67], v[170:173], v[204:207], v[64:67]
	v_mfma_f32_16x16x32_bf16 v[108:111], v[166:169], v[182:185], v[108:111]
	v_mfma_f32_16x16x32_bf16 v[104:107], v[174:177], v[182:185], v[104:107]
	v_mfma_f32_16x16x32_bf16 v[92:95], v[166:169], v[190:193], v[92:95]
	v_mfma_f32_16x16x32_bf16 v[88:91], v[174:177], v[190:193], v[88:91]
	v_mfma_f32_16x16x32_bf16 v[76:79], v[166:169], v[198:201], v[76:79]
	v_mfma_f32_16x16x32_bf16 v[72:75], v[174:177], v[198:201], v[72:75]
	v_mfma_f32_16x16x32_bf16 v[68:71], v[166:169], v[208:211], v[68:71]
	v_mfma_f32_16x16x32_bf16 v[64:67], v[174:177], v[208:211], v[64:67]
	s_barrier
; #define PG8_STAGE(bufoff, gbase, voff) do { _Pragma("unroll") for (int _i = 0; _i < 2; ++_i) \
;         __builtin_amdgcn_global_load_lds((const unsigned*)((const char*)(gbase) + (voff)[_i]), (LAS unsigned*)(lds + (bufoff) + ldsw + _i * 8192), 16, 0, 0); } while (0)
; #define PG8_LDA(dst, b, h) do { _Pragma("unroll") for (int m = 0; m < 4; ++m) _Pragma("unroll") for (int k = 0; k < 2; ++k) dst[m][k] = *(const LAS bf16x8*)(lds + PG8_SA(b, h) + aoff + m * 2048 + k * 1024); } while (0)
; #define PG8_MMA(ai, bj, At, Bt) do { __builtin_amdgcn_s_setprio(1); _Pragma("unroll") for (int m = 0; m < 4; ++m) _Pragma("unroll") for (int n = 0; n < 2; ++n) _Pragma("unroll") for (int k = 0; k < 2; ++k) \
;         acc[ai][bj][m][n] = __builtin_amdgcn_mfma_f32_16x16x32_bf16(Bt[n][k], At[m][k], acc[ai][bj][m][n], 0, 0, 0); __builtin_amdgcn_s_setprio(0); } while (0)
; #define PG8_WAIT_V(n) asm volatile("s_waitcnt vmcnt(" #n ")" ::: "memory")
; #define PG8_WAIT_L(n) asm volatile("s_waitcnt lgkmcnt(" #n ")" ::: "memory")
; #define PG8_BAR __builtin_amdgcn_s_barrier()
; #define PG8_SCHED __builtin_amdgcn_sched_barrier(0)
; template <class Epi>
; __device__ __forceinline__ void gemm_phase(LAS unsigned char* lds, const Gemm g, const Sched& S, const Epi& E) {
;     ...
;             PG8_LDA(At, 1, 1); PG8_STAGE(PG8_SB(1, 0), b3, voffB); PG8_STAGE(PG8_SB(1, 1), b3 + hstepB, voffB); PG8_STAGE(PG8_SA(1, 0), a3, voffA);
;             PG8_WAIT_V(8); PG8_WAIT_L(0); PG8_BAR; PG8_MMA(1, 0, At, B0); PG8_MMA(1, 1, At, B1); PG8_BAR; PG8_SCHED;
;         }
;         if (wr == 0) PG8_BAR;
	s_add_i32 s44, s67, s52
	v_lshl_add_u64 v[212:213], v[212:213], 0, s[4:5]
	s_mov_b32 m0, s44
	ds_read_b128 v[178:181], v145 offset:49152
	ds_read_b128 v[182:185], v145 offset:50176
	ds_read_b128 v[186:189], v145 offset:51200
	ds_read_b128 v[190:193], v145 offset:52224
	ds_read_b128 v[194:197], v145 offset:53248
	ds_read_b128 v[198:201], v145 offset:54272
	ds_read_b128 v[204:207], v145 offset:55296
	ds_read_b128 v[208:211], v145 offset:56320
	global_load_lds_dwordx4 v[212:213], off
	s_add_i32 m0, s44, 0x2000
	s_add_u32 s40, s40, 0x40080
	v_lshl_add_u64 v[212:213], v[214:215], 0, s[4:5]
	s_addc_u32 s41, s41, 0
	s_add_i32 s44, s78, s52
	global_load_lds_dwordx4 v[212:213], off
	v_lshl_add_u64 v[212:213], s[40:41], 0, v[130:131]
	s_mov_b32 m0, s44
	s_nop 0
	global_load_lds_dwordx4 v[212:213], off
	v_lshl_add_u64 v[212:213], s[40:41], 0, v[134:135]
	s_add_i32 m0, s44, 0x2000
	s_nop 0
	global_load_lds_dwordx4 v[212:213], off
	v_lshl_add_u64 v[212:213], v[216:217], 0, s[4:5]
	s_mov_b32 m0, s57
	s_nop 0
	global_load_lds_dwordx4 v[212:213], off
	v_lshl_add_u64 v[212:213], v[218:219], 0, s[4:5]
	s_mov_b32 m0, s58
	s_nop 0
	global_load_lds_dwordx4 v[212:213], off
	s_waitcnt vmcnt(8)
	s_waitcnt lgkmcnt(0)
	s_barrier
	s_waitcnt lgkmcnt(0)
	v_mfma_f32_16x16x32_bf16 v[60:63], v[146:149], v[178:181], v[60:63]
	v_mfma_f32_16x16x32_bf16 v[56:59], v[154:157], v[178:181], v[56:59]
	v_mfma_f32_16x16x32_bf16 v[52:55], v[146:149], v[186:189], v[52:55]
	v_mfma_f32_16x16x32_bf16 v[48:51], v[154:157], v[186:189], v[48:51]
	v_mfma_f32_16x16x32_bf16 v[36:39], v[146:149], v[194:197], v[36:39]
	v_mfma_f32_16x16x32_bf16 v[32:35], v[154:157], v[194:197], v[32:35]
	v_mfma_f32_16x16x32_bf16 v[20:23], v[146:149], v[204:207], v[20:23]
	v_mfma_f32_16x16x32_bf16 v[16:19], v[154:157], v[204:207], v[16:19]
	v_mfma_f32_16x16x32_bf16 v[60:63], v[150:153], v[182:185], v[60:63]
	v_mfma_f32_16x16x32_bf16 v[56:59], v[158:161], v[182:185], v[56:59]
	v_mfma_f32_16x16x32_bf16 v[52:55], v[150:153], v[190:193], v[52:55]
	v_mfma_f32_16x16x32_bf16 v[48:51], v[158:161], v[190:193], v[48:51]
	v_mfma_f32_16x16x32_bf16 v[36:39], v[150:153], v[198:201], v[36:39]
	v_mfma_f32_16x16x32_bf16 v[32:35], v[158:161], v[198:201], v[32:35]
	v_mfma_f32_16x16x32_bf16 v[20:23], v[150:153], v[208:211], v[20:23]
	v_mfma_f32_16x16x32_bf16 v[16:19], v[158:161], v[208:211], v[16:19]
	v_mfma_f32_16x16x32_bf16 v[44:47], v[162:165], v[178:181], v[44:47]
	v_mfma_f32_16x16x32_bf16 v[40:43], v[170:173], v[178:181], v[40:43]
	v_mfma_f32_16x16x32_bf16 v[28:31], v[162:165], v[186:189], v[28:31]
	v_mfma_f32_16x16x32_bf16 v[24:27], v[170:173], v[186:189], v[24:27]
	v_mfma_f32_16x16x32_bf16 v[12:15], v[162:165], v[194:197], v[12:15]
	v_mfma_f32_16x16x32_bf16 v[8:11], v[170:173], v[194:197], v[8:11]
	v_mfma_f32_16x16x32_bf16 v[4:7], v[162:165], v[204:207], v[4:7]
	v_mfma_f32_16x16x32_bf16 v[0:3], v[170:173], v[204:207], v[0:3]
	v_mfma_f32_16x16x32_bf16 v[44:47], v[166:169], v[182:185], v[44:47]
	v_mfma_f32_16x16x32_bf16 v[40:43], v[174:177], v[182:185], v[40:43]
	v_mfma_f32_16x16x32_bf16 v[28:31], v[166:169], v[190:193], v[28:31]
	v_mfma_f32_16x16x32_bf16 v[24:27], v[174:177], v[190:193], v[24:27]
	v_mfma_f32_16x16x32_bf16 v[12:15], v[166:169], v[198:201], v[12:15]
	v_mfma_f32_16x16x32_bf16 v[8:11], v[174:177], v[198:201], v[8:11]
	v_mfma_f32_16x16x32_bf16 v[4:7], v[166:169], v[208:211], v[4:7]
	v_mfma_f32_16x16x32_bf16 v[0:3], v[174:177], v[208:211], v[0:3]
	s_add_i32 s66, s66, 2
	s_add_u32 s28, s28, 0x100
	s_addc_u32 s29, s29, 0
	s_add_u32 s64, s64, 0x100
	s_addc_u32 s65, s65, 0
	s_cmp_gt_u32 s66, 13
	s_barrier
	s_cbranch_scc0 .LBB0_293
	s_and_b64 vcc, exec, s[6:7]
	s_cbranch_vccz .LBB0_296
	s_barrier

; #define PG8_STAGE(bufoff, gbase, voff) do { _Pragma("unroll") for (int _i = 0; _i < 2; ++_i) \
;         __builtin_amdgcn_global_load_lds((const unsigned*)((const char*)(gbase) + (voff)[_i]), (LAS unsigned*)(lds + (bufoff) + ldsw + _i * 8192), 16, 0, 0); } while (0)
; #define PG8_LDA(dst, b, h) do { _Pragma("unroll") for (int m = 0; m < 4; ++m) _Pragma("unroll") for (int k = 0; k < 2; ++k) dst[m][k] = *(const LAS bf16x8*)(lds + PG8_SA(b, h) + aoff + m * 2048 + k * 1024); } while (0)
; #define PG8_LDB(dst, b, h) do { _Pragma("unroll") for (int n = 0; n < 2; ++n) _Pragma("unroll") for (int k = 0; k < 2; ++k) dst[n][k] = *(const LAS bf16x8*)(lds + PG8_SB(b, h) + boff + n * 2048 + k * 1024); } while (0)
; #define PG8_MMA(ai, bj, At, Bt) do { __builtin_amdgcn_s_setprio(1); _Pragma("unroll") for (int m = 0; m < 4; ++m) _Pragma("unroll") for (int n = 0; n < 2; ++n) _Pragma("unroll") for (int k = 0; k < 2; ++k) \
;         acc[ai][bj][m][n] = __builtin_amdgcn_mfma_f32_16x16x32_bf16(Bt[n][k], At[m][k], acc[ai][bj][m][n], 0, 0, 0); __builtin_amdgcn_s_setprio(0); } while (0)
; #define PG8_WAIT_V(n) asm volatile("s_waitcnt vmcnt(" #n ")" ::: "memory")
; #define PG8_WAIT_L(n) asm volatile("s_waitcnt lgkmcnt(" #n ")" ::: "memory")
; #define PG8_BAR __builtin_amdgcn_s_barrier()
; #define PG8_SCHED __builtin_amdgcn_sched_barrier(0)
; template <class Epi>
; __device__ __forceinline__ void gemm_phase(LAS unsigned char* lds, const Gemm g, const Sched& S, const Epi& E) {
;     ...
;         for (int t = 0; t < nt; t += 2) {
;             const bool last = (t == nt - 2);
;             const char* a1 = cA + (size_t)(t + 1) * kstep;
;             const char* a2 = last ? nA : cA + (size_t)(t + 2) * kstep; const char* b2 = last ? nB : cB + (size_t)(t + 2) * kstep;
;             const char* a3 = a2 + kstep; const char* b3 = b2 + kstep;
;             PG8_LDB(B0, 0, 0); PG8_LDB(B1, 0, 1); PG8_SCHED; PG8_LDA(At, 0, 0); PG8_STAGE(PG8_SA(1, 1), a1 + hstepA, voffA);
;             PG8_WAIT_V(8); PG8_WAIT_L(0); PG8_BAR; PG8_MMA(0, 0, At, B0); PG8_MMA(0, 1, At, B1); PG8_BAR; PG8_SCHED;
;             PG8_LDA(At, 0, 1); PG8_STAGE(PG8_SB(0, 0), b2, voffB); PG8_STAGE(PG8_SB(0, 1), b2 + hstepB, voffB); PG8_STAGE(PG8_SA(0, 0), a2, voffA);
;             PG8_WAIT_V(8); PG8_WAIT_L(0); PG8_BAR; PG8_MMA(1, 0, At, B0); PG8_MMA(1, 1, At, B1); PG8_BAR; PG8_SCHED;
.LBB0_374:
	v_add_u32_e32 v158, s64, v144
	v_add_u32_e32 v174, s65, v144
	s_add_u32 s40, s26, s28
	ds_read_b128 v[146:149], v158
	ds_read_b128 v[150:153], v158 offset:1024
	ds_read_b128 v[154:157], v158 offset:2048
	ds_read_b128 v[158:161], v158 offset:3072
	ds_read_b128 v[162:165], v174
	ds_read_b128 v[166:169], v174 offset:1024
	ds_read_b128 v[170:173], v174 offset:2048
	ds_read_b128 v[174:177], v174 offset:3072
	s_addc_u32 s41, s27, s29
	s_add_u32 s40, s40, 0x100
	s_addc_u32 s41, s41, 0
	s_add_u32 s84, s87, s28
	s_addc_u32 s85, s88, s29
	s_cmpk_eq_i32 s28, 0x1500
	s_cselect_b32 s45, s23, s41
	s_cselect_b32 s44, s22, s40
	s_cselect_b32 s41, s25, s85
	s_cselect_b32 s40, s24, s84
	s_mov_b32 m0, s66
	v_lshl_add_u64 v[186:187], v[140:141], 0, s[28:29]
	ds_read_b128 v[178:181], v145
	ds_read_b128 v[182:185], v145 offset:1024
	ds_read_b128 v[192:195], v145 offset:2048
	ds_read_b128 v[196:199], v145 offset:3072
	ds_read_b128 v[204:207], v145 offset:4096
	ds_read_b128 v[208:211], v145 offset:5120
	ds_read_b128 v[212:215], v145 offset:6144
	ds_read_b128 v[216:219], v145 offset:7168
	global_load_lds_dwordx4 v[186:187], off
	v_lshl_add_u64 v[186:187], v[142:143], 0, s[28:29]
	s_mov_b32 m0, s67
	s_nop 0
	global_load_lds_dwordx4 v[186:187], off
	s_waitcnt vmcnt(8)
	s_waitcnt lgkmcnt(0)
	s_barrier
	s_waitcnt lgkmcnt(0)
	v_mfma_f32_16x16x32_bf16 v[124:127], v[146:149], v[178:181], v[124:127]
	v_mfma_f32_16x16x32_bf16 v[120:123], v[154:157], v[178:181], v[120:123]
	v_mfma_f32_16x16x32_bf16 v[108:111], v[146:149], v[192:195], v[108:111]
	v_mfma_f32_16x16x32_bf16 v[104:107], v[154:157], v[192:195], v[104:107]
	v_mfma_f32_16x16x32_bf16 v[92:95], v[146:149], v[204:207], v[92:95]
	v_mfma_f32_16x16x32_bf16 v[88:91], v[154:157], v[204:207], v[88:91]
	v_mfma_f32_16x16x32_bf16 v[76:79], v[146:149], v[212:215], v[76:79]
	v_mfma_f32_16x16x32_bf16 v[72:75], v[154:157], v[212:215], v[72:75]
	v_mfma_f32_16x16x32_bf16 v[124:127], v[150:153], v[182:185], v[124:127]
	v_mfma_f32_16x16x32_bf16 v[120:123], v[158:161], v[182:185], v[120:123]
	v_mfma_f32_16x16x32_bf16 v[108:111], v[150:153], v[196:199], v[108:111]
	v_mfma_f32_16x16x32_bf16 v[104:107], v[158:161], v[196:199], v[104:107]
	v_mfma_f32_16x16x32_bf16 v[92:95], v[150:153], v[208:211], v[92:95]
	v_mfma_f32_16x16x32_bf16 v[88:91], v[158:161], v[208:211], v[88:91]
	v_mfma_f32_16x16x32_bf16 v[76:79], v[150:153], v[216:219], v[76:79]
	v_mfma_f32_16x16x32_bf16 v[72:75], v[158:161], v[216:219], v[72:75]
	v_mfma_f32_16x16x32_bf16 v[116:119], v[162:165], v[178:181], v[116:119]
	v_mfma_f32_16x16x32_bf16 v[112:115], v[170:173], v[178:181], v[112:115]
	v_mfma_f32_16x16x32_bf16 v[100:103], v[162:165], v[192:195], v[100:103]
	v_mfma_f32_16x16x32_bf16 v[96:99], v[170:173], v[192:195], v[96:99]
	v_mfma_f32_16x16x32_bf16 v[84:87], v[162:165], v[204:207], v[84:87]
	v_mfma_f32_16x16x32_bf16 v[80:83], v[170:173], v[204:207], v[80:83]
	v_mfma_f32_16x16x32_bf16 v[68:71], v[162:165], v[212:215], v[68:71]
	v_mfma_f32_16x16x32_bf16 v[64:67], v[170:173], v[212:215], v[64:67]
	v_mfma_f32_16x16x32_bf16 v[116:119], v[166:169], v[182:185], v[116:119]
	v_mfma_f32_16x16x32_bf16 v[112:115], v[174:177], v[182:185], v[112:115]
	v_mfma_f32_16x16x32_bf16 v[100:103], v[166:169], v[196:199], v[100:103]
	v_mfma_f32_16x16x32_bf16 v[96:99], v[174:177], v[196:199], v[96:99]
	v_mfma_f32_16x16x32_bf16 v[84:87], v[166:169], v[208:211], v[84:87]
	v_mfma_f32_16x16x32_bf16 v[80:83], v[174:177], v[208:211], v[80:83]
	v_mfma_f32_16x16x32_bf16 v[68:71], v[166:169], v[216:219], v[68:71]
	v_mfma_f32_16x16x32_bf16 v[64:67], v[174:177], v[216:219], v[64:67]
	s_barrier
	s_mov_b32 m0, s78
	v_lshl_add_u64 v[186:187], s[40:41], 0, v[130:131]
	ds_read_b128 v[178:181], v145 offset:16384
	ds_read_b128 v[182:185], v145 offset:17408
	ds_read_b128 v[192:195], v145 offset:18432
	ds_read_b128 v[196:199], v145 offset:19456
	ds_read_b128 v[204:207], v145 offset:20480
	ds_read_b128 v[208:211], v145 offset:21504
	ds_read_b128 v[212:215], v145 offset:22528
	ds_read_b128 v[216:219], v145 offset:23552
	global_load_lds_dwordx4 v[186:187], off
	s_add_i32 m0, s78, 0x2000
	s_add_u32 s84, s40, 0xb0000
	v_lshl_add_u64 v[200:201], s[40:41], 0, v[134:135]
	s_addc_u32 s85, s41, 0
	s_add_i32 s90, s65, s56
	global_load_lds_dwordx4 v[200:201], off
	v_lshl_add_u64 v[220:221], s[84:85], 0, v[130:131]
	s_mov_b32 m0, s90
	v_lshl_add_u64 v[222:223], s[44:45], 0, v[132:133]
	global_load_lds_dwordx4 v[220:221], off
	v_lshl_add_u64 v[220:221], s[84:85], 0, v[134:135]
	s_add_i32 m0, s90, 0x2000
	s_nop 0
	global_load_lds_dwordx4 v[220:221], off
	v_lshl_add_u64 v[220:221], s[44:45], 0, v[128:129]
	s_mov_b32 m0, s57
	s_nop 0
	global_load_lds_dwordx4 v[220:221], off
	s_mov_b32 m0, s58
	s_nop 0
	global_load_lds_dwordx4 v[222:223], off
	s_waitcnt vmcnt(8)
	s_waitcnt lgkmcnt(0)
	s_barrier
; #define PG8_STAGE(bufoff, gbase, voff) do { _Pragma("unroll") for (int _i = 0; _i < 2; ++_i) \
;         __builtin_amdgcn_global_load_lds((const unsigned*)((const char*)(gbase) + (voff)[_i]), (LAS unsigned*)(lds + (bufoff) + ldsw + _i * 8192), 16, 0, 0); } while (0)
; #define PG8_LDA(dst, b, h) do { _Pragma("unroll") for (int m = 0; m < 4; ++m) _Pragma("unroll") for (int k = 0; k < 2; ++k) dst[m][k] = *(const LAS bf16x8*)(lds + PG8_SA(b, h) + aoff + m * 2048 + k * 1024); } while (0)
; #define PG8_LDB(dst, b, h) do { _Pragma("unroll") for (int n = 0; n < 2; ++n) _Pragma("unroll") for (int k = 0; k < 2; ++k) dst[n][k] = *(const LAS bf16x8*)(lds + PG8_SB(b, h) + boff + n * 2048 + k * 1024); } while (0)
; #define PG8_MMA(ai, bj, At, Bt) do { __builtin_amdgcn_s_setprio(1); _Pragma("unroll") for (int m = 0; m < 4; ++m) _Pragma("unroll") for (int n = 0; n < 2; ++n) _Pragma("unroll") for (int k = 0; k < 2; ++k) \
;         acc[ai][bj][m][n] = __builtin_amdgcn_mfma_f32_16x16x32_bf16(Bt[n][k], At[m][k], acc[ai][bj][m][n], 0, 0, 0); __builtin_amdgcn_s_setprio(0); } while (0)
; #define PG8_WAIT_V(n) asm volatile("s_waitcnt vmcnt(" #n ")" ::: "memory")
; #define PG8_WAIT_L(n) asm volatile("s_waitcnt lgkmcnt(" #n ")" ::: "memory")
; #define PG8_BAR __builtin_amdgcn_s_barrier()
; #define PG8_SCHED __builtin_amdgcn_sched_barrier(0)
; template <class Epi>
; __device__ __forceinline__ void gemm_phase(LAS unsigned char* lds, const Gemm g, const Sched& S, const Epi& E) {
;     ...
;             PG8_WAIT_V(8); PG8_WAIT_L(0); PG8_BAR; PG8_MMA(1, 0, At, B0); PG8_MMA(1, 1, At, B1); PG8_BAR; PG8_SCHED;
;             PG8_LDB(B0, 1, 0); PG8_LDB(B1, 1, 1); PG8_SCHED; PG8_LDA(At, 1, 0); PG8_STAGE(PG8_SA(0, 1), a2 + hstepA, voffA);
;             PG8_WAIT_V(8); PG8_WAIT_L(0); PG8_BAR; PG8_MMA(0, 0, At, B0); PG8_MMA(0, 1, At, B1); PG8_BAR; PG8_SCHED;
	s_waitcnt lgkmcnt(0)
	v_mfma_f32_16x16x32_bf16 v[60:63], v[146:149], v[178:181], v[60:63]
	v_mfma_f32_16x16x32_bf16 v[56:59], v[154:157], v[178:181], v[56:59]
	v_mfma_f32_16x16x32_bf16 v[44:47], v[146:149], v[192:195], v[44:47]
	v_mfma_f32_16x16x32_bf16 v[40:43], v[154:157], v[192:195], v[40:43]
	v_mfma_f32_16x16x32_bf16 v[28:31], v[146:149], v[204:207], v[28:31]
	v_mfma_f32_16x16x32_bf16 v[24:27], v[154:157], v[204:207], v[24:27]
	v_mfma_f32_16x16x32_bf16 v[12:15], v[146:149], v[212:215], v[12:15]
	v_mfma_f32_16x16x32_bf16 v[8:11], v[154:157], v[212:215], v[8:11]
	v_mfma_f32_16x16x32_bf16 v[60:63], v[150:153], v[182:185], v[60:63]
	v_mfma_f32_16x16x32_bf16 v[56:59], v[158:161], v[182:185], v[56:59]
	v_mfma_f32_16x16x32_bf16 v[44:47], v[150:153], v[196:199], v[44:47]
	v_mfma_f32_16x16x32_bf16 v[40:43], v[158:161], v[196:199], v[40:43]
	v_mfma_f32_16x16x32_bf16 v[28:31], v[150:153], v[208:211], v[28:31]
	v_mfma_f32_16x16x32_bf16 v[24:27], v[158:161], v[208:211], v[24:27]
	v_mfma_f32_16x16x32_bf16 v[12:15], v[150:153], v[216:219], v[12:15]
	v_mfma_f32_16x16x32_bf16 v[8:11], v[158:161], v[216:219], v[8:11]
	v_mfma_f32_16x16x32_bf16 v[52:55], v[162:165], v[178:181], v[52:55]
	v_mfma_f32_16x16x32_bf16 v[48:51], v[170:173], v[178:181], v[48:51]
	v_mfma_f32_16x16x32_bf16 v[36:39], v[162:165], v[192:195], v[36:39]
	v_mfma_f32_16x16x32_bf16 v[32:35], v[170:173], v[192:195], v[32:35]
	v_mfma_f32_16x16x32_bf16 v[20:23], v[162:165], v[204:207], v[20:23]
	v_mfma_f32_16x16x32_bf16 v[16:19], v[170:173], v[204:207], v[16:19]
	v_mfma_f32_16x16x32_bf16 v[4:7], v[162:165], v[212:215], v[4:7]
	v_mfma_f32_16x16x32_bf16 v[0:3], v[170:173], v[212:215], v[0:3]
	v_mfma_f32_16x16x32_bf16 v[52:55], v[166:169], v[182:185], v[52:55]
	v_mfma_f32_16x16x32_bf16 v[48:51], v[174:177], v[182:185], v[48:51]
	v_mfma_f32_16x16x32_bf16 v[36:39], v[166:169], v[196:199], v[36:39]
	v_mfma_f32_16x16x32_bf16 v[32:35], v[174:177], v[196:199], v[32:35]
	v_mfma_f32_16x16x32_bf16 v[20:23], v[166:169], v[208:211], v[20:23]
	v_mfma_f32_16x16x32_bf16 v[16:19], v[174:177], v[208:211], v[16:19]
	v_mfma_f32_16x16x32_bf16 v[4:7], v[166:169], v[216:219], v[4:7]
	v_mfma_f32_16x16x32_bf16 v[0:3], v[174:177], v[216:219], v[0:3]
	s_barrier
	s_add_i32 s84, 0, 0x18000
	s_add_i32 s85, 0, 0x1c000
	v_add_u32_e32 v158, s84, v144
	v_add_u32_e32 v174, s85, v144
	ds_read_b128 v[146:149], v158
	ds_read_b128 v[150:153], v158 offset:1024
	ds_read_b128 v[154:157], v158 offset:2048
	ds_read_b128 v[158:161], v158 offset:3072
	ds_read_b128 v[162:165], v174
	ds_read_b128 v[166:169], v174 offset:1024
	ds_read_b128 v[170:173], v174 offset:2048
	ds_read_b128 v[174:177], v174 offset:3072
	s_add_u32 s44, s44, 0xb0000
	s_addc_u32 s45, s45, 0
	s_mov_b32 m0, s59
	v_lshl_add_u64 v[224:225], s[44:45], 0, v[128:129]
	ds_read_b128 v[178:181], v145 offset:32768
	ds_read_b128 v[182:185], v145 offset:33792
	ds_read_b128 v[192:195], v145 offset:34816
	ds_read_b128 v[196:199], v145 offset:35840
	ds_read_b128 v[204:207], v145 offset:36864
	ds_read_b128 v[208:211], v145 offset:37888
	ds_read_b128 v[212:215], v145 offset:38912
	ds_read_b128 v[216:219], v145 offset:39936
	global_load_lds_dwordx4 v[224:225], off
	v_lshl_add_u64 v[224:225], s[44:45], 0, v[132:133]
	s_mov_b32 m0, s60
	s_nop 0
	global_load_lds_dwordx4 v[224:225], off
	s_waitcnt vmcnt(8)
	s_waitcnt lgkmcnt(0)
	s_barrier
	s_waitcnt lgkmcnt(0)
	v_mfma_f32_16x16x32_bf16 v[124:127], v[146:149], v[178:181], v[124:127]
	v_mfma_f32_16x16x32_bf16 v[120:123], v[154:157], v[178:181], v[120:123]
	v_mfma_f32_16x16x32_bf16 v[108:111], v[146:149], v[192:195], v[108:111]
	v_mfma_f32_16x16x32_bf16 v[104:107], v[154:157], v[192:195], v[104:107]
	v_mfma_f32_16x16x32_bf16 v[92:95], v[146:149], v[204:207], v[92:95]
	v_mfma_f32_16x16x32_bf16 v[88:91], v[154:157], v[204:207], v[88:91]
	v_mfma_f32_16x16x32_bf16 v[76:79], v[146:149], v[212:215], v[76:79]
	v_mfma_f32_16x16x32_bf16 v[72:75], v[154:157], v[212:215], v[72:75]
	v_mfma_f32_16x16x32_bf16 v[124:127], v[150:153], v[182:185], v[124:127]
	v_mfma_f32_16x16x32_bf16 v[120:123], v[158:161], v[182:185], v[120:123]
	v_mfma_f32_16x16x32_bf16 v[108:111], v[150:153], v[196:199], v[108:111]
	v_mfma_f32_16x16x32_bf16 v[104:107], v[158:161], v[196:199], v[104:107]
	v_mfma_f32_16x16x32_bf16 v[92:95], v[150:153], v[208:211], v[92:95]
	v_mfma_f32_16x16x32_bf16 v[88:91], v[158:161], v[208:211], v[88:91]
	v_mfma_f32_16x16x32_bf16 v[76:79], v[150:153], v[216:219], v[76:79]
	v_mfma_f32_16x16x32_bf16 v[72:75], v[158:161], v[216:219], v[72:75]
	v_mfma_f32_16x16x32_bf16 v[116:119], v[162:165], v[178:181], v[116:119]
	v_mfma_f32_16x16x32_bf16 v[112:115], v[170:173], v[178:181], v[112:115]
	v_mfma_f32_16x16x32_bf16 v[100:103], v[162:165], v[192:195], v[100:103]
	v_mfma_f32_16x16x32_bf16 v[96:99], v[170:173], v[192:195], v[96:99]
	v_mfma_f32_16x16x32_bf16 v[84:87], v[162:165], v[204:207], v[84:87]
	v_mfma_f32_16x16x32_bf16 v[80:83], v[170:173], v[204:207], v[80:83]
	v_mfma_f32_16x16x32_bf16 v[68:71], v[162:165], v[212:215], v[68:71]
	v_mfma_f32_16x16x32_bf16 v[64:67], v[170:173], v[212:215], v[64:67]
	v_mfma_f32_16x16x32_bf16 v[116:119], v[166:169], v[182:185], v[116:119]
	v_mfma_f32_16x16x32_bf16 v[112:115], v[174:177], v[182:185], v[112:115]
	v_mfma_f32_16x16x32_bf16 v[100:103], v[166:169], v[196:199], v[100:103]
	v_mfma_f32_16x16x32_bf16 v[96:99], v[174:177], v[196:199], v[96:99]
	v_mfma_f32_16x16x32_bf16 v[84:87], v[166:169], v[208:211], v[84:87]
	v_mfma_f32_16x16x32_bf16 v[80:83], v[174:177], v[208:211], v[80:83]
	v_mfma_f32_16x16x32_bf16 v[68:71], v[166:169], v[216:219], v[68:71]
	v_mfma_f32_16x16x32_bf16 v[64:67], v[174:177], v[216:219], v[64:67]
	s_barrier
; #define PG8_STAGE(bufoff, gbase, voff) do { _Pragma("unroll") for (int _i = 0; _i < 2; ++_i) \
;         __builtin_amdgcn_global_load_lds((const unsigned*)((const char*)(gbase) + (voff)[_i]), (LAS unsigned*)(lds + (bufoff) + ldsw + _i * 8192), 16, 0, 0); } while (0)
; #define PG8_LDA(dst, b, h) do { _Pragma("unroll") for (int m = 0; m < 4; ++m) _Pragma("unroll") for (int k = 0; k < 2; ++k) dst[m][k] = *(const LAS bf16x8*)(lds + PG8_SA(b, h) + aoff + m * 2048 + k * 1024); } while (0)
; #define PG8_MMA(ai, bj, At, Bt) do { __builtin_amdgcn_s_setprio(1); _Pragma("unroll") for (int m = 0; m < 4; ++m) _Pragma("unroll") for (int n = 0; n < 2; ++n) _Pragma("unroll") for (int k = 0; k < 2; ++k) \
;         acc[ai][bj][m][n] = __builtin_amdgcn_mfma_f32_16x16x32_bf16(Bt[n][k], At[m][k], acc[ai][bj][m][n], 0, 0, 0); __builtin_amdgcn_s_setprio(0); } while (0)
; #define PG8_WAIT_V(n) asm volatile("s_waitcnt vmcnt(" #n ")" ::: "memory")
; #define PG8_WAIT_L(n) asm volatile("s_waitcnt lgkmcnt(" #n ")" ::: "memory")
; #define PG8_BAR __builtin_amdgcn_s_barrier()
; #define PG8_SCHED __builtin_amdgcn_sched_barrier(0)
; template <class Epi>
; __device__ __forceinline__ void gemm_phase(LAS unsigned char* lds, const Gemm g, const Sched& S, const Epi& E) {
;     ...
;             PG8_LDA(At, 1, 1); PG8_STAGE(PG8_SB(1, 0), b3, voffB); PG8_STAGE(PG8_SB(1, 1), b3 + hstepB, voffB); PG8_STAGE(PG8_SA(1, 0), a3, voffA);
;             PG8_WAIT_V(8); PG8_WAIT_L(0); PG8_BAR; PG8_MMA(1, 0, At, B0); PG8_MMA(1, 1, At, B1); PG8_BAR; PG8_SCHED;
;         }
;         if (wr == 0) PG8_BAR;
	s_add_i32 s44, s84, s56
	v_lshl_add_u64 v[186:187], v[186:187], 0, s[8:9]
	s_mov_b32 m0, s44
	ds_read_b128 v[178:181], v145 offset:49152
	ds_read_b128 v[182:185], v145 offset:50176
	ds_read_b128 v[192:195], v145 offset:51200
	ds_read_b128 v[196:199], v145 offset:52224
	ds_read_b128 v[204:207], v145 offset:53248
	ds_read_b128 v[208:211], v145 offset:54272
	ds_read_b128 v[212:215], v145 offset:55296
	ds_read_b128 v[216:219], v145 offset:56320
	global_load_lds_dwordx4 v[186:187], off
	s_add_i32 m0, s44, 0x2000
	s_add_u32 s40, s40, 0xb0080
	v_lshl_add_u64 v[186:187], v[200:201], 0, s[8:9]
	s_addc_u32 s41, s41, 0
	s_add_i32 s44, s85, s56
	global_load_lds_dwordx4 v[186:187], off
	v_lshl_add_u64 v[186:187], s[40:41], 0, v[130:131]
	s_mov_b32 m0, s44
	s_nop 0
	global_load_lds_dwordx4 v[186:187], off
	v_lshl_add_u64 v[186:187], s[40:41], 0, v[134:135]
	s_add_i32 m0, s44, 0x2000
	s_nop 0
	global_load_lds_dwordx4 v[186:187], off
	v_lshl_add_u64 v[186:187], v[220:221], 0, s[8:9]
	s_mov_b32 m0, s62
	s_nop 0
	global_load_lds_dwordx4 v[186:187], off
	v_lshl_add_u64 v[186:187], v[222:223], 0, s[8:9]
	s_mov_b32 m0, s63
	s_nop 0
	global_load_lds_dwordx4 v[186:187], off
	s_waitcnt vmcnt(8)
	s_waitcnt lgkmcnt(0)
	s_barrier
	s_waitcnt lgkmcnt(0)
	v_mfma_f32_16x16x32_bf16 v[60:63], v[146:149], v[178:181], v[60:63]
	v_mfma_f32_16x16x32_bf16 v[56:59], v[154:157], v[178:181], v[56:59]
	v_mfma_f32_16x16x32_bf16 v[44:47], v[146:149], v[192:195], v[44:47]
	v_mfma_f32_16x16x32_bf16 v[40:43], v[154:157], v[192:195], v[40:43]
	v_mfma_f32_16x16x32_bf16 v[28:31], v[146:149], v[204:207], v[28:31]
	v_mfma_f32_16x16x32_bf16 v[24:27], v[154:157], v[204:207], v[24:27]
	v_mfma_f32_16x16x32_bf16 v[12:15], v[146:149], v[212:215], v[12:15]
	v_mfma_f32_16x16x32_bf16 v[8:11], v[154:157], v[212:215], v[8:11]
	v_mfma_f32_16x16x32_bf16 v[60:63], v[150:153], v[182:185], v[60:63]
	v_mfma_f32_16x16x32_bf16 v[56:59], v[158:161], v[182:185], v[56:59]
	v_mfma_f32_16x16x32_bf16 v[44:47], v[150:153], v[196:199], v[44:47]
	v_mfma_f32_16x16x32_bf16 v[40:43], v[158:161], v[196:199], v[40:43]
	v_mfma_f32_16x16x32_bf16 v[28:31], v[150:153], v[208:211], v[28:31]
	v_mfma_f32_16x16x32_bf16 v[24:27], v[158:161], v[208:211], v[24:27]
	v_mfma_f32_16x16x32_bf16 v[12:15], v[150:153], v[216:219], v[12:15]
	v_mfma_f32_16x16x32_bf16 v[8:11], v[158:161], v[216:219], v[8:11]
	v_mfma_f32_16x16x32_bf16 v[52:55], v[162:165], v[178:181], v[52:55]
	v_mfma_f32_16x16x32_bf16 v[48:51], v[170:173], v[178:181], v[48:51]
	v_mfma_f32_16x16x32_bf16 v[36:39], v[162:165], v[192:195], v[36:39]
	v_mfma_f32_16x16x32_bf16 v[32:35], v[170:173], v[192:195], v[32:35]
	v_mfma_f32_16x16x32_bf16 v[20:23], v[162:165], v[204:207], v[20:23]
	v_mfma_f32_16x16x32_bf16 v[16:19], v[170:173], v[204:207], v[16:19]
	v_mfma_f32_16x16x32_bf16 v[4:7], v[162:165], v[212:215], v[4:7]
	v_mfma_f32_16x16x32_bf16 v[0:3], v[170:173], v[212:215], v[0:3]
	v_mfma_f32_16x16x32_bf16 v[52:55], v[166:169], v[182:185], v[52:55]
	v_mfma_f32_16x16x32_bf16 v[48:51], v[174:177], v[182:185], v[48:51]
	v_mfma_f32_16x16x32_bf16 v[36:39], v[166:169], v[196:199], v[36:39]
	v_mfma_f32_16x16x32_bf16 v[32:35], v[174:177], v[196:199], v[32:35]
	v_mfma_f32_16x16x32_bf16 v[20:23], v[166:169], v[208:211], v[20:23]
	v_mfma_f32_16x16x32_bf16 v[16:19], v[174:177], v[208:211], v[16:19]
	v_mfma_f32_16x16x32_bf16 v[4:7], v[166:169], v[216:219], v[4:7]
	v_mfma_f32_16x16x32_bf16 v[0:3], v[174:177], v[216:219], v[0:3]
	s_add_i32 s89, s89, 2
	s_add_u32 s28, s28, 0x100
	s_addc_u32 s29, s29, 0
	s_cmp_gt_u32 s89, 41
	s_barrier
	s_cbranch_scc0 .LBB0_374
	s_and_b64 vcc, exec, s[14:15]
	s_cbranch_vccz .LBB0_377
	s_barrier

; #define PG8_MMA(ai, bj, At, Bt) do { __builtin_amdgcn_s_setprio(1); _Pragma("unroll") for (int m = 0; m < 4; ++m) _Pragma("unroll") for (int n = 0; n < 2; ++n) _Pragma("unroll") for (int k = 0; k < 2; ++k) \
;         acc[ai][bj][m][n] = __builtin_amdgcn_mfma_f32_16x16x32_bf16(Bt[n][k], At[m][k], acc[ai][bj][m][n], 0, 0, 0); __builtin_amdgcn_s_setprio(0); } while (0)
; #define PG8_WAIT_V(n) asm volatile("s_waitcnt vmcnt(" #n ")" ::: "memory")
; #define PG8_WAIT_L(n) asm volatile("s_waitcnt lgkmcnt(" #n ")" ::: "memory")
; #define PG8_BAR __builtin_amdgcn_s_barrier()
; #define PG8_SCHED __builtin_amdgcn_sched_barrier(0)
; template <class Epi>
; __device__ __forceinline__ void gemm_phase(LAS unsigned char* lds, const Gemm g, const Sched& S, const Epi& E) {
;     ...
;             PG8_WAIT_V(8); PG8_WAIT_L(0); PG8_BAR; PG8_MMA(1, 0, At, B0); PG8_MMA(1, 1, At, B1); PG8_BAR; PG8_SCHED;
;         }
;         if (wr == 0) PG8_BAR;
;     __device__ __forceinline__ void operator()(AccRef acc, const Unit& u, int wr, int wc, int fr, int fq) const {
;     ...
;         if (pn >= 17 && pn < 25) {
.Lp4_padskip_3:
	s_add_i32 s57, s57, 2
	s_add_u32 s2, s2, 0x100
	s_addc_u32 s3, s3, 0
	s_add_u32 s55, s55, 0x100
	s_addc_u32 s56, s56, 0
	s_cmp_gt_u32 s57, 13
	s_barrier
	s_cbranch_scc0 .LBB0_520
	s_and_b64 vcc, exec, s[20:21]
	s_cbranch_vccnz .LBB0_525
	s_sub_i32 s0, s44, 17
	s_cmp_gt_u32 s0, 7
	s_mov_b64 s[2:3], -1
	s_cbranch_scc1 .LBB0_526

; #define PG8_STAGE(bufoff, gbase, voff) do { _Pragma("unroll") for (int _i = 0; _i < 2; ++_i) \
;         __builtin_amdgcn_global_load_lds((const unsigned*)((const char*)(gbase) + (voff)[_i]), (LAS unsigned*)(lds + (bufoff) + ldsw + _i * 8192), 16, 0, 0); } while (0)
; #define PG8_LDA(dst, b, h) do { _Pragma("unroll") for (int m = 0; m < 4; ++m) _Pragma("unroll") for (int k = 0; k < 2; ++k) dst[m][k] = *(const LAS bf16x8*)(lds + PG8_SA(b, h) + aoff + m * 2048 + k * 1024); } while (0)
; #define PG8_LDB(dst, b, h) do { _Pragma("unroll") for (int n = 0; n < 2; ++n) _Pragma("unroll") for (int k = 0; k < 2; ++k) dst[n][k] = *(const LAS bf16x8*)(lds + PG8_SB(b, h) + boff + n * 2048 + k * 1024); } while (0)
; #define PG8_MMA(ai, bj, At, Bt) do { __builtin_amdgcn_s_setprio(1); _Pragma("unroll") for (int m = 0; m < 4; ++m) _Pragma("unroll") for (int n = 0; n < 2; ++n) _Pragma("unroll") for (int k = 0; k < 2; ++k) \
;         acc[ai][bj][m][n] = __builtin_amdgcn_mfma_f32_16x16x32_bf16(Bt[n][k], At[m][k], acc[ai][bj][m][n], 0, 0, 0); __builtin_amdgcn_s_setprio(0); } while (0)
; #define PG8_BAR __builtin_amdgcn_s_barrier()
; template <class Epi>
; __device__ __forceinline__ void gemm_phase(LAS unsigned char* lds, const Gemm g, const Sched& S, const Epi& E) {
;     ...
;         const bool has_next = S.next(ui + 1, nxt);
;         const char* nA = has_next ? (const char*)g.A + (size_t)S.aoff(nxt) * 2 : cA; const char* nB = has_next ? (const char*)g.Bt + (size_t)S.boff(nxt) * 2 : cB;
;         _Pragma("nounroll")
;         for (int t = 0; t < nt; t += 2) {
;             const bool last = (t == nt - 2);
;             const char* a1 = cA + (size_t)(t + 1) * kstep;
;             const char* a2 = last ? nA : cA + (size_t)(t + 2) * kstep; const char* b2 = last ? nB : cB + (size_t)(t + 2) * kstep;
;             const char* a3 = a2 + kstep; const char* b3 = b2 + kstep;
;             PG8_LDB(B0, 0, 0); PG8_LDB(B1, 0, 1); PG8_SCHED; PG8_LDA(At, 0, 0); PG8_STAGE(PG8_SA(1, 1), a1 + hstepA, voffA);
;             PG8_WAIT_V(8); PG8_WAIT_L(0); PG8_BAR; PG8_MMA(0, 0, At, B0); PG8_MMA(0, 1, At, B1); PG8_BAR; PG8_SCHED;
;             PG8_LDA(At, 0, 1); PG8_STAGE(PG8_SB(0, 0), b2, voffB); PG8_STAGE(PG8_SB(0, 1), b2 + hstepB, voffB); PG8_STAGE(PG8_SA(0, 0), a2, voffA);
;             PG8_WAIT_V(8); PG8_WAIT_L(0); PG8_BAR; PG8_MMA(1, 0, At, B0); PG8_MMA(1, 1, At, B1); PG8_BAR; PG8_SCHED;
.LBB0_773:
	s_add_u32 s60, s46, s74
	s_addc_u32 s61, s47, s75
	s_add_u32 s62, s60, 0x100
	s_addc_u32 s63, s61, 0
	s_and_b64 s[58:59], s[56:57], exec
	s_cselect_b32 s77, s3, s63
	s_cselect_b32 s76, s5, s62
	s_add_u32 s58, s52, s74
	s_addc_u32 s59, s53, s75
	s_add_u32 s58, s58, 0x100
	s_addc_u32 s59, s59, 0
	s_and_b64 s[56:57], s[56:57], exec
	s_cselect_b32 s79, s25, s59
	s_cselect_b32 s78, s27, s58
	s_add_u32 s86, s60, 0x10080
	ds_read_b128 v[80:83], v162
	ds_read_b128 v[84:87], v162 offset:1024
	ds_read_b128 v[136:139], v162 offset:2048
	ds_read_b128 v[140:143], v162 offset:3072
	ds_read_b128 v[154:157], v163
	ds_read_b128 v[166:169], v163 offset:1024
	ds_read_b128 v[170:173], v163 offset:2048
	ds_read_b128 v[174:177], v163 offset:3072
	s_addc_u32 s87, s61, 0
	s_add_i32 s67, s96, s15
	s_add_i32 s64, s67, 0x2000
	s_add_u32 s82, s78, 0x10000
	s_addc_u32 s83, s79, 0
	s_add_i32 s66, s97, s15
	s_add_i32 s65, s66, 0x2000
	s_add_i32 s63, 0, 0x18000
	s_add_i32 s62, 0, 0x1c000
	s_add_u32 s74, s76, 0x10000
	s_addc_u32 s75, s77, 0
	s_add_i32 s61, s63, s15
	s_add_i32 s59, s61, 0x2000
	s_add_u32 s56, s78, 0x10080
	s_addc_u32 s57, s79, 0
	s_add_i32 s60, s62, s15
	s_add_i32 s58, s60, 0x2000
	s_mov_b32 m0, s88
	v_lshl_add_u64 v[212:213], s[86:87], 0, v[144:145]
	ds_read_b128 v[178:181], v164
	ds_read_b128 v[182:185], v164 offset:1024
	ds_read_b128 v[186:189], v164 offset:2048
	ds_read_b128 v[190:193], v164 offset:3072
	ds_read_b128 v[194:197], v164 offset:4096
	ds_read_b128 v[198:201], v164 offset:5120
	ds_read_b128 v[204:207], v164 offset:6144
	ds_read_b128 v[208:211], v164 offset:7168
	global_load_lds_dwordx4 v[212:213], off
	v_lshl_add_u64 v[212:213], s[86:87], 0, v[148:149]
	s_mov_b32 m0, s11
	s_nop 0
	global_load_lds_dwordx4 v[212:213], off
	s_waitcnt vmcnt(8)
	s_waitcnt lgkmcnt(0)
	s_barrier
	s_waitcnt lgkmcnt(0)
	v_mfma_f32_16x16x32_bf16 v[132:135], v[80:83], v[178:181], v[132:135]
	v_mfma_f32_16x16x32_bf16 v[128:131], v[136:139], v[178:181], v[128:131]
	v_mfma_f32_16x16x32_bf16 v[124:127], v[80:83], v[186:189], v[124:127]
	v_mfma_f32_16x16x32_bf16 v[120:123], v[136:139], v[186:189], v[120:123]
	v_mfma_f32_16x16x32_bf16 v[116:119], v[80:83], v[194:197], v[116:119]
	v_mfma_f32_16x16x32_bf16 v[112:115], v[136:139], v[194:197], v[112:115]
	v_mfma_f32_16x16x32_bf16 v[108:111], v[80:83], v[204:207], v[108:111]
	v_mfma_f32_16x16x32_bf16 v[104:107], v[136:139], v[204:207], v[104:107]
	v_mfma_f32_16x16x32_bf16 v[132:135], v[84:87], v[182:185], v[132:135]
	v_mfma_f32_16x16x32_bf16 v[128:131], v[140:143], v[182:185], v[128:131]
	v_mfma_f32_16x16x32_bf16 v[124:127], v[84:87], v[190:193], v[124:127]
	v_mfma_f32_16x16x32_bf16 v[120:123], v[140:143], v[190:193], v[120:123]
	v_mfma_f32_16x16x32_bf16 v[116:119], v[84:87], v[198:201], v[116:119]
	v_mfma_f32_16x16x32_bf16 v[112:115], v[140:143], v[198:201], v[112:115]
	v_mfma_f32_16x16x32_bf16 v[108:111], v[84:87], v[208:211], v[108:111]
	v_mfma_f32_16x16x32_bf16 v[104:107], v[140:143], v[208:211], v[104:107]
	v_mfma_f32_16x16x32_bf16 v[60:63], v[154:157], v[178:181], v[60:63]
	v_mfma_f32_16x16x32_bf16 v[56:59], v[170:173], v[178:181], v[56:59]
	v_mfma_f32_16x16x32_bf16 v[52:55], v[154:157], v[186:189], v[52:55]
	v_mfma_f32_16x16x32_bf16 v[48:51], v[170:173], v[186:189], v[48:51]
	v_mfma_f32_16x16x32_bf16 v[44:47], v[154:157], v[194:197], v[44:47]
	v_mfma_f32_16x16x32_bf16 v[40:43], v[170:173], v[194:197], v[40:43]
	v_mfma_f32_16x16x32_bf16 v[36:39], v[154:157], v[204:207], v[36:39]
	v_mfma_f32_16x16x32_bf16 v[32:35], v[170:173], v[204:207], v[32:35]
	v_mfma_f32_16x16x32_bf16 v[60:63], v[166:169], v[182:185], v[60:63]
	v_mfma_f32_16x16x32_bf16 v[56:59], v[174:177], v[182:185], v[56:59]
	v_mfma_f32_16x16x32_bf16 v[52:55], v[166:169], v[190:193], v[52:55]
	v_mfma_f32_16x16x32_bf16 v[48:51], v[174:177], v[190:193], v[48:51]
	v_mfma_f32_16x16x32_bf16 v[44:47], v[166:169], v[198:201], v[44:47]
	v_mfma_f32_16x16x32_bf16 v[40:43], v[174:177], v[198:201], v[40:43]
	v_mfma_f32_16x16x32_bf16 v[36:39], v[166:169], v[208:211], v[36:39]
	v_mfma_f32_16x16x32_bf16 v[32:35], v[174:177], v[208:211], v[32:35]
	s_barrier
	s_mov_b32 m0, s67
	v_lshl_add_u64 v[212:213], s[78:79], 0, v[146:147]
	ds_read_b128 v[178:181], v164 offset:16384
	ds_read_b128 v[182:185], v164 offset:17408
	ds_read_b128 v[186:189], v164 offset:18432
	ds_read_b128 v[190:193], v164 offset:19456
	ds_read_b128 v[194:197], v164 offset:20480
	ds_read_b128 v[198:201], v164 offset:21504
	ds_read_b128 v[204:207], v164 offset:22528
	ds_read_b128 v[208:211], v164 offset:23552
	global_load_lds_dwordx4 v[212:213], off
	v_lshl_add_u64 v[214:215], s[78:79], 0, v[150:151]
	s_mov_b32 m0, s64
	v_lshl_add_u64 v[216:217], s[82:83], 0, v[146:147]
	global_load_lds_dwordx4 v[214:215], off
	s_mov_b32 m0, s66
	v_lshl_add_u64 v[218:219], s[76:77], 0, v[148:149]
	global_load_lds_dwordx4 v[216:217], off
	v_lshl_add_u64 v[216:217], s[82:83], 0, v[150:151]
	s_mov_b32 m0, s65
	s_nop 0
	global_load_lds_dwordx4 v[216:217], off
	v_lshl_add_u64 v[216:217], s[76:77], 0, v[144:145]
	s_mov_b32 m0, s10
	s_nop 0
	global_load_lds_dwordx4 v[216:217], off
	s_mov_b32 m0, s89
	s_nop 0
	global_load_lds_dwordx4 v[218:219], off
	s_waitcnt vmcnt(8)
	s_waitcnt lgkmcnt(0)
	s_barrier
; #define PG8_STAGE(bufoff, gbase, voff) do { _Pragma("unroll") for (int _i = 0; _i < 2; ++_i) \
;         __builtin_amdgcn_global_load_lds((const unsigned*)((const char*)(gbase) + (voff)[_i]), (LAS unsigned*)(lds + (bufoff) + ldsw + _i * 8192), 16, 0, 0); } while (0)
; #define PG8_LDA(dst, b, h) do { _Pragma("unroll") for (int m = 0; m < 4; ++m) _Pragma("unroll") for (int k = 0; k < 2; ++k) dst[m][k] = *(const LAS bf16x8*)(lds + PG8_SA(b, h) + aoff + m * 2048 + k * 1024); } while (0)
; #define PG8_LDB(dst, b, h) do { _Pragma("unroll") for (int n = 0; n < 2; ++n) _Pragma("unroll") for (int k = 0; k < 2; ++k) dst[n][k] = *(const LAS bf16x8*)(lds + PG8_SB(b, h) + boff + n * 2048 + k * 1024); } while (0)
; #define PG8_MMA(ai, bj, At, Bt) do { __builtin_amdgcn_s_setprio(1); _Pragma("unroll") for (int m = 0; m < 4; ++m) _Pragma("unroll") for (int n = 0; n < 2; ++n) _Pragma("unroll") for (int k = 0; k < 2; ++k) \
;         acc[ai][bj][m][n] = __builtin_amdgcn_mfma_f32_16x16x32_bf16(Bt[n][k], At[m][k], acc[ai][bj][m][n], 0, 0, 0); __builtin_amdgcn_s_setprio(0); } while (0)
; #define PG8_WAIT_V(n) asm volatile("s_waitcnt vmcnt(" #n ")" ::: "memory")
; #define PG8_WAIT_L(n) asm volatile("s_waitcnt lgkmcnt(" #n ")" ::: "memory")
; #define PG8_BAR __builtin_amdgcn_s_barrier()
; #define PG8_SCHED __builtin_amdgcn_sched_barrier(0)
; template <class Epi>
; __device__ __forceinline__ void gemm_phase(LAS unsigned char* lds, const Gemm g, const Sched& S, const Epi& E) {
;     ...
;             PG8_WAIT_V(8); PG8_WAIT_L(0); PG8_BAR; PG8_MMA(1, 0, At, B0); PG8_MMA(1, 1, At, B1); PG8_BAR; PG8_SCHED;
;             PG8_LDB(B0, 1, 0); PG8_LDB(B1, 1, 1); PG8_SCHED; PG8_LDA(At, 1, 0); PG8_STAGE(PG8_SA(0, 1), a2 + hstepA, voffA);
;             PG8_WAIT_V(8); PG8_WAIT_L(0); PG8_BAR; PG8_MMA(0, 0, At, B0); PG8_MMA(0, 1, At, B1); PG8_BAR; PG8_SCHED;
	s_waitcnt lgkmcnt(0)
	v_mfma_f32_16x16x32_bf16 v[100:103], v[80:83], v[178:181], v[100:103]
	v_mfma_f32_16x16x32_bf16 v[96:99], v[136:139], v[178:181], v[96:99]
	v_mfma_f32_16x16x32_bf16 v[92:95], v[80:83], v[186:189], v[92:95]
	v_mfma_f32_16x16x32_bf16 v[88:91], v[136:139], v[186:189], v[88:91]
	v_mfma_f32_16x16x32_bf16 v[76:79], v[80:83], v[194:197], v[76:79]
	v_mfma_f32_16x16x32_bf16 v[72:75], v[136:139], v[194:197], v[72:75]
	v_mfma_f32_16x16x32_bf16 v[68:71], v[80:83], v[204:207], v[68:71]
	v_mfma_f32_16x16x32_bf16 v[64:67], v[136:139], v[204:207], v[64:67]
	v_mfma_f32_16x16x32_bf16 v[100:103], v[84:87], v[182:185], v[100:103]
	v_mfma_f32_16x16x32_bf16 v[96:99], v[140:143], v[182:185], v[96:99]
	v_mfma_f32_16x16x32_bf16 v[92:95], v[84:87], v[190:193], v[92:95]
	v_mfma_f32_16x16x32_bf16 v[88:91], v[140:143], v[190:193], v[88:91]
	v_mfma_f32_16x16x32_bf16 v[76:79], v[84:87], v[198:201], v[76:79]
	v_mfma_f32_16x16x32_bf16 v[72:75], v[140:143], v[198:201], v[72:75]
	v_mfma_f32_16x16x32_bf16 v[68:71], v[84:87], v[208:211], v[68:71]
	v_mfma_f32_16x16x32_bf16 v[64:67], v[140:143], v[208:211], v[64:67]
	v_mfma_f32_16x16x32_bf16 v[28:31], v[154:157], v[178:181], v[28:31]
	v_mfma_f32_16x16x32_bf16 v[24:27], v[170:173], v[178:181], v[24:27]
	v_mfma_f32_16x16x32_bf16 v[20:23], v[154:157], v[186:189], v[20:23]
	v_mfma_f32_16x16x32_bf16 v[16:19], v[170:173], v[186:189], v[16:19]
	v_mfma_f32_16x16x32_bf16 v[12:15], v[154:157], v[194:197], v[12:15]
	v_mfma_f32_16x16x32_bf16 v[8:11], v[170:173], v[194:197], v[8:11]
	v_mfma_f32_16x16x32_bf16 v[4:7], v[154:157], v[204:207], v[4:7]
	v_mfma_f32_16x16x32_bf16 v[0:3], v[170:173], v[204:207], v[0:3]
	v_mfma_f32_16x16x32_bf16 v[28:31], v[166:169], v[182:185], v[28:31]
	v_mfma_f32_16x16x32_bf16 v[24:27], v[174:177], v[182:185], v[24:27]
	v_mfma_f32_16x16x32_bf16 v[20:23], v[166:169], v[190:193], v[20:23]
	v_mfma_f32_16x16x32_bf16 v[16:19], v[174:177], v[190:193], v[16:19]
	v_mfma_f32_16x16x32_bf16 v[12:15], v[166:169], v[198:201], v[12:15]
	v_mfma_f32_16x16x32_bf16 v[8:11], v[174:177], v[198:201], v[8:11]
	v_mfma_f32_16x16x32_bf16 v[4:7], v[166:169], v[208:211], v[4:7]
	v_mfma_f32_16x16x32_bf16 v[0:3], v[174:177], v[208:211], v[0:3]
	s_barrier
	v_add_u32_e32 v140, s63, v160
	v_add_u32_e32 v152, s62, v160
	ds_read_b128 v[80:83], v140
	ds_read_b128 v[84:87], v140 offset:1024
	ds_read_b128 v[136:139], v140 offset:2048
	ds_read_b128 v[140:143], v140 offset:3072
	ds_read_b128 v[154:157], v152
	ds_read_b128 v[166:169], v152 offset:1024
	ds_read_b128 v[170:173], v152 offset:2048
	ds_read_b128 v[174:177], v152 offset:3072
	s_mov_b32 m0, s90
	v_lshl_add_u64 v[220:221], s[74:75], 0, v[144:145]
	ds_read_b128 v[178:181], v164 offset:32768
	ds_read_b128 v[182:185], v164 offset:33792
	ds_read_b128 v[186:189], v164 offset:34816
	ds_read_b128 v[190:193], v164 offset:35840
	ds_read_b128 v[194:197], v164 offset:36864
	ds_read_b128 v[198:201], v164 offset:37888
	ds_read_b128 v[204:207], v164 offset:38912
	ds_read_b128 v[208:211], v164 offset:39936
	global_load_lds_dwordx4 v[220:221], off
	v_lshl_add_u64 v[220:221], s[74:75], 0, v[148:149]
	s_mov_b32 m0, s91
	s_nop 0
	global_load_lds_dwordx4 v[220:221], off
	s_waitcnt vmcnt(8)
	s_waitcnt lgkmcnt(0)
	s_barrier
	s_waitcnt lgkmcnt(0)
	v_mfma_f32_16x16x32_bf16 v[132:135], v[80:83], v[178:181], v[132:135]
	v_mfma_f32_16x16x32_bf16 v[128:131], v[136:139], v[178:181], v[128:131]
	v_mfma_f32_16x16x32_bf16 v[124:127], v[80:83], v[186:189], v[124:127]
	v_mfma_f32_16x16x32_bf16 v[120:123], v[136:139], v[186:189], v[120:123]
	v_mfma_f32_16x16x32_bf16 v[116:119], v[80:83], v[194:197], v[116:119]
	v_mfma_f32_16x16x32_bf16 v[112:115], v[136:139], v[194:197], v[112:115]
	v_mfma_f32_16x16x32_bf16 v[108:111], v[80:83], v[204:207], v[108:111]
	v_mfma_f32_16x16x32_bf16 v[104:107], v[136:139], v[204:207], v[104:107]
	v_mfma_f32_16x16x32_bf16 v[132:135], v[84:87], v[182:185], v[132:135]
	v_mfma_f32_16x16x32_bf16 v[128:131], v[140:143], v[182:185], v[128:131]
	v_mfma_f32_16x16x32_bf16 v[124:127], v[84:87], v[190:193], v[124:127]
	v_mfma_f32_16x16x32_bf16 v[120:123], v[140:143], v[190:193], v[120:123]
	v_mfma_f32_16x16x32_bf16 v[116:119], v[84:87], v[198:201], v[116:119]
	v_mfma_f32_16x16x32_bf16 v[112:115], v[140:143], v[198:201], v[112:115]
	v_mfma_f32_16x16x32_bf16 v[108:111], v[84:87], v[208:211], v[108:111]
	v_mfma_f32_16x16x32_bf16 v[104:107], v[140:143], v[208:211], v[104:107]
	v_mfma_f32_16x16x32_bf16 v[60:63], v[154:157], v[178:181], v[60:63]
	v_mfma_f32_16x16x32_bf16 v[56:59], v[170:173], v[178:181], v[56:59]
	v_mfma_f32_16x16x32_bf16 v[52:55], v[154:157], v[186:189], v[52:55]
	v_mfma_f32_16x16x32_bf16 v[48:51], v[170:173], v[186:189], v[48:51]
	v_mfma_f32_16x16x32_bf16 v[44:47], v[154:157], v[194:197], v[44:47]
	v_mfma_f32_16x16x32_bf16 v[40:43], v[170:173], v[194:197], v[40:43]
	v_mfma_f32_16x16x32_bf16 v[36:39], v[154:157], v[204:207], v[36:39]
	v_mfma_f32_16x16x32_bf16 v[32:35], v[170:173], v[204:207], v[32:35]
	v_mfma_f32_16x16x32_bf16 v[60:63], v[166:169], v[182:185], v[60:63]
	v_mfma_f32_16x16x32_bf16 v[56:59], v[174:177], v[182:185], v[56:59]
	v_mfma_f32_16x16x32_bf16 v[52:55], v[166:169], v[190:193], v[52:55]
	v_mfma_f32_16x16x32_bf16 v[48:51], v[174:177], v[190:193], v[48:51]
	v_mfma_f32_16x16x32_bf16 v[44:47], v[166:169], v[198:201], v[44:47]
	v_mfma_f32_16x16x32_bf16 v[40:43], v[174:177], v[198:201], v[40:43]
	v_mfma_f32_16x16x32_bf16 v[36:39], v[166:169], v[208:211], v[36:39]
	v_mfma_f32_16x16x32_bf16 v[32:35], v[174:177], v[208:211], v[32:35]
	s_barrier
; #define PG8_STAGE(bufoff, gbase, voff) do { _Pragma("unroll") for (int _i = 0; _i < 2; ++_i) \
;         __builtin_amdgcn_global_load_lds((const unsigned*)((const char*)(gbase) + (voff)[_i]), (LAS unsigned*)(lds + (bufoff) + ldsw + _i * 8192), 16, 0, 0); } while (0)
; #define PG8_LDA(dst, b, h) do { _Pragma("unroll") for (int m = 0; m < 4; ++m) _Pragma("unroll") for (int k = 0; k < 2; ++k) dst[m][k] = *(const LAS bf16x8*)(lds + PG8_SA(b, h) + aoff + m * 2048 + k * 1024); } while (0)
; #define PG8_MMA(ai, bj, At, Bt) do { __builtin_amdgcn_s_setprio(1); _Pragma("unroll") for (int m = 0; m < 4; ++m) _Pragma("unroll") for (int n = 0; n < 2; ++n) _Pragma("unroll") for (int k = 0; k < 2; ++k) \
;         acc[ai][bj][m][n] = __builtin_amdgcn_mfma_f32_16x16x32_bf16(Bt[n][k], At[m][k], acc[ai][bj][m][n], 0, 0, 0); __builtin_amdgcn_s_setprio(0); } while (0)
; #define PG8_WAIT_V(n) asm volatile("s_waitcnt vmcnt(" #n ")" ::: "memory")
; #define PG8_WAIT_L(n) asm volatile("s_waitcnt lgkmcnt(" #n ")" ::: "memory")
; #define PG8_BAR __builtin_amdgcn_s_barrier()
; #define PG8_SCHED __builtin_amdgcn_sched_barrier(0)
; template <class Epi>
; __device__ __forceinline__ void gemm_phase(LAS unsigned char* lds, const Gemm g, const Sched& S, const Epi& E) {
;     ...
;             PG8_LDA(At, 1, 1); PG8_STAGE(PG8_SB(1, 0), b3, voffB); PG8_STAGE(PG8_SB(1, 1), b3 + hstepB, voffB); PG8_STAGE(PG8_SA(1, 0), a3, voffA);
;             PG8_WAIT_V(8); PG8_WAIT_L(0); PG8_BAR; PG8_MMA(1, 0, At, B0); PG8_MMA(1, 1, At, B1); PG8_BAR; PG8_SCHED;
;         }
;         if (wr == 0) PG8_BAR;
	s_mov_b32 m0, s61
	v_lshl_add_u64 v[212:213], v[212:213], 0, s[6:7]
	ds_read_b128 v[178:181], v164 offset:49152
	ds_read_b128 v[182:185], v164 offset:50176
	ds_read_b128 v[186:189], v164 offset:51200
	ds_read_b128 v[190:193], v164 offset:52224
	ds_read_b128 v[194:197], v164 offset:53248
	ds_read_b128 v[198:201], v164 offset:54272
	ds_read_b128 v[204:207], v164 offset:55296
	ds_read_b128 v[208:211], v164 offset:56320
	global_load_lds_dwordx4 v[212:213], off
	v_lshl_add_u64 v[212:213], v[214:215], 0, s[6:7]
	s_mov_b32 m0, s59
	s_nop 0
	global_load_lds_dwordx4 v[212:213], off
	v_lshl_add_u64 v[212:213], s[56:57], 0, v[146:147]
	s_mov_b32 m0, s60
	s_nop 0
	global_load_lds_dwordx4 v[212:213], off
	v_lshl_add_u64 v[212:213], s[56:57], 0, v[150:151]
	s_mov_b32 m0, s58
	s_nop 0
	global_load_lds_dwordx4 v[212:213], off
	v_lshl_add_u64 v[212:213], v[216:217], 0, s[6:7]
	s_mov_b32 m0, s94
	s_nop 0
	global_load_lds_dwordx4 v[212:213], off
	v_lshl_add_u64 v[212:213], v[218:219], 0, s[6:7]
	s_mov_b32 m0, s95
	s_nop 0
	global_load_lds_dwordx4 v[212:213], off
	s_waitcnt vmcnt(8)
	s_waitcnt lgkmcnt(0)
	s_barrier
	s_waitcnt lgkmcnt(0)
	v_mfma_f32_16x16x32_bf16 v[100:103], v[80:83], v[178:181], v[100:103]
	v_mfma_f32_16x16x32_bf16 v[96:99], v[136:139], v[178:181], v[96:99]
	v_mfma_f32_16x16x32_bf16 v[92:95], v[80:83], v[186:189], v[92:95]
	v_mfma_f32_16x16x32_bf16 v[88:91], v[136:139], v[186:189], v[88:91]
	v_mfma_f32_16x16x32_bf16 v[76:79], v[80:83], v[194:197], v[76:79]
	v_mfma_f32_16x16x32_bf16 v[72:75], v[136:139], v[194:197], v[72:75]
	v_mfma_f32_16x16x32_bf16 v[68:71], v[80:83], v[204:207], v[68:71]
	v_mfma_f32_16x16x32_bf16 v[64:67], v[136:139], v[204:207], v[64:67]
	v_mfma_f32_16x16x32_bf16 v[100:103], v[84:87], v[182:185], v[100:103]
	v_mfma_f32_16x16x32_bf16 v[96:99], v[140:143], v[182:185], v[96:99]
	v_mfma_f32_16x16x32_bf16 v[92:95], v[84:87], v[190:193], v[92:95]
	v_mfma_f32_16x16x32_bf16 v[88:91], v[140:143], v[190:193], v[88:91]
	v_mfma_f32_16x16x32_bf16 v[76:79], v[84:87], v[198:201], v[76:79]
	v_mfma_f32_16x16x32_bf16 v[72:75], v[140:143], v[198:201], v[72:75]
	v_mfma_f32_16x16x32_bf16 v[68:71], v[84:87], v[208:211], v[68:71]
	v_mfma_f32_16x16x32_bf16 v[64:67], v[140:143], v[208:211], v[64:67]
	v_mfma_f32_16x16x32_bf16 v[28:31], v[154:157], v[178:181], v[28:31]
	v_mfma_f32_16x16x32_bf16 v[24:27], v[170:173], v[178:181], v[24:27]
	v_mfma_f32_16x16x32_bf16 v[20:23], v[154:157], v[186:189], v[20:23]
	v_mfma_f32_16x16x32_bf16 v[16:19], v[170:173], v[186:189], v[16:19]
	v_mfma_f32_16x16x32_bf16 v[12:15], v[154:157], v[194:197], v[12:15]
	v_mfma_f32_16x16x32_bf16 v[8:11], v[170:173], v[194:197], v[8:11]
	v_mfma_f32_16x16x32_bf16 v[4:7], v[154:157], v[204:207], v[4:7]
	v_mfma_f32_16x16x32_bf16 v[0:3], v[170:173], v[204:207], v[0:3]
	v_mfma_f32_16x16x32_bf16 v[28:31], v[166:169], v[182:185], v[28:31]
	v_mfma_f32_16x16x32_bf16 v[24:27], v[174:177], v[182:185], v[24:27]
	v_mfma_f32_16x16x32_bf16 v[20:23], v[166:169], v[190:193], v[20:23]
	v_mfma_f32_16x16x32_bf16 v[16:19], v[174:177], v[190:193], v[16:19]
	v_mfma_f32_16x16x32_bf16 v[12:15], v[166:169], v[198:201], v[12:15]
	v_mfma_f32_16x16x32_bf16 v[8:11], v[174:177], v[198:201], v[8:11]
	v_mfma_f32_16x16x32_bf16 v[4:7], v[166:169], v[208:211], v[4:7]
	v_mfma_f32_16x16x32_bf16 v[0:3], v[174:177], v[208:211], v[0:3]
	s_andn2_b64 vcc, exec, s[54:55]
	s_mov_b64 s[56:57], -1
	s_mov_b64 s[54:55], 0
	s_mov_b64 s[74:75], 0x100
	s_barrier
	s_cbranch_vccz .LBB0_773
	s_and_b64 vcc, exec, s[8:9]
	s_cbranch_vccz .LBB0_776
	s_barrier

; #define PG8_STAGE(bufoff, gbase, voff) do { _Pragma("unroll") for (int _i = 0; _i < 2; ++_i) \
;         __builtin_amdgcn_global_load_lds((const unsigned*)((const char*)(gbase) + (voff)[_i]), (LAS unsigned*)(lds + (bufoff) + ldsw + _i * 8192), 16, 0, 0); } while (0)
; #define PG8_LDA(dst, b, h) do { _Pragma("unroll") for (int m = 0; m < 4; ++m) _Pragma("unroll") for (int k = 0; k < 2; ++k) dst[m][k] = *(const LAS bf16x8*)(lds + PG8_SA(b, h) + aoff + m * 2048 + k * 1024); } while (0)
; #define PG8_LDB(dst, b, h) do { _Pragma("unroll") for (int n = 0; n < 2; ++n) _Pragma("unroll") for (int k = 0; k < 2; ++k) dst[n][k] = *(const LAS bf16x8*)(lds + PG8_SB(b, h) + boff + n * 2048 + k * 1024); } while (0)
; #define PG8_MMA(ai, bj, At, Bt) do { __builtin_amdgcn_s_setprio(1); _Pragma("unroll") for (int m = 0; m < 4; ++m) _Pragma("unroll") for (int n = 0; n < 2; ++n) _Pragma("unroll") for (int k = 0; k < 2; ++k) \
;         acc[ai][bj][m][n] = __builtin_amdgcn_mfma_f32_16x16x32_bf16(Bt[n][k], At[m][k], acc[ai][bj][m][n], 0, 0, 0); __builtin_amdgcn_s_setprio(0); } while (0)
; #define PG8_BAR __builtin_amdgcn_s_barrier()
; template <class Epi>
; __device__ __forceinline__ void gemm_phase(LAS unsigned char* lds, const Gemm g, const Sched& S, const Epi& E) {
;     ...
;         const bool has_next = S.next(ui + 1, nxt);
;         const char* nA = has_next ? (const char*)g.A + (size_t)S.aoff(nxt) * 2 : cA; const char* nB = has_next ? (const char*)g.Bt + (size_t)S.boff(nxt) * 2 : cB;
;         _Pragma("nounroll")
;         for (int t = 0; t < nt; t += 2) {
;             const bool last = (t == nt - 2);
;             const char* a1 = cA + (size_t)(t + 1) * kstep;
;             const char* a2 = last ? nA : cA + (size_t)(t + 2) * kstep; const char* b2 = last ? nB : cB + (size_t)(t + 2) * kstep;
;             const char* a3 = a2 + kstep; const char* b3 = b2 + kstep;
;             PG8_LDB(B0, 0, 0); PG8_LDB(B1, 0, 1); PG8_SCHED; PG8_LDA(At, 0, 0); PG8_STAGE(PG8_SA(1, 1), a1 + hstepA, voffA);
;             PG8_WAIT_V(8); PG8_WAIT_L(0); PG8_BAR; PG8_MMA(0, 0, At, B0); PG8_MMA(0, 1, At, B1); PG8_BAR; PG8_SCHED;
;             PG8_LDA(At, 0, 1); PG8_STAGE(PG8_SB(0, 0), b2, voffB); PG8_STAGE(PG8_SB(0, 1), b2 + hstepB, voffB); PG8_STAGE(PG8_SA(0, 0), a2, voffA);
;             PG8_WAIT_V(8); PG8_WAIT_L(0); PG8_BAR; PG8_MMA(1, 0, At, B0); PG8_MMA(1, 1, At, B1); PG8_BAR; PG8_SCHED;
.LBB0_900:
	s_add_u32 s57, s4, s78
	s_addc_u32 s64, s5, s79
	s_add_u32 s65, s57, 0x100
	s_addc_u32 s66, s64, 0
	s_and_b64 s[62:63], s[14:15], exec
	s_cselect_b32 s83, s75, s66
	s_cselect_b32 s82, s74, s65
	s_add_u32 s62, s6, s78
	s_addc_u32 s63, s7, s79
	s_add_u32 s62, s62, 0x100
	s_addc_u32 s63, s63, 0
	s_and_b64 s[14:15], s[14:15], exec
	s_cselect_b32 s87, s1, s63
	s_cselect_b32 s86, s55, s62
	s_add_u32 s90, s57, 0x40080
	ds_read_b128 v[96:99], v155
	ds_read_b128 v[100:103], v155 offset:1024
	ds_read_b128 v[144:147], v155 offset:2048
	ds_read_b128 v[148:151], v155 offset:3072
	ds_read_b128 v[160:163], v156
	ds_read_b128 v[164:167], v156 offset:1024
	ds_read_b128 v[168:171], v156 offset:2048
	ds_read_b128 v[172:175], v156 offset:3072
	s_addc_u32 s91, s64, 0
	s_add_i32 s67, s59, s10
	s_add_i32 m0, s11, 0xc000
	s_add_i32 s85, s11, 0xe000
	s_add_i32 s84, s67, 0x2000
	s_add_u32 s88, s86, 0x10000
	s_addc_u32 s89, s87, 0
	s_add_i32 vcc_hi, s60, s10
	s_add_i32 vcc_lo, vcc_hi, 0x2000
	s_add_i32 s66, 0, 0x18000
	s_add_i32 s65, 0, 0x1c000
	s_add_u32 s78, s82, 0x40000
	s_addc_u32 s79, s83, 0
	s_add_i32 s64, s66, s10
	s_add_i32 s62, s64, 0x2000
	s_add_u32 s14, s86, 0x10080
	s_addc_u32 s15, s87, 0
	s_add_i32 s63, s65, s10
	s_add_i32 s57, s63, 0x2000
	v_lshl_add_u64 v[200:201], s[90:91], 0, v[136:137]
	ds_read_b128 v[176:179], v157
	ds_read_b128 v[180:183], v157 offset:1024
	ds_read_b128 v[184:187], v157 offset:2048
	ds_read_b128 v[188:191], v157 offset:3072
	ds_read_b128 v[192:195], v157 offset:4096
	ds_read_b128 v[196:199], v157 offset:5120
	ds_read_b128 v[204:207], v157 offset:6144
	ds_read_b128 v[208:211], v157 offset:7168
	global_load_lds_dwordx4 v[200:201], off
	v_lshl_add_u64 v[200:201], s[90:91], 0, v[140:141]
	s_mov_b32 m0, s85
	s_nop 0
	global_load_lds_dwordx4 v[200:201], off
	s_waitcnt vmcnt(8)
	s_waitcnt lgkmcnt(0)
	s_barrier
	s_waitcnt lgkmcnt(0)
	v_mfma_f32_16x16x32_bf16 v[132:135], v[96:99], v[176:179], v[132:135]
	v_mfma_f32_16x16x32_bf16 v[128:131], v[144:147], v[176:179], v[128:131]
	v_mfma_f32_16x16x32_bf16 v[124:127], v[96:99], v[184:187], v[124:127]
	v_mfma_f32_16x16x32_bf16 v[120:123], v[144:147], v[184:187], v[120:123]
	v_mfma_f32_16x16x32_bf16 v[116:119], v[96:99], v[192:195], v[116:119]
	v_mfma_f32_16x16x32_bf16 v[112:115], v[144:147], v[192:195], v[112:115]
	v_mfma_f32_16x16x32_bf16 v[108:111], v[96:99], v[204:207], v[108:111]
	v_mfma_f32_16x16x32_bf16 v[104:107], v[144:147], v[204:207], v[104:107]
	v_mfma_f32_16x16x32_bf16 v[132:135], v[100:103], v[180:183], v[132:135]
	v_mfma_f32_16x16x32_bf16 v[128:131], v[148:151], v[180:183], v[128:131]
	v_mfma_f32_16x16x32_bf16 v[124:127], v[100:103], v[188:191], v[124:127]
	v_mfma_f32_16x16x32_bf16 v[120:123], v[148:151], v[188:191], v[120:123]
	v_mfma_f32_16x16x32_bf16 v[116:119], v[100:103], v[196:199], v[116:119]
	v_mfma_f32_16x16x32_bf16 v[112:115], v[148:151], v[196:199], v[112:115]
	v_mfma_f32_16x16x32_bf16 v[108:111], v[100:103], v[208:211], v[108:111]
	v_mfma_f32_16x16x32_bf16 v[104:107], v[148:151], v[208:211], v[104:107]
	v_mfma_f32_16x16x32_bf16 v[60:63], v[160:163], v[176:179], v[60:63]
	v_mfma_f32_16x16x32_bf16 v[56:59], v[168:171], v[176:179], v[56:59]
	v_mfma_f32_16x16x32_bf16 v[52:55], v[160:163], v[184:187], v[52:55]
	v_mfma_f32_16x16x32_bf16 v[48:51], v[168:171], v[184:187], v[48:51]
	v_mfma_f32_16x16x32_bf16 v[44:47], v[160:163], v[192:195], v[44:47]
	v_mfma_f32_16x16x32_bf16 v[40:43], v[168:171], v[192:195], v[40:43]
	v_mfma_f32_16x16x32_bf16 v[36:39], v[160:163], v[204:207], v[36:39]
	v_mfma_f32_16x16x32_bf16 v[32:35], v[168:171], v[204:207], v[32:35]
	v_mfma_f32_16x16x32_bf16 v[60:63], v[164:167], v[180:183], v[60:63]
	v_mfma_f32_16x16x32_bf16 v[56:59], v[172:175], v[180:183], v[56:59]
	v_mfma_f32_16x16x32_bf16 v[52:55], v[164:167], v[188:191], v[52:55]
	v_mfma_f32_16x16x32_bf16 v[48:51], v[172:175], v[188:191], v[48:51]
	v_mfma_f32_16x16x32_bf16 v[44:47], v[164:167], v[196:199], v[44:47]
	v_mfma_f32_16x16x32_bf16 v[40:43], v[172:175], v[196:199], v[40:43]
	v_mfma_f32_16x16x32_bf16 v[36:39], v[164:167], v[208:211], v[36:39]
	v_mfma_f32_16x16x32_bf16 v[32:35], v[172:175], v[208:211], v[32:35]
	s_barrier
	s_mov_b32 m0, s67
	v_lshl_add_u64 v[200:201], s[86:87], 0, v[138:139]
	ds_read_b128 v[176:179], v157 offset:16384
	ds_read_b128 v[180:183], v157 offset:17408
	ds_read_b128 v[184:187], v157 offset:18432
	ds_read_b128 v[188:191], v157 offset:19456
	ds_read_b128 v[192:195], v157 offset:20480
	ds_read_b128 v[196:199], v157 offset:21504
	ds_read_b128 v[204:207], v157 offset:22528
	ds_read_b128 v[208:211], v157 offset:23552
	global_load_lds_dwordx4 v[200:201], off
	v_lshl_add_u64 v[212:213], s[86:87], 0, v[142:143]
	s_mov_b32 m0, s84
	v_lshl_add_u64 v[214:215], s[88:89], 0, v[138:139]
	global_load_lds_dwordx4 v[212:213], off
	s_mov_b32 m0, vcc_hi
	v_lshl_add_u64 v[216:217], s[82:83], 0, v[140:141]
	global_load_lds_dwordx4 v[214:215], off
	v_lshl_add_u64 v[214:215], s[88:89], 0, v[142:143]
	s_mov_b32 m0, vcc_lo
	s_nop 0
	global_load_lds_dwordx4 v[214:215], off
	v_lshl_add_u64 v[214:215], s[82:83], 0, v[136:137]
	s_mov_b32 m0, s11
	s_nop 0
	global_load_lds_dwordx4 v[214:215], off
	s_mov_b32 m0, s93
	s_nop 0
	global_load_lds_dwordx4 v[216:217], off
	s_waitcnt vmcnt(8)
	s_waitcnt lgkmcnt(0)
	s_barrier
; #define PG8_STAGE(bufoff, gbase, voff) do { _Pragma("unroll") for (int _i = 0; _i < 2; ++_i) \
;         __builtin_amdgcn_global_load_lds((const unsigned*)((const char*)(gbase) + (voff)[_i]), (LAS unsigned*)(lds + (bufoff) + ldsw + _i * 8192), 16, 0, 0); } while (0)
; #define PG8_LDA(dst, b, h) do { _Pragma("unroll") for (int m = 0; m < 4; ++m) _Pragma("unroll") for (int k = 0; k < 2; ++k) dst[m][k] = *(const LAS bf16x8*)(lds + PG8_SA(b, h) + aoff + m * 2048 + k * 1024); } while (0)
; #define PG8_LDB(dst, b, h) do { _Pragma("unroll") for (int n = 0; n < 2; ++n) _Pragma("unroll") for (int k = 0; k < 2; ++k) dst[n][k] = *(const LAS bf16x8*)(lds + PG8_SB(b, h) + boff + n * 2048 + k * 1024); } while (0)
; #define PG8_MMA(ai, bj, At, Bt) do { __builtin_amdgcn_s_setprio(1); _Pragma("unroll") for (int m = 0; m < 4; ++m) _Pragma("unroll") for (int n = 0; n < 2; ++n) _Pragma("unroll") for (int k = 0; k < 2; ++k) \
;         acc[ai][bj][m][n] = __builtin_amdgcn_mfma_f32_16x16x32_bf16(Bt[n][k], At[m][k], acc[ai][bj][m][n], 0, 0, 0); __builtin_amdgcn_s_setprio(0); } while (0)
; #define PG8_WAIT_V(n) asm volatile("s_waitcnt vmcnt(" #n ")" ::: "memory")
; #define PG8_WAIT_L(n) asm volatile("s_waitcnt lgkmcnt(" #n ")" ::: "memory")
; #define PG8_BAR __builtin_amdgcn_s_barrier()
; #define PG8_SCHED __builtin_amdgcn_sched_barrier(0)
; template <class Epi>
; __device__ __forceinline__ void gemm_phase(LAS unsigned char* lds, const Gemm g, const Sched& S, const Epi& E) {
;     ...
;             PG8_WAIT_V(8); PG8_WAIT_L(0); PG8_BAR; PG8_MMA(1, 0, At, B0); PG8_MMA(1, 1, At, B1); PG8_BAR; PG8_SCHED;
;             PG8_LDB(B0, 1, 0); PG8_LDB(B1, 1, 1); PG8_SCHED; PG8_LDA(At, 1, 0); PG8_STAGE(PG8_SA(0, 1), a2 + hstepA, voffA);
;             PG8_WAIT_V(8); PG8_WAIT_L(0); PG8_BAR; PG8_MMA(0, 0, At, B0); PG8_MMA(0, 1, At, B1); PG8_BAR; PG8_SCHED;
	s_waitcnt lgkmcnt(0)
	v_mfma_f32_16x16x32_bf16 v[92:95], v[96:99], v[176:179], v[92:95]
	v_mfma_f32_16x16x32_bf16 v[88:91], v[144:147], v[176:179], v[88:91]
	v_mfma_f32_16x16x32_bf16 v[84:87], v[96:99], v[184:187], v[84:87]
	v_mfma_f32_16x16x32_bf16 v[80:83], v[144:147], v[184:187], v[80:83]
	v_mfma_f32_16x16x32_bf16 v[76:79], v[96:99], v[192:195], v[76:79]
	v_mfma_f32_16x16x32_bf16 v[72:75], v[144:147], v[192:195], v[72:75]
	v_mfma_f32_16x16x32_bf16 v[68:71], v[96:99], v[204:207], v[68:71]
	v_mfma_f32_16x16x32_bf16 v[64:67], v[144:147], v[204:207], v[64:67]
	v_mfma_f32_16x16x32_bf16 v[92:95], v[100:103], v[180:183], v[92:95]
	v_mfma_f32_16x16x32_bf16 v[88:91], v[148:151], v[180:183], v[88:91]
	v_mfma_f32_16x16x32_bf16 v[84:87], v[100:103], v[188:191], v[84:87]
	v_mfma_f32_16x16x32_bf16 v[80:83], v[148:151], v[188:191], v[80:83]
	v_mfma_f32_16x16x32_bf16 v[76:79], v[100:103], v[196:199], v[76:79]
	v_mfma_f32_16x16x32_bf16 v[72:75], v[148:151], v[196:199], v[72:75]
	v_mfma_f32_16x16x32_bf16 v[68:71], v[100:103], v[208:211], v[68:71]
	v_mfma_f32_16x16x32_bf16 v[64:67], v[148:151], v[208:211], v[64:67]
	v_mfma_f32_16x16x32_bf16 v[28:31], v[160:163], v[176:179], v[28:31]
	v_mfma_f32_16x16x32_bf16 v[24:27], v[168:171], v[176:179], v[24:27]
	v_mfma_f32_16x16x32_bf16 v[20:23], v[160:163], v[184:187], v[20:23]
	v_mfma_f32_16x16x32_bf16 v[16:19], v[168:171], v[184:187], v[16:19]
	v_mfma_f32_16x16x32_bf16 v[12:15], v[160:163], v[192:195], v[12:15]
	v_mfma_f32_16x16x32_bf16 v[8:11], v[168:171], v[192:195], v[8:11]
	v_mfma_f32_16x16x32_bf16 v[4:7], v[160:163], v[204:207], v[4:7]
	v_mfma_f32_16x16x32_bf16 v[0:3], v[168:171], v[204:207], v[0:3]
	v_mfma_f32_16x16x32_bf16 v[28:31], v[164:167], v[180:183], v[28:31]
	v_mfma_f32_16x16x32_bf16 v[24:27], v[172:175], v[180:183], v[24:27]
	v_mfma_f32_16x16x32_bf16 v[20:23], v[164:167], v[188:191], v[20:23]
	v_mfma_f32_16x16x32_bf16 v[16:19], v[172:175], v[188:191], v[16:19]
	v_mfma_f32_16x16x32_bf16 v[12:15], v[164:167], v[196:199], v[12:15]
	v_mfma_f32_16x16x32_bf16 v[8:11], v[172:175], v[196:199], v[8:11]
	v_mfma_f32_16x16x32_bf16 v[4:7], v[164:167], v[208:211], v[4:7]
	v_mfma_f32_16x16x32_bf16 v[0:3], v[172:175], v[208:211], v[0:3]
	s_barrier
	v_add_u32_e32 v148, s66, v153
	v_add_u32_e32 v159, s65, v153
	ds_read_b128 v[96:99], v148
	ds_read_b128 v[100:103], v148 offset:1024
	ds_read_b128 v[144:147], v148 offset:2048
	ds_read_b128 v[148:151], v148 offset:3072
	ds_read_b128 v[160:163], v159
	ds_read_b128 v[164:167], v159 offset:1024
	ds_read_b128 v[168:171], v159 offset:2048
	ds_read_b128 v[172:175], v159 offset:3072
	s_mov_b32 m0, s94
	v_lshl_add_u64 v[218:219], s[78:79], 0, v[136:137]
	ds_read_b128 v[176:179], v157 offset:32768
	ds_read_b128 v[180:183], v157 offset:33792
	ds_read_b128 v[184:187], v157 offset:34816
	ds_read_b128 v[188:191], v157 offset:35840
	ds_read_b128 v[192:195], v157 offset:36864
	ds_read_b128 v[196:199], v157 offset:37888
	ds_read_b128 v[204:207], v157 offset:38912
	ds_read_b128 v[208:211], v157 offset:39936
	global_load_lds_dwordx4 v[218:219], off
	v_lshl_add_u64 v[218:219], s[78:79], 0, v[140:141]
	s_mov_b32 m0, s95
	s_nop 0
	global_load_lds_dwordx4 v[218:219], off
	s_waitcnt vmcnt(8)
	s_waitcnt lgkmcnt(0)
	s_barrier
	s_waitcnt lgkmcnt(0)
	v_mfma_f32_16x16x32_bf16 v[132:135], v[96:99], v[176:179], v[132:135]
	v_mfma_f32_16x16x32_bf16 v[128:131], v[144:147], v[176:179], v[128:131]
	v_mfma_f32_16x16x32_bf16 v[124:127], v[96:99], v[184:187], v[124:127]
	v_mfma_f32_16x16x32_bf16 v[120:123], v[144:147], v[184:187], v[120:123]
	v_mfma_f32_16x16x32_bf16 v[116:119], v[96:99], v[192:195], v[116:119]
	v_mfma_f32_16x16x32_bf16 v[112:115], v[144:147], v[192:195], v[112:115]
	v_mfma_f32_16x16x32_bf16 v[108:111], v[96:99], v[204:207], v[108:111]
	v_mfma_f32_16x16x32_bf16 v[104:107], v[144:147], v[204:207], v[104:107]
	v_mfma_f32_16x16x32_bf16 v[132:135], v[100:103], v[180:183], v[132:135]
	v_mfma_f32_16x16x32_bf16 v[128:131], v[148:151], v[180:183], v[128:131]
	v_mfma_f32_16x16x32_bf16 v[124:127], v[100:103], v[188:191], v[124:127]
	v_mfma_f32_16x16x32_bf16 v[120:123], v[148:151], v[188:191], v[120:123]
	v_mfma_f32_16x16x32_bf16 v[116:119], v[100:103], v[196:199], v[116:119]
	v_mfma_f32_16x16x32_bf16 v[112:115], v[148:151], v[196:199], v[112:115]
	v_mfma_f32_16x16x32_bf16 v[108:111], v[100:103], v[208:211], v[108:111]
	v_mfma_f32_16x16x32_bf16 v[104:107], v[148:151], v[208:211], v[104:107]
	v_mfma_f32_16x16x32_bf16 v[60:63], v[160:163], v[176:179], v[60:63]
	v_mfma_f32_16x16x32_bf16 v[56:59], v[168:171], v[176:179], v[56:59]
	v_mfma_f32_16x16x32_bf16 v[52:55], v[160:163], v[184:187], v[52:55]
	v_mfma_f32_16x16x32_bf16 v[48:51], v[168:171], v[184:187], v[48:51]
	v_mfma_f32_16x16x32_bf16 v[44:47], v[160:163], v[192:195], v[44:47]
	v_mfma_f32_16x16x32_bf16 v[40:43], v[168:171], v[192:195], v[40:43]
	v_mfma_f32_16x16x32_bf16 v[36:39], v[160:163], v[204:207], v[36:39]
	v_mfma_f32_16x16x32_bf16 v[32:35], v[168:171], v[204:207], v[32:35]
	v_mfma_f32_16x16x32_bf16 v[60:63], v[164:167], v[180:183], v[60:63]
	v_mfma_f32_16x16x32_bf16 v[56:59], v[172:175], v[180:183], v[56:59]
	v_mfma_f32_16x16x32_bf16 v[52:55], v[164:167], v[188:191], v[52:55]
	v_mfma_f32_16x16x32_bf16 v[48:51], v[172:175], v[188:191], v[48:51]
	v_mfma_f32_16x16x32_bf16 v[44:47], v[164:167], v[196:199], v[44:47]
	v_mfma_f32_16x16x32_bf16 v[40:43], v[172:175], v[196:199], v[40:43]
	v_mfma_f32_16x16x32_bf16 v[36:39], v[164:167], v[208:211], v[36:39]
	v_mfma_f32_16x16x32_bf16 v[32:35], v[172:175], v[208:211], v[32:35]
	s_barrier
; #define PG8_STAGE(bufoff, gbase, voff) do { _Pragma("unroll") for (int _i = 0; _i < 2; ++_i) \
;         __builtin_amdgcn_global_load_lds((const unsigned*)((const char*)(gbase) + (voff)[_i]), (LAS unsigned*)(lds + (bufoff) + ldsw + _i * 8192), 16, 0, 0); } while (0)
; #define PG8_LDA(dst, b, h) do { _Pragma("unroll") for (int m = 0; m < 4; ++m) _Pragma("unroll") for (int k = 0; k < 2; ++k) dst[m][k] = *(const LAS bf16x8*)(lds + PG8_SA(b, h) + aoff + m * 2048 + k * 1024); } while (0)
; #define PG8_MMA(ai, bj, At, Bt) do { __builtin_amdgcn_s_setprio(1); _Pragma("unroll") for (int m = 0; m < 4; ++m) _Pragma("unroll") for (int n = 0; n < 2; ++n) _Pragma("unroll") for (int k = 0; k < 2; ++k) \
;         acc[ai][bj][m][n] = __builtin_amdgcn_mfma_f32_16x16x32_bf16(Bt[n][k], At[m][k], acc[ai][bj][m][n], 0, 0, 0); __builtin_amdgcn_s_setprio(0); } while (0)
; #define PG8_WAIT_V(n) asm volatile("s_waitcnt vmcnt(" #n ")" ::: "memory")
; #define PG8_WAIT_L(n) asm volatile("s_waitcnt lgkmcnt(" #n ")" ::: "memory")
; #define PG8_BAR __builtin_amdgcn_s_barrier()
; #define PG8_SCHED __builtin_amdgcn_sched_barrier(0)
; template <class Epi>
; __device__ __forceinline__ void gemm_phase(LAS unsigned char* lds, const Gemm g, const Sched& S, const Epi& E) {
;     ...
;             PG8_LDA(At, 1, 1); PG8_STAGE(PG8_SB(1, 0), b3, voffB); PG8_STAGE(PG8_SB(1, 1), b3 + hstepB, voffB); PG8_STAGE(PG8_SA(1, 0), a3, voffA);
;             PG8_WAIT_V(8); PG8_WAIT_L(0); PG8_BAR; PG8_MMA(1, 0, At, B0); PG8_MMA(1, 1, At, B1); PG8_BAR; PG8_SCHED;
;         }
;         if (wr == 0) PG8_BAR;
	s_mov_b32 m0, s64
	v_lshl_add_u64 v[200:201], v[200:201], 0, s[46:47]
	ds_read_b128 v[176:179], v157 offset:49152
	ds_read_b128 v[180:183], v157 offset:50176
	ds_read_b128 v[184:187], v157 offset:51200
	ds_read_b128 v[188:191], v157 offset:52224
	ds_read_b128 v[192:195], v157 offset:53248
	ds_read_b128 v[196:199], v157 offset:54272
	ds_read_b128 v[204:207], v157 offset:55296
	ds_read_b128 v[208:211], v157 offset:56320
	global_load_lds_dwordx4 v[200:201], off
	v_lshl_add_u64 v[200:201], v[212:213], 0, s[46:47]
	s_mov_b32 m0, s62
	s_nop 0
	global_load_lds_dwordx4 v[200:201], off
	v_lshl_add_u64 v[200:201], s[14:15], 0, v[138:139]
	s_mov_b32 m0, s63
	s_nop 0
	global_load_lds_dwordx4 v[200:201], off
	v_lshl_add_u64 v[200:201], s[14:15], 0, v[142:143]
	s_mov_b32 m0, s57
	s_nop 0
	global_load_lds_dwordx4 v[200:201], off
	v_lshl_add_u64 v[200:201], v[214:215], 0, s[46:47]
	s_mov_b32 m0, s97
	s_nop 0
	global_load_lds_dwordx4 v[200:201], off
	v_lshl_add_u64 v[200:201], v[216:217], 0, s[46:47]
	s_mov_b32 m0, s58
	s_nop 0
	global_load_lds_dwordx4 v[200:201], off
	s_waitcnt vmcnt(8)
	s_waitcnt lgkmcnt(0)
	s_barrier
	s_waitcnt lgkmcnt(0)
	v_mfma_f32_16x16x32_bf16 v[92:95], v[96:99], v[176:179], v[92:95]
	v_mfma_f32_16x16x32_bf16 v[88:91], v[144:147], v[176:179], v[88:91]
	v_mfma_f32_16x16x32_bf16 v[84:87], v[96:99], v[184:187], v[84:87]
	v_mfma_f32_16x16x32_bf16 v[80:83], v[144:147], v[184:187], v[80:83]
	v_mfma_f32_16x16x32_bf16 v[76:79], v[96:99], v[192:195], v[76:79]
	v_mfma_f32_16x16x32_bf16 v[72:75], v[144:147], v[192:195], v[72:75]
	v_mfma_f32_16x16x32_bf16 v[68:71], v[96:99], v[204:207], v[68:71]
	v_mfma_f32_16x16x32_bf16 v[64:67], v[144:147], v[204:207], v[64:67]
	v_mfma_f32_16x16x32_bf16 v[92:95], v[100:103], v[180:183], v[92:95]
	v_mfma_f32_16x16x32_bf16 v[88:91], v[148:151], v[180:183], v[88:91]
	v_mfma_f32_16x16x32_bf16 v[84:87], v[100:103], v[188:191], v[84:87]
	v_mfma_f32_16x16x32_bf16 v[80:83], v[148:151], v[188:191], v[80:83]
	v_mfma_f32_16x16x32_bf16 v[76:79], v[100:103], v[196:199], v[76:79]
	v_mfma_f32_16x16x32_bf16 v[72:75], v[148:151], v[196:199], v[72:75]
	v_mfma_f32_16x16x32_bf16 v[68:71], v[100:103], v[208:211], v[68:71]
	v_mfma_f32_16x16x32_bf16 v[64:67], v[148:151], v[208:211], v[64:67]
	v_mfma_f32_16x16x32_bf16 v[28:31], v[160:163], v[176:179], v[28:31]
	v_mfma_f32_16x16x32_bf16 v[24:27], v[168:171], v[176:179], v[24:27]
	v_mfma_f32_16x16x32_bf16 v[20:23], v[160:163], v[184:187], v[20:23]
	v_mfma_f32_16x16x32_bf16 v[16:19], v[168:171], v[184:187], v[16:19]
	v_mfma_f32_16x16x32_bf16 v[12:15], v[160:163], v[192:195], v[12:15]
	v_mfma_f32_16x16x32_bf16 v[8:11], v[168:171], v[192:195], v[8:11]
	v_mfma_f32_16x16x32_bf16 v[4:7], v[160:163], v[204:207], v[4:7]
	v_mfma_f32_16x16x32_bf16 v[0:3], v[168:171], v[204:207], v[0:3]
	v_mfma_f32_16x16x32_bf16 v[28:31], v[164:167], v[180:183], v[28:31]
	v_mfma_f32_16x16x32_bf16 v[24:27], v[172:175], v[180:183], v[24:27]
	v_mfma_f32_16x16x32_bf16 v[20:23], v[164:167], v[188:191], v[20:23]
	v_mfma_f32_16x16x32_bf16 v[16:19], v[172:175], v[188:191], v[16:19]
	v_mfma_f32_16x16x32_bf16 v[12:15], v[164:167], v[196:199], v[12:15]
	v_mfma_f32_16x16x32_bf16 v[8:11], v[172:175], v[196:199], v[8:11]
	v_mfma_f32_16x16x32_bf16 v[4:7], v[164:167], v[208:211], v[4:7]
	v_mfma_f32_16x16x32_bf16 v[0:3], v[172:175], v[208:211], v[0:3]
	s_andn2_b64 vcc, exec, s[8:9]
	s_mov_b64 s[14:15], -1
	s_mov_b64 s[8:9], 0
	s_mov_b64 s[78:79], 0x100
	s_barrier
	s_cbranch_vccz .LBB0_900
	s_and_b64 vcc, exec, s[52:53]
	s_cbranch_vccz .LBB0_903
	s_barrier

; #define PG8_STAGE(bufoff, gbase, voff) do { _Pragma("unroll") for (int _i = 0; _i < 2; ++_i) \
;         __builtin_amdgcn_global_load_lds((const unsigned*)((const char*)(gbase) + (voff)[_i]), (LAS unsigned*)(lds + (bufoff) + ldsw + _i * 8192), 16, 0, 0); } while (0)
; #define PG8_LDA(dst, b, h) do { _Pragma("unroll") for (int m = 0; m < 4; ++m) _Pragma("unroll") for (int k = 0; k < 2; ++k) dst[m][k] = *(const LAS bf16x8*)(lds + PG8_SA(b, h) + aoff + m * 2048 + k * 1024); } while (0)
; #define PG8_LDB(dst, b, h) do { _Pragma("unroll") for (int n = 0; n < 2; ++n) _Pragma("unroll") for (int k = 0; k < 2; ++k) dst[n][k] = *(const LAS bf16x8*)(lds + PG8_SB(b, h) + boff + n * 2048 + k * 1024); } while (0)
; #define PG8_MMA(ai, bj, At, Bt) do { __builtin_amdgcn_s_setprio(1); _Pragma("unroll") for (int m = 0; m < 4; ++m) _Pragma("unroll") for (int n = 0; n < 2; ++n) _Pragma("unroll") for (int k = 0; k < 2; ++k) \
;         acc[ai][bj][m][n] = __builtin_amdgcn_mfma_f32_16x16x32_bf16(Bt[n][k], At[m][k], acc[ai][bj][m][n], 0, 0, 0); __builtin_amdgcn_s_setprio(0); } while (0)
; #define PG8_WAIT_V(n) asm volatile("s_waitcnt vmcnt(" #n ")" ::: "memory")
; #define PG8_WAIT_L(n) asm volatile("s_waitcnt lgkmcnt(" #n ")" ::: "memory")
; #define PG8_BAR __builtin_amdgcn_s_barrier()
; #define PG8_SCHED __builtin_amdgcn_sched_barrier(0)
; template <class Epi>
; __device__ __forceinline__ void gemm_phase(LAS unsigned char* lds, const Gemm g, const Sched& S, const Epi& E) {
;     ...
;         for (int t = 0; t < nt; t += 2) {
;             const bool last = (t == nt - 2);
;             const char* a1 = cA + (size_t)(t + 1) * kstep;
;             const char* a2 = last ? nA : cA + (size_t)(t + 2) * kstep; const char* b2 = last ? nB : cB + (size_t)(t + 2) * kstep;
;             const char* a3 = a2 + kstep; const char* b3 = b2 + kstep;
;             PG8_LDB(B0, 0, 0); PG8_LDB(B1, 0, 1); PG8_SCHED; PG8_LDA(At, 0, 0); PG8_STAGE(PG8_SA(1, 1), a1 + hstepA, voffA);
;             PG8_WAIT_V(8); PG8_WAIT_L(0); PG8_BAR; PG8_MMA(0, 0, At, B0); PG8_MMA(0, 1, At, B1); PG8_BAR; PG8_SCHED;
;             PG8_LDA(At, 0, 1); PG8_STAGE(PG8_SB(0, 0), b2, voffB); PG8_STAGE(PG8_SB(0, 1), b2 + hstepB, voffB); PG8_STAGE(PG8_SA(0, 0), a2, voffA);
;             PG8_WAIT_V(8); PG8_WAIT_L(0); PG8_BAR; PG8_MMA(1, 0, At, B0); PG8_MMA(1, 1, At, B1); PG8_BAR; PG8_SCHED;
.LBB0_1214:
	v_add_u32_e32 v158, s58, v144
	v_add_u32_e32 v174, s59, v144
	s_add_u32 s46, s40, s44
	ds_read_b128 v[146:149], v158
	ds_read_b128 v[150:153], v158 offset:1024
	ds_read_b128 v[154:157], v158 offset:2048
	ds_read_b128 v[158:161], v158 offset:3072
	ds_read_b128 v[162:165], v174
	ds_read_b128 v[166:169], v174 offset:1024
	ds_read_b128 v[170:173], v174 offset:2048
	ds_read_b128 v[174:177], v174 offset:3072
	s_addc_u32 s47, s41, s45
	s_add_u32 s46, s46, 0x100
	s_addc_u32 s47, s47, 0
	s_add_u32 s67, s62, s44
	s_addc_u32 s68, s63, s45
	s_cmpk_eq_i32 s44, 0x700
	s_cselect_b32 s49, s25, s47
	s_cselect_b32 s48, s64, s46
	s_cselect_b32 s47, s27, s68
	s_cselect_b32 s46, s65, s67
	v_lshl_add_u64 v[186:187], v[140:141], 0, s[44:45]
	s_add_i32 m0, s51, 0xc000
	ds_read_b128 v[178:181], v145
	ds_read_b128 v[182:185], v145 offset:1024
	ds_read_b128 v[192:195], v145 offset:2048
	ds_read_b128 v[196:199], v145 offset:3072
	ds_read_b128 v[204:207], v145 offset:4096
	ds_read_b128 v[208:211], v145 offset:5120
	ds_read_b128 v[212:215], v145 offset:6144
	ds_read_b128 v[216:219], v145 offset:7168
	global_load_lds_dwordx4 v[186:187], off
	v_lshl_add_u64 v[186:187], v[142:143], 0, s[44:45]
	s_add_i32 m0, s51, 0xe000
	s_nop 0
	global_load_lds_dwordx4 v[186:187], off
	s_waitcnt vmcnt(8)
	s_waitcnt lgkmcnt(0)
	s_barrier
	s_waitcnt lgkmcnt(0)
	v_mfma_f32_16x16x32_bf16 v[124:127], v[146:149], v[178:181], v[124:127]
	v_mfma_f32_16x16x32_bf16 v[120:123], v[154:157], v[178:181], v[120:123]
	v_mfma_f32_16x16x32_bf16 v[108:111], v[146:149], v[192:195], v[108:111]
	v_mfma_f32_16x16x32_bf16 v[104:107], v[154:157], v[192:195], v[104:107]
	v_mfma_f32_16x16x32_bf16 v[92:95], v[146:149], v[204:207], v[92:95]
	v_mfma_f32_16x16x32_bf16 v[88:91], v[154:157], v[204:207], v[88:91]
	v_mfma_f32_16x16x32_bf16 v[76:79], v[146:149], v[212:215], v[76:79]
	v_mfma_f32_16x16x32_bf16 v[72:75], v[154:157], v[212:215], v[72:75]
	v_mfma_f32_16x16x32_bf16 v[124:127], v[150:153], v[182:185], v[124:127]
	v_mfma_f32_16x16x32_bf16 v[120:123], v[158:161], v[182:185], v[120:123]
	v_mfma_f32_16x16x32_bf16 v[108:111], v[150:153], v[196:199], v[108:111]
	v_mfma_f32_16x16x32_bf16 v[104:107], v[158:161], v[196:199], v[104:107]
	v_mfma_f32_16x16x32_bf16 v[92:95], v[150:153], v[208:211], v[92:95]
	v_mfma_f32_16x16x32_bf16 v[88:91], v[158:161], v[208:211], v[88:91]
	v_mfma_f32_16x16x32_bf16 v[76:79], v[150:153], v[216:219], v[76:79]
	v_mfma_f32_16x16x32_bf16 v[72:75], v[158:161], v[216:219], v[72:75]
	v_mfma_f32_16x16x32_bf16 v[116:119], v[162:165], v[178:181], v[116:119]
	v_mfma_f32_16x16x32_bf16 v[112:115], v[170:173], v[178:181], v[112:115]
	v_mfma_f32_16x16x32_bf16 v[100:103], v[162:165], v[192:195], v[100:103]
	v_mfma_f32_16x16x32_bf16 v[96:99], v[170:173], v[192:195], v[96:99]
	v_mfma_f32_16x16x32_bf16 v[84:87], v[162:165], v[204:207], v[84:87]
	v_mfma_f32_16x16x32_bf16 v[80:83], v[170:173], v[204:207], v[80:83]
	v_mfma_f32_16x16x32_bf16 v[68:71], v[162:165], v[212:215], v[68:71]
	v_mfma_f32_16x16x32_bf16 v[64:67], v[170:173], v[212:215], v[64:67]
	v_mfma_f32_16x16x32_bf16 v[116:119], v[166:169], v[182:185], v[116:119]
	v_mfma_f32_16x16x32_bf16 v[112:115], v[174:177], v[182:185], v[112:115]
	v_mfma_f32_16x16x32_bf16 v[100:103], v[166:169], v[196:199], v[100:103]
	v_mfma_f32_16x16x32_bf16 v[96:99], v[174:177], v[196:199], v[96:99]
	v_mfma_f32_16x16x32_bf16 v[84:87], v[166:169], v[208:211], v[84:87]
	v_mfma_f32_16x16x32_bf16 v[80:83], v[174:177], v[208:211], v[80:83]
	v_mfma_f32_16x16x32_bf16 v[68:71], v[166:169], v[216:219], v[68:71]
	v_mfma_f32_16x16x32_bf16 v[64:67], v[174:177], v[216:219], v[64:67]
	s_barrier
	s_add_i32 s67, s58, s50
	v_lshl_add_u64 v[186:187], s[46:47], 0, v[130:131]
	s_mov_b32 m0, s67
	ds_read_b128 v[178:181], v145 offset:16384
	ds_read_b128 v[182:185], v145 offset:17408
	ds_read_b128 v[192:195], v145 offset:18432
	ds_read_b128 v[196:199], v145 offset:19456
	ds_read_b128 v[204:207], v145 offset:20480
	ds_read_b128 v[208:211], v145 offset:21504
	ds_read_b128 v[212:215], v145 offset:22528
	ds_read_b128 v[216:219], v145 offset:23552
	global_load_lds_dwordx4 v[186:187], off
	s_add_i32 m0, s67, 0x2000
	s_add_u32 s68, s46, 0x40000
	v_lshl_add_u64 v[200:201], s[46:47], 0, v[134:135]
	s_addc_u32 s69, s47, 0
	s_add_i32 s67, s59, s50
	global_load_lds_dwordx4 v[200:201], off
	v_lshl_add_u64 v[220:221], s[68:69], 0, v[130:131]
	s_mov_b32 m0, s67
	v_lshl_add_u64 v[222:223], s[48:49], 0, v[132:133]
	global_load_lds_dwordx4 v[220:221], off
	v_lshl_add_u64 v[220:221], s[68:69], 0, v[134:135]
	s_add_i32 m0, s67, 0x2000
	s_nop 0
	global_load_lds_dwordx4 v[220:221], off
	v_lshl_add_u64 v[220:221], s[48:49], 0, v[128:129]
	s_mov_b32 m0, s51
	s_nop 0
	global_load_lds_dwordx4 v[220:221], off
	s_mov_b32 m0, s52
	s_nop 0
	global_load_lds_dwordx4 v[222:223], off
	s_waitcnt vmcnt(8)
	s_waitcnt lgkmcnt(0)
	s_barrier
; #define PG8_STAGE(bufoff, gbase, voff) do { _Pragma("unroll") for (int _i = 0; _i < 2; ++_i) \
;         __builtin_amdgcn_global_load_lds((const unsigned*)((const char*)(gbase) + (voff)[_i]), (LAS unsigned*)(lds + (bufoff) + ldsw + _i * 8192), 16, 0, 0); } while (0)
; #define PG8_LDA(dst, b, h) do { _Pragma("unroll") for (int m = 0; m < 4; ++m) _Pragma("unroll") for (int k = 0; k < 2; ++k) dst[m][k] = *(const LAS bf16x8*)(lds + PG8_SA(b, h) + aoff + m * 2048 + k * 1024); } while (0)
; #define PG8_LDB(dst, b, h) do { _Pragma("unroll") for (int n = 0; n < 2; ++n) _Pragma("unroll") for (int k = 0; k < 2; ++k) dst[n][k] = *(const LAS bf16x8*)(lds + PG8_SB(b, h) + boff + n * 2048 + k * 1024); } while (0)
; #define PG8_MMA(ai, bj, At, Bt) do { __builtin_amdgcn_s_setprio(1); _Pragma("unroll") for (int m = 0; m < 4; ++m) _Pragma("unroll") for (int n = 0; n < 2; ++n) _Pragma("unroll") for (int k = 0; k < 2; ++k) \
;         acc[ai][bj][m][n] = __builtin_amdgcn_mfma_f32_16x16x32_bf16(Bt[n][k], At[m][k], acc[ai][bj][m][n], 0, 0, 0); __builtin_amdgcn_s_setprio(0); } while (0)
; #define PG8_WAIT_V(n) asm volatile("s_waitcnt vmcnt(" #n ")" ::: "memory")
; #define PG8_WAIT_L(n) asm volatile("s_waitcnt lgkmcnt(" #n ")" ::: "memory")
; #define PG8_BAR __builtin_amdgcn_s_barrier()
; #define PG8_SCHED __builtin_amdgcn_sched_barrier(0)
; template <class Epi>
; __device__ __forceinline__ void gemm_phase(LAS unsigned char* lds, const Gemm g, const Sched& S, const Epi& E) {
;     ...
;             PG8_WAIT_V(8); PG8_WAIT_L(0); PG8_BAR; PG8_MMA(1, 0, At, B0); PG8_MMA(1, 1, At, B1); PG8_BAR; PG8_SCHED;
;             PG8_LDB(B0, 1, 0); PG8_LDB(B1, 1, 1); PG8_SCHED; PG8_LDA(At, 1, 0); PG8_STAGE(PG8_SA(0, 1), a2 + hstepA, voffA);
;             PG8_WAIT_V(8); PG8_WAIT_L(0); PG8_BAR; PG8_MMA(0, 0, At, B0); PG8_MMA(0, 1, At, B1); PG8_BAR; PG8_SCHED;
	s_waitcnt lgkmcnt(0)
	v_mfma_f32_16x16x32_bf16 v[60:63], v[146:149], v[178:181], v[60:63]
	v_mfma_f32_16x16x32_bf16 v[56:59], v[154:157], v[178:181], v[56:59]
	v_mfma_f32_16x16x32_bf16 v[44:47], v[146:149], v[192:195], v[44:47]
	v_mfma_f32_16x16x32_bf16 v[40:43], v[154:157], v[192:195], v[40:43]
	v_mfma_f32_16x16x32_bf16 v[28:31], v[146:149], v[204:207], v[28:31]
	v_mfma_f32_16x16x32_bf16 v[24:27], v[154:157], v[204:207], v[24:27]
	v_mfma_f32_16x16x32_bf16 v[12:15], v[146:149], v[212:215], v[12:15]
	v_mfma_f32_16x16x32_bf16 v[8:11], v[154:157], v[212:215], v[8:11]
	v_mfma_f32_16x16x32_bf16 v[60:63], v[150:153], v[182:185], v[60:63]
	v_mfma_f32_16x16x32_bf16 v[56:59], v[158:161], v[182:185], v[56:59]
	v_mfma_f32_16x16x32_bf16 v[44:47], v[150:153], v[196:199], v[44:47]
	v_mfma_f32_16x16x32_bf16 v[40:43], v[158:161], v[196:199], v[40:43]
	v_mfma_f32_16x16x32_bf16 v[28:31], v[150:153], v[208:211], v[28:31]
	v_mfma_f32_16x16x32_bf16 v[24:27], v[158:161], v[208:211], v[24:27]
	v_mfma_f32_16x16x32_bf16 v[12:15], v[150:153], v[216:219], v[12:15]
	v_mfma_f32_16x16x32_bf16 v[8:11], v[158:161], v[216:219], v[8:11]
	v_mfma_f32_16x16x32_bf16 v[52:55], v[162:165], v[178:181], v[52:55]
	v_mfma_f32_16x16x32_bf16 v[48:51], v[170:173], v[178:181], v[48:51]
	v_mfma_f32_16x16x32_bf16 v[36:39], v[162:165], v[192:195], v[36:39]
	v_mfma_f32_16x16x32_bf16 v[32:35], v[170:173], v[192:195], v[32:35]
	v_mfma_f32_16x16x32_bf16 v[20:23], v[162:165], v[204:207], v[20:23]
	v_mfma_f32_16x16x32_bf16 v[16:19], v[170:173], v[204:207], v[16:19]
	v_mfma_f32_16x16x32_bf16 v[4:7], v[162:165], v[212:215], v[4:7]
	v_mfma_f32_16x16x32_bf16 v[0:3], v[170:173], v[212:215], v[0:3]
	v_mfma_f32_16x16x32_bf16 v[52:55], v[166:169], v[182:185], v[52:55]
	v_mfma_f32_16x16x32_bf16 v[48:51], v[174:177], v[182:185], v[48:51]
	v_mfma_f32_16x16x32_bf16 v[36:39], v[166:169], v[196:199], v[36:39]
	v_mfma_f32_16x16x32_bf16 v[32:35], v[174:177], v[196:199], v[32:35]
	v_mfma_f32_16x16x32_bf16 v[20:23], v[166:169], v[208:211], v[20:23]
	v_mfma_f32_16x16x32_bf16 v[16:19], v[174:177], v[208:211], v[16:19]
	v_mfma_f32_16x16x32_bf16 v[4:7], v[166:169], v[216:219], v[4:7]
	v_mfma_f32_16x16x32_bf16 v[0:3], v[174:177], v[216:219], v[0:3]
	s_barrier
	s_add_i32 s67, 0, 0x18000
	s_add_i32 s68, 0, 0x1c000
	v_add_u32_e32 v158, s67, v144
	v_add_u32_e32 v174, s68, v144
	ds_read_b128 v[146:149], v158
	ds_read_b128 v[150:153], v158 offset:1024
	ds_read_b128 v[154:157], v158 offset:2048
	ds_read_b128 v[158:161], v158 offset:3072
	ds_read_b128 v[162:165], v174
	ds_read_b128 v[166:169], v174 offset:1024
	ds_read_b128 v[170:173], v174 offset:2048
	ds_read_b128 v[174:177], v174 offset:3072
	s_add_u32 s48, s48, 0x40000
	s_addc_u32 s49, s49, 0
	s_mov_b32 m0, s53
	v_lshl_add_u64 v[224:225], s[48:49], 0, v[128:129]
	ds_read_b128 v[178:181], v145 offset:32768
	ds_read_b128 v[182:185], v145 offset:33792
	ds_read_b128 v[192:195], v145 offset:34816
	ds_read_b128 v[196:199], v145 offset:35840
	ds_read_b128 v[204:207], v145 offset:36864
	ds_read_b128 v[208:211], v145 offset:37888
	ds_read_b128 v[212:215], v145 offset:38912
	ds_read_b128 v[216:219], v145 offset:39936
	global_load_lds_dwordx4 v[224:225], off
	v_lshl_add_u64 v[224:225], s[48:49], 0, v[132:133]
	s_mov_b32 m0, s54
	s_nop 0
	global_load_lds_dwordx4 v[224:225], off
	s_waitcnt vmcnt(8)
	s_waitcnt lgkmcnt(0)
	s_barrier
	s_waitcnt lgkmcnt(0)
	v_mfma_f32_16x16x32_bf16 v[124:127], v[146:149], v[178:181], v[124:127]
	v_mfma_f32_16x16x32_bf16 v[120:123], v[154:157], v[178:181], v[120:123]
	v_mfma_f32_16x16x32_bf16 v[108:111], v[146:149], v[192:195], v[108:111]
	v_mfma_f32_16x16x32_bf16 v[104:107], v[154:157], v[192:195], v[104:107]
	v_mfma_f32_16x16x32_bf16 v[92:95], v[146:149], v[204:207], v[92:95]
	v_mfma_f32_16x16x32_bf16 v[88:91], v[154:157], v[204:207], v[88:91]
	v_mfma_f32_16x16x32_bf16 v[76:79], v[146:149], v[212:215], v[76:79]
	v_mfma_f32_16x16x32_bf16 v[72:75], v[154:157], v[212:215], v[72:75]
	v_mfma_f32_16x16x32_bf16 v[124:127], v[150:153], v[182:185], v[124:127]
	v_mfma_f32_16x16x32_bf16 v[120:123], v[158:161], v[182:185], v[120:123]
	v_mfma_f32_16x16x32_bf16 v[108:111], v[150:153], v[196:199], v[108:111]
	v_mfma_f32_16x16x32_bf16 v[104:107], v[158:161], v[196:199], v[104:107]
	v_mfma_f32_16x16x32_bf16 v[92:95], v[150:153], v[208:211], v[92:95]
	v_mfma_f32_16x16x32_bf16 v[88:91], v[158:161], v[208:211], v[88:91]
	v_mfma_f32_16x16x32_bf16 v[76:79], v[150:153], v[216:219], v[76:79]
	v_mfma_f32_16x16x32_bf16 v[72:75], v[158:161], v[216:219], v[72:75]
	v_mfma_f32_16x16x32_bf16 v[116:119], v[162:165], v[178:181], v[116:119]
	v_mfma_f32_16x16x32_bf16 v[112:115], v[170:173], v[178:181], v[112:115]
	v_mfma_f32_16x16x32_bf16 v[100:103], v[162:165], v[192:195], v[100:103]
	v_mfma_f32_16x16x32_bf16 v[96:99], v[170:173], v[192:195], v[96:99]
	v_mfma_f32_16x16x32_bf16 v[84:87], v[162:165], v[204:207], v[84:87]
	v_mfma_f32_16x16x32_bf16 v[80:83], v[170:173], v[204:207], v[80:83]
	v_mfma_f32_16x16x32_bf16 v[68:71], v[162:165], v[212:215], v[68:71]
	v_mfma_f32_16x16x32_bf16 v[64:67], v[170:173], v[212:215], v[64:67]
	v_mfma_f32_16x16x32_bf16 v[116:119], v[166:169], v[182:185], v[116:119]
	v_mfma_f32_16x16x32_bf16 v[112:115], v[174:177], v[182:185], v[112:115]
	v_mfma_f32_16x16x32_bf16 v[100:103], v[166:169], v[196:199], v[100:103]
	v_mfma_f32_16x16x32_bf16 v[96:99], v[174:177], v[196:199], v[96:99]
	v_mfma_f32_16x16x32_bf16 v[84:87], v[166:169], v[208:211], v[84:87]
	v_mfma_f32_16x16x32_bf16 v[80:83], v[174:177], v[208:211], v[80:83]
	v_mfma_f32_16x16x32_bf16 v[68:71], v[166:169], v[216:219], v[68:71]
	v_mfma_f32_16x16x32_bf16 v[64:67], v[174:177], v[216:219], v[64:67]
	s_barrier
; #define PG8_STAGE(bufoff, gbase, voff) do { _Pragma("unroll") for (int _i = 0; _i < 2; ++_i) \
;         __builtin_amdgcn_global_load_lds((const unsigned*)((const char*)(gbase) + (voff)[_i]), (LAS unsigned*)(lds + (bufoff) + ldsw + _i * 8192), 16, 0, 0); } while (0)
; #define PG8_LDA(dst, b, h) do { _Pragma("unroll") for (int m = 0; m < 4; ++m) _Pragma("unroll") for (int k = 0; k < 2; ++k) dst[m][k] = *(const LAS bf16x8*)(lds + PG8_SA(b, h) + aoff + m * 2048 + k * 1024); } while (0)
; #define PG8_MMA(ai, bj, At, Bt) do { __builtin_amdgcn_s_setprio(1); _Pragma("unroll") for (int m = 0; m < 4; ++m) _Pragma("unroll") for (int n = 0; n < 2; ++n) _Pragma("unroll") for (int k = 0; k < 2; ++k) \
;         acc[ai][bj][m][n] = __builtin_amdgcn_mfma_f32_16x16x32_bf16(Bt[n][k], At[m][k], acc[ai][bj][m][n], 0, 0, 0); __builtin_amdgcn_s_setprio(0); } while (0)
; #define PG8_WAIT_V(n) asm volatile("s_waitcnt vmcnt(" #n ")" ::: "memory")
; #define PG8_WAIT_L(n) asm volatile("s_waitcnt lgkmcnt(" #n ")" ::: "memory")
; #define PG8_BAR __builtin_amdgcn_s_barrier()
; #define PG8_SCHED __builtin_amdgcn_sched_barrier(0)
; template <class Epi>
; __device__ __forceinline__ void gemm_phase(LAS unsigned char* lds, const Gemm g, const Sched& S, const Epi& E) {
;     ...
;             PG8_LDA(At, 1, 1); PG8_STAGE(PG8_SB(1, 0), b3, voffB); PG8_STAGE(PG8_SB(1, 1), b3 + hstepB, voffB); PG8_STAGE(PG8_SA(1, 0), a3, voffA);
;             PG8_WAIT_V(8); PG8_WAIT_L(0); PG8_BAR; PG8_MMA(1, 0, At, B0); PG8_MMA(1, 1, At, B1); PG8_BAR; PG8_SCHED;
;         }
;         if (wr == 0) PG8_BAR;
	s_add_i32 s48, s67, s50
	v_lshl_add_u64 v[186:187], v[186:187], 0, s[4:5]
	s_mov_b32 m0, s48
	ds_read_b128 v[178:181], v145 offset:49152
	ds_read_b128 v[182:185], v145 offset:50176
	ds_read_b128 v[192:195], v145 offset:51200
	ds_read_b128 v[196:199], v145 offset:52224
	ds_read_b128 v[204:207], v145 offset:53248
	ds_read_b128 v[208:211], v145 offset:54272
	ds_read_b128 v[212:215], v145 offset:55296
	ds_read_b128 v[216:219], v145 offset:56320
	global_load_lds_dwordx4 v[186:187], off
	s_add_i32 m0, s48, 0x2000
	s_add_u32 s46, s46, 0x40080
	v_lshl_add_u64 v[186:187], v[200:201], 0, s[4:5]
	s_addc_u32 s47, s47, 0
	s_add_i32 s48, s68, s50
	global_load_lds_dwordx4 v[186:187], off
	v_lshl_add_u64 v[186:187], s[46:47], 0, v[130:131]
	s_mov_b32 m0, s48
	s_nop 0
	global_load_lds_dwordx4 v[186:187], off
	v_lshl_add_u64 v[186:187], s[46:47], 0, v[134:135]
	s_add_i32 m0, s48, 0x2000
	s_nop 0
	global_load_lds_dwordx4 v[186:187], off
	v_lshl_add_u64 v[186:187], v[220:221], 0, s[4:5]
	s_mov_b32 m0, s56
	s_nop 0
	global_load_lds_dwordx4 v[186:187], off
	v_lshl_add_u64 v[186:187], v[222:223], 0, s[4:5]
	s_mov_b32 m0, s57
	s_nop 0
	global_load_lds_dwordx4 v[186:187], off
	s_waitcnt vmcnt(8)
	s_waitcnt lgkmcnt(0)
	s_barrier
	s_waitcnt lgkmcnt(0)
	v_mfma_f32_16x16x32_bf16 v[60:63], v[146:149], v[178:181], v[60:63]
	v_mfma_f32_16x16x32_bf16 v[56:59], v[154:157], v[178:181], v[56:59]
	v_mfma_f32_16x16x32_bf16 v[44:47], v[146:149], v[192:195], v[44:47]
	v_mfma_f32_16x16x32_bf16 v[40:43], v[154:157], v[192:195], v[40:43]
	v_mfma_f32_16x16x32_bf16 v[28:31], v[146:149], v[204:207], v[28:31]
	v_mfma_f32_16x16x32_bf16 v[24:27], v[154:157], v[204:207], v[24:27]
	v_mfma_f32_16x16x32_bf16 v[12:15], v[146:149], v[212:215], v[12:15]
	v_mfma_f32_16x16x32_bf16 v[8:11], v[154:157], v[212:215], v[8:11]
	v_mfma_f32_16x16x32_bf16 v[60:63], v[150:153], v[182:185], v[60:63]
	v_mfma_f32_16x16x32_bf16 v[56:59], v[158:161], v[182:185], v[56:59]
	v_mfma_f32_16x16x32_bf16 v[44:47], v[150:153], v[196:199], v[44:47]
	v_mfma_f32_16x16x32_bf16 v[40:43], v[158:161], v[196:199], v[40:43]
	v_mfma_f32_16x16x32_bf16 v[28:31], v[150:153], v[208:211], v[28:31]
	v_mfma_f32_16x16x32_bf16 v[24:27], v[158:161], v[208:211], v[24:27]
	v_mfma_f32_16x16x32_bf16 v[12:15], v[150:153], v[216:219], v[12:15]
	v_mfma_f32_16x16x32_bf16 v[8:11], v[158:161], v[216:219], v[8:11]
	v_mfma_f32_16x16x32_bf16 v[52:55], v[162:165], v[178:181], v[52:55]
	v_mfma_f32_16x16x32_bf16 v[48:51], v[170:173], v[178:181], v[48:51]
	v_mfma_f32_16x16x32_bf16 v[36:39], v[162:165], v[192:195], v[36:39]
	v_mfma_f32_16x16x32_bf16 v[32:35], v[170:173], v[192:195], v[32:35]
	v_mfma_f32_16x16x32_bf16 v[20:23], v[162:165], v[204:207], v[20:23]
	v_mfma_f32_16x16x32_bf16 v[16:19], v[170:173], v[204:207], v[16:19]
	v_mfma_f32_16x16x32_bf16 v[4:7], v[162:165], v[212:215], v[4:7]
	v_mfma_f32_16x16x32_bf16 v[0:3], v[170:173], v[212:215], v[0:3]
	v_mfma_f32_16x16x32_bf16 v[52:55], v[166:169], v[182:185], v[52:55]
	v_mfma_f32_16x16x32_bf16 v[48:51], v[174:177], v[182:185], v[48:51]
	v_mfma_f32_16x16x32_bf16 v[36:39], v[166:169], v[196:199], v[36:39]
	v_mfma_f32_16x16x32_bf16 v[32:35], v[174:177], v[196:199], v[32:35]
	v_mfma_f32_16x16x32_bf16 v[20:23], v[166:169], v[208:211], v[20:23]
	v_mfma_f32_16x16x32_bf16 v[16:19], v[174:177], v[208:211], v[16:19]
	v_mfma_f32_16x16x32_bf16 v[4:7], v[166:169], v[216:219], v[4:7]
	v_mfma_f32_16x16x32_bf16 v[0:3], v[174:177], v[216:219], v[0:3]
	s_add_i32 s66, s66, 2
	s_add_u32 s44, s44, 0x100
	s_addc_u32 s45, s45, 0
	s_cmp_gt_u32 s66, 13
	s_barrier
	s_cbranch_scc0 .LBB0_1214
	s_and_b64 vcc, exec, s[22:23]
	s_cbranch_vccz .LBB0_1217
	s_barrier

; #define PG8_STAGE(bufoff, gbase, voff) do { _Pragma("unroll") for (int _i = 0; _i < 2; ++_i) \
;         __builtin_amdgcn_global_load_lds((const unsigned*)((const char*)(gbase) + (voff)[_i]), (LAS unsigned*)(lds + (bufoff) + ldsw + _i * 8192), 16, 0, 0); } while (0)
; #define PG8_LDA(dst, b, h) do { _Pragma("unroll") for (int m = 0; m < 4; ++m) _Pragma("unroll") for (int k = 0; k < 2; ++k) dst[m][k] = *(const LAS bf16x8*)(lds + PG8_SA(b, h) + aoff + m * 2048 + k * 1024); } while (0)
; #define PG8_LDB(dst, b, h) do { _Pragma("unroll") for (int n = 0; n < 2; ++n) _Pragma("unroll") for (int k = 0; k < 2; ++k) dst[n][k] = *(const LAS bf16x8*)(lds + PG8_SB(b, h) + boff + n * 2048 + k * 1024); } while (0)
; #define PG8_MMA(ai, bj, At, Bt) do { __builtin_amdgcn_s_setprio(1); _Pragma("unroll") for (int m = 0; m < 4; ++m) _Pragma("unroll") for (int n = 0; n < 2; ++n) _Pragma("unroll") for (int k = 0; k < 2; ++k) \
;         acc[ai][bj][m][n] = __builtin_amdgcn_mfma_f32_16x16x32_bf16(Bt[n][k], At[m][k], acc[ai][bj][m][n], 0, 0, 0); __builtin_amdgcn_s_setprio(0); } while (0)
; #define PG8_WAIT_V(n) asm volatile("s_waitcnt vmcnt(" #n ")" ::: "memory")
; #define PG8_WAIT_L(n) asm volatile("s_waitcnt lgkmcnt(" #n ")" ::: "memory")
; #define PG8_BAR __builtin_amdgcn_s_barrier()
; #define PG8_SCHED __builtin_amdgcn_sched_barrier(0)
; template <class Epi>
; __device__ __forceinline__ void gemm_phase(LAS unsigned char* lds, const Gemm g, const Sched& S, const Epi& E) {
;     ...
;         for (int t = 0; t < nt; t += 2) {
;             const bool last = (t == nt - 2);
;             const char* a1 = cA + (size_t)(t + 1) * kstep;
;             const char* a2 = last ? nA : cA + (size_t)(t + 2) * kstep; const char* b2 = last ? nB : cB + (size_t)(t + 2) * kstep;
;             const char* a3 = a2 + kstep; const char* b3 = b2 + kstep;
;             PG8_LDB(B0, 0, 0); PG8_LDB(B1, 0, 1); PG8_SCHED; PG8_LDA(At, 0, 0); PG8_STAGE(PG8_SA(1, 1), a1 + hstepA, voffA);
;             PG8_WAIT_V(8); PG8_WAIT_L(0); PG8_BAR; PG8_MMA(0, 0, At, B0); PG8_MMA(0, 1, At, B1); PG8_BAR; PG8_SCHED;
;             PG8_LDA(At, 0, 1); PG8_STAGE(PG8_SB(0, 0), b2, voffB); PG8_STAGE(PG8_SB(0, 1), b2 + hstepB, voffB); PG8_STAGE(PG8_SA(0, 0), a2, voffA);
;             PG8_WAIT_V(8); PG8_WAIT_L(0); PG8_BAR; PG8_MMA(1, 0, At, B0); PG8_MMA(1, 1, At, B1); PG8_BAR; PG8_SCHED;
.LBB0_1355:
	ds_read_b128 v[140:143], v148
	ds_read_b128 v[152:155], v148 offset:1024
	ds_read_b128 v[156:159], v148 offset:2048
	ds_read_b128 v[160:163], v148 offset:3072
	ds_read_b128 v[164:167], v149
	ds_read_b128 v[168:171], v149 offset:1024
	ds_read_b128 v[172:175], v149 offset:2048
	ds_read_b128 v[176:179], v149 offset:3072
	s_add_u32 s40, s38, 0xfffc0080
	s_addc_u32 s41, s39, -1
	s_cmp_eq_u32 s54, 12
	s_cselect_b32 s43, s23, s41
	s_cselect_b32 s42, s50, s40
	s_cselect_b32 s41, s25, s53
	s_cselect_b32 s40, s51, s52
	v_lshl_add_u64 v[200:201], s[38:39], 0, v[136:137]
	s_add_i32 m0, s11, 0xc000
	ds_read_b128 v[180:183], v150
	ds_read_b128 v[184:187], v150 offset:1024
	ds_read_b128 v[188:191], v150 offset:2048
	ds_read_b128 v[192:195], v150 offset:3072
	ds_read_b128 v[196:199], v150 offset:4096
	ds_read_b128 v[204:207], v150 offset:5120
	ds_read_b128 v[208:211], v150 offset:6144
	ds_read_b128 v[212:215], v150 offset:7168
	global_load_lds_dwordx4 v[200:201], off
	v_lshl_add_u64 v[200:201], s[38:39], 0, v[138:139]
	s_add_i32 m0, s11, 0xe000
	s_nop 0
	global_load_lds_dwordx4 v[200:201], off
	s_waitcnt vmcnt(8)
	s_waitcnt lgkmcnt(0)
	s_barrier
	s_waitcnt lgkmcnt(0)
	v_mfma_f32_16x16x32_bf16 v[124:127], v[140:143], v[180:183], v[124:127]
	v_mfma_f32_16x16x32_bf16 v[120:123], v[156:159], v[180:183], v[120:123]
	v_mfma_f32_16x16x32_bf16 v[116:119], v[140:143], v[188:191], v[116:119]
	v_mfma_f32_16x16x32_bf16 v[108:111], v[156:159], v[188:191], v[108:111]
	v_mfma_f32_16x16x32_bf16 v[100:103], v[140:143], v[196:199], v[100:103]
	v_mfma_f32_16x16x32_bf16 v[92:95], v[156:159], v[196:199], v[92:95]
	v_mfma_f32_16x16x32_bf16 v[84:87], v[140:143], v[208:211], v[84:87]
	v_mfma_f32_16x16x32_bf16 v[76:79], v[156:159], v[208:211], v[76:79]
	v_mfma_f32_16x16x32_bf16 v[124:127], v[152:155], v[184:187], v[124:127]
	v_mfma_f32_16x16x32_bf16 v[120:123], v[160:163], v[184:187], v[120:123]
	v_mfma_f32_16x16x32_bf16 v[116:119], v[152:155], v[192:195], v[116:119]
	v_mfma_f32_16x16x32_bf16 v[108:111], v[160:163], v[192:195], v[108:111]
	v_mfma_f32_16x16x32_bf16 v[100:103], v[152:155], v[204:207], v[100:103]
	v_mfma_f32_16x16x32_bf16 v[92:95], v[160:163], v[204:207], v[92:95]
	v_mfma_f32_16x16x32_bf16 v[84:87], v[152:155], v[212:215], v[84:87]
	v_mfma_f32_16x16x32_bf16 v[76:79], v[160:163], v[212:215], v[76:79]
	v_mfma_f32_16x16x32_bf16 v[112:115], v[164:167], v[180:183], v[112:115]
	v_mfma_f32_16x16x32_bf16 v[104:107], v[172:175], v[180:183], v[104:107]
	v_mfma_f32_16x16x32_bf16 v[96:99], v[164:167], v[188:191], v[96:99]
	v_mfma_f32_16x16x32_bf16 v[88:91], v[172:175], v[188:191], v[88:91]
	v_mfma_f32_16x16x32_bf16 v[80:83], v[164:167], v[196:199], v[80:83]
	v_mfma_f32_16x16x32_bf16 v[72:75], v[172:175], v[196:199], v[72:75]
	v_mfma_f32_16x16x32_bf16 v[68:71], v[164:167], v[208:211], v[68:71]
	v_mfma_f32_16x16x32_bf16 v[64:67], v[172:175], v[208:211], v[64:67]
	v_mfma_f32_16x16x32_bf16 v[112:115], v[168:171], v[184:187], v[112:115]
	v_mfma_f32_16x16x32_bf16 v[104:107], v[176:179], v[184:187], v[104:107]
	v_mfma_f32_16x16x32_bf16 v[96:99], v[168:171], v[192:195], v[96:99]
	v_mfma_f32_16x16x32_bf16 v[88:91], v[176:179], v[192:195], v[88:91]
	v_mfma_f32_16x16x32_bf16 v[80:83], v[168:171], v[204:207], v[80:83]
	v_mfma_f32_16x16x32_bf16 v[72:75], v[176:179], v[204:207], v[72:75]
	v_mfma_f32_16x16x32_bf16 v[68:71], v[168:171], v[212:215], v[68:71]
	v_mfma_f32_16x16x32_bf16 v[64:67], v[176:179], v[212:215], v[64:67]
	s_barrier
	s_add_i32 s55, s47, s10
	v_lshl_add_u64 v[200:201], s[40:41], 0, v[130:131]
	s_mov_b32 m0, s55
	ds_read_b128 v[180:183], v150 offset:16384
	ds_read_b128 v[184:187], v150 offset:17408
	ds_read_b128 v[188:191], v150 offset:18432
	ds_read_b128 v[192:195], v150 offset:19456
	ds_read_b128 v[196:199], v150 offset:20480
	ds_read_b128 v[204:207], v150 offset:21504
	ds_read_b128 v[208:211], v150 offset:22528
	ds_read_b128 v[212:215], v150 offset:23552
	global_load_lds_dwordx4 v[200:201], off
	s_add_i32 m0, s55, 0x2000
	s_add_u32 s56, s40, 0x40000
	v_lshl_add_u64 v[216:217], s[40:41], 0, v[134:135]
	s_addc_u32 s57, s41, 0
	s_add_i32 s55, s48, s10
	global_load_lds_dwordx4 v[216:217], off
	v_lshl_add_u64 v[218:219], s[56:57], 0, v[130:131]
	s_mov_b32 m0, s55
	v_lshl_add_u64 v[220:221], s[42:43], 0, v[132:133]
	global_load_lds_dwordx4 v[218:219], off
	v_lshl_add_u64 v[218:219], s[56:57], 0, v[134:135]
	s_add_i32 m0, s55, 0x2000
	s_nop 0
	global_load_lds_dwordx4 v[218:219], off
	v_lshl_add_u64 v[218:219], s[42:43], 0, v[128:129]
	s_mov_b32 m0, s11
	s_nop 0
	global_load_lds_dwordx4 v[218:219], off
	s_mov_b32 m0, s13
	s_nop 0
	global_load_lds_dwordx4 v[220:221], off
	s_waitcnt vmcnt(8)
	s_waitcnt lgkmcnt(0)
	s_barrier
; #define PG8_STAGE(bufoff, gbase, voff) do { _Pragma("unroll") for (int _i = 0; _i < 2; ++_i) \
;         __builtin_amdgcn_global_load_lds((const unsigned*)((const char*)(gbase) + (voff)[_i]), (LAS unsigned*)(lds + (bufoff) + ldsw + _i * 8192), 16, 0, 0); } while (0)
; #define PG8_LDA(dst, b, h) do { _Pragma("unroll") for (int m = 0; m < 4; ++m) _Pragma("unroll") for (int k = 0; k < 2; ++k) dst[m][k] = *(const LAS bf16x8*)(lds + PG8_SA(b, h) + aoff + m * 2048 + k * 1024); } while (0)
; #define PG8_LDB(dst, b, h) do { _Pragma("unroll") for (int n = 0; n < 2; ++n) _Pragma("unroll") for (int k = 0; k < 2; ++k) dst[n][k] = *(const LAS bf16x8*)(lds + PG8_SB(b, h) + boff + n * 2048 + k * 1024); } while (0)
; #define PG8_MMA(ai, bj, At, Bt) do { __builtin_amdgcn_s_setprio(1); _Pragma("unroll") for (int m = 0; m < 4; ++m) _Pragma("unroll") for (int n = 0; n < 2; ++n) _Pragma("unroll") for (int k = 0; k < 2; ++k) \
;         acc[ai][bj][m][n] = __builtin_amdgcn_mfma_f32_16x16x32_bf16(Bt[n][k], At[m][k], acc[ai][bj][m][n], 0, 0, 0); __builtin_amdgcn_s_setprio(0); } while (0)
; #define PG8_WAIT_V(n) asm volatile("s_waitcnt vmcnt(" #n ")" ::: "memory")
; #define PG8_WAIT_L(n) asm volatile("s_waitcnt lgkmcnt(" #n ")" ::: "memory")
; #define PG8_BAR __builtin_amdgcn_s_barrier()
; #define PG8_SCHED __builtin_amdgcn_sched_barrier(0)
; template <class Epi>
; __device__ __forceinline__ void gemm_phase(LAS unsigned char* lds, const Gemm g, const Sched& S, const Epi& E) {
;     ...
;             PG8_WAIT_V(8); PG8_WAIT_L(0); PG8_BAR; PG8_MMA(1, 0, At, B0); PG8_MMA(1, 1, At, B1); PG8_BAR; PG8_SCHED;
;             PG8_LDB(B0, 1, 0); PG8_LDB(B1, 1, 1); PG8_SCHED; PG8_LDA(At, 1, 0); PG8_STAGE(PG8_SA(0, 1), a2 + hstepA, voffA);
;             PG8_WAIT_V(8); PG8_WAIT_L(0); PG8_BAR; PG8_MMA(0, 0, At, B0); PG8_MMA(0, 1, At, B1); PG8_BAR; PG8_SCHED;
	s_waitcnt lgkmcnt(0)
	v_mfma_f32_16x16x32_bf16 v[60:63], v[140:143], v[180:183], v[60:63]
	v_mfma_f32_16x16x32_bf16 v[56:59], v[156:159], v[180:183], v[56:59]
	v_mfma_f32_16x16x32_bf16 v[52:55], v[140:143], v[188:191], v[52:55]
	v_mfma_f32_16x16x32_bf16 v[44:47], v[156:159], v[188:191], v[44:47]
	v_mfma_f32_16x16x32_bf16 v[36:39], v[140:143], v[196:199], v[36:39]
	v_mfma_f32_16x16x32_bf16 v[28:31], v[156:159], v[196:199], v[28:31]
	v_mfma_f32_16x16x32_bf16 v[20:23], v[140:143], v[208:211], v[20:23]
	v_mfma_f32_16x16x32_bf16 v[12:15], v[156:159], v[208:211], v[12:15]
	v_mfma_f32_16x16x32_bf16 v[60:63], v[152:155], v[184:187], v[60:63]
	v_mfma_f32_16x16x32_bf16 v[56:59], v[160:163], v[184:187], v[56:59]
	v_mfma_f32_16x16x32_bf16 v[52:55], v[152:155], v[192:195], v[52:55]
	v_mfma_f32_16x16x32_bf16 v[44:47], v[160:163], v[192:195], v[44:47]
	v_mfma_f32_16x16x32_bf16 v[36:39], v[152:155], v[204:207], v[36:39]
	v_mfma_f32_16x16x32_bf16 v[28:31], v[160:163], v[204:207], v[28:31]
	v_mfma_f32_16x16x32_bf16 v[20:23], v[152:155], v[212:215], v[20:23]
	v_mfma_f32_16x16x32_bf16 v[12:15], v[160:163], v[212:215], v[12:15]
	v_mfma_f32_16x16x32_bf16 v[48:51], v[164:167], v[180:183], v[48:51]
	v_mfma_f32_16x16x32_bf16 v[40:43], v[172:175], v[180:183], v[40:43]
	v_mfma_f32_16x16x32_bf16 v[32:35], v[164:167], v[188:191], v[32:35]
	v_mfma_f32_16x16x32_bf16 v[24:27], v[172:175], v[188:191], v[24:27]
	v_mfma_f32_16x16x32_bf16 v[16:19], v[164:167], v[196:199], v[16:19]
	v_mfma_f32_16x16x32_bf16 v[8:11], v[172:175], v[196:199], v[8:11]
	v_mfma_f32_16x16x32_bf16 v[4:7], v[164:167], v[208:211], v[4:7]
	v_mfma_f32_16x16x32_bf16 v[0:3], v[172:175], v[208:211], v[0:3]
	v_mfma_f32_16x16x32_bf16 v[48:51], v[168:171], v[184:187], v[48:51]
	v_mfma_f32_16x16x32_bf16 v[40:43], v[176:179], v[184:187], v[40:43]
	v_mfma_f32_16x16x32_bf16 v[32:35], v[168:171], v[192:195], v[32:35]
	v_mfma_f32_16x16x32_bf16 v[24:27], v[176:179], v[192:195], v[24:27]
	v_mfma_f32_16x16x32_bf16 v[16:19], v[168:171], v[204:207], v[16:19]
	v_mfma_f32_16x16x32_bf16 v[8:11], v[176:179], v[204:207], v[8:11]
	v_mfma_f32_16x16x32_bf16 v[4:7], v[168:171], v[212:215], v[4:7]
	v_mfma_f32_16x16x32_bf16 v[0:3], v[176:179], v[212:215], v[0:3]
	s_barrier
	s_add_i32 s55, 0, 0x18000
	v_add_u32_e32 v151, s55, v146
	s_add_i32 s56, 0, 0x1c000
	ds_read_b128 v[140:143], v151
	ds_read_b128 v[152:155], v151 offset:1024
	ds_read_b128 v[156:159], v151 offset:2048
	ds_read_b128 v[160:163], v151 offset:3072
	v_add_u32_e32 v151, s56, v146
	ds_read_b128 v[164:167], v151
	ds_read_b128 v[168:171], v151 offset:1024
	ds_read_b128 v[172:175], v151 offset:2048
	ds_read_b128 v[176:179], v151 offset:3072
	s_add_u32 s42, s42, 0x40000
	s_addc_u32 s43, s43, 0
	s_mov_b32 m0, s19
	v_lshl_add_u64 v[222:223], s[42:43], 0, v[128:129]
	ds_read_b128 v[180:183], v150 offset:32768
	ds_read_b128 v[184:187], v150 offset:33792
	ds_read_b128 v[188:191], v150 offset:34816
	ds_read_b128 v[192:195], v150 offset:35840
	ds_read_b128 v[196:199], v150 offset:36864
	ds_read_b128 v[204:207], v150 offset:37888
	ds_read_b128 v[208:211], v150 offset:38912
	ds_read_b128 v[212:215], v150 offset:39936
	global_load_lds_dwordx4 v[222:223], off
	v_lshl_add_u64 v[222:223], s[42:43], 0, v[132:133]
	s_mov_b32 m0, s37
	s_nop 0
	global_load_lds_dwordx4 v[222:223], off
	s_waitcnt vmcnt(8)
	s_waitcnt lgkmcnt(0)
	s_barrier
	s_waitcnt lgkmcnt(0)
	v_mfma_f32_16x16x32_bf16 v[124:127], v[140:143], v[180:183], v[124:127]
	v_mfma_f32_16x16x32_bf16 v[120:123], v[156:159], v[180:183], v[120:123]
	v_mfma_f32_16x16x32_bf16 v[116:119], v[140:143], v[188:191], v[116:119]
	v_mfma_f32_16x16x32_bf16 v[108:111], v[156:159], v[188:191], v[108:111]
	v_mfma_f32_16x16x32_bf16 v[100:103], v[140:143], v[196:199], v[100:103]
	v_mfma_f32_16x16x32_bf16 v[92:95], v[156:159], v[196:199], v[92:95]
	v_mfma_f32_16x16x32_bf16 v[84:87], v[140:143], v[208:211], v[84:87]
	v_mfma_f32_16x16x32_bf16 v[76:79], v[156:159], v[208:211], v[76:79]
	v_mfma_f32_16x16x32_bf16 v[124:127], v[152:155], v[184:187], v[124:127]
	v_mfma_f32_16x16x32_bf16 v[120:123], v[160:163], v[184:187], v[120:123]
	v_mfma_f32_16x16x32_bf16 v[116:119], v[152:155], v[192:195], v[116:119]
	v_mfma_f32_16x16x32_bf16 v[108:111], v[160:163], v[192:195], v[108:111]
	v_mfma_f32_16x16x32_bf16 v[100:103], v[152:155], v[204:207], v[100:103]
	v_mfma_f32_16x16x32_bf16 v[92:95], v[160:163], v[204:207], v[92:95]
	v_mfma_f32_16x16x32_bf16 v[84:87], v[152:155], v[212:215], v[84:87]
	v_mfma_f32_16x16x32_bf16 v[76:79], v[160:163], v[212:215], v[76:79]
	v_mfma_f32_16x16x32_bf16 v[112:115], v[164:167], v[180:183], v[112:115]
	v_mfma_f32_16x16x32_bf16 v[104:107], v[172:175], v[180:183], v[104:107]
	v_mfma_f32_16x16x32_bf16 v[96:99], v[164:167], v[188:191], v[96:99]
	v_mfma_f32_16x16x32_bf16 v[88:91], v[172:175], v[188:191], v[88:91]
	v_mfma_f32_16x16x32_bf16 v[80:83], v[164:167], v[196:199], v[80:83]
	v_mfma_f32_16x16x32_bf16 v[72:75], v[172:175], v[196:199], v[72:75]
	v_mfma_f32_16x16x32_bf16 v[68:71], v[164:167], v[208:211], v[68:71]
	v_mfma_f32_16x16x32_bf16 v[64:67], v[172:175], v[208:211], v[64:67]
	v_mfma_f32_16x16x32_bf16 v[112:115], v[168:171], v[184:187], v[112:115]
	v_mfma_f32_16x16x32_bf16 v[104:107], v[176:179], v[184:187], v[104:107]
	v_mfma_f32_16x16x32_bf16 v[96:99], v[168:171], v[192:195], v[96:99]
	v_mfma_f32_16x16x32_bf16 v[88:91], v[176:179], v[192:195], v[88:91]
	v_mfma_f32_16x16x32_bf16 v[80:83], v[168:171], v[204:207], v[80:83]
	v_mfma_f32_16x16x32_bf16 v[72:75], v[176:179], v[204:207], v[72:75]
	v_mfma_f32_16x16x32_bf16 v[68:71], v[168:171], v[212:215], v[68:71]
	v_mfma_f32_16x16x32_bf16 v[64:67], v[176:179], v[212:215], v[64:67]
	s_barrier
; #define PG8_STAGE(bufoff, gbase, voff) do { _Pragma("unroll") for (int _i = 0; _i < 2; ++_i) \
;         __builtin_amdgcn_global_load_lds((const unsigned*)((const char*)(gbase) + (voff)[_i]), (LAS unsigned*)(lds + (bufoff) + ldsw + _i * 8192), 16, 0, 0); } while (0)
; #define PG8_LDA(dst, b, h) do { _Pragma("unroll") for (int m = 0; m < 4; ++m) _Pragma("unroll") for (int k = 0; k < 2; ++k) dst[m][k] = *(const LAS bf16x8*)(lds + PG8_SA(b, h) + aoff + m * 2048 + k * 1024); } while (0)
; #define PG8_MMA(ai, bj, At, Bt) do { __builtin_amdgcn_s_setprio(1); _Pragma("unroll") for (int m = 0; m < 4; ++m) _Pragma("unroll") for (int n = 0; n < 2; ++n) _Pragma("unroll") for (int k = 0; k < 2; ++k) \
;         acc[ai][bj][m][n] = __builtin_amdgcn_mfma_f32_16x16x32_bf16(Bt[n][k], At[m][k], acc[ai][bj][m][n], 0, 0, 0); __builtin_amdgcn_s_setprio(0); } while (0)
; #define PG8_WAIT_V(n) asm volatile("s_waitcnt vmcnt(" #n ")" ::: "memory")
; #define PG8_WAIT_L(n) asm volatile("s_waitcnt lgkmcnt(" #n ")" ::: "memory")
; #define PG8_BAR __builtin_amdgcn_s_barrier()
; #define PG8_SCHED __builtin_amdgcn_sched_barrier(0)
; template <class Epi>
; __device__ __forceinline__ void gemm_phase(LAS unsigned char* lds, const Gemm g, const Sched& S, const Epi& E) {
;     ...
;             PG8_LDA(At, 1, 1); PG8_STAGE(PG8_SB(1, 0), b3, voffB); PG8_STAGE(PG8_SB(1, 1), b3 + hstepB, voffB); PG8_STAGE(PG8_SA(1, 0), a3, voffA);
;             PG8_WAIT_V(8); PG8_WAIT_L(0); PG8_BAR; PG8_MMA(1, 0, At, B0); PG8_MMA(1, 1, At, B1); PG8_BAR; PG8_SCHED;
;         }
;         if (wr == 0) PG8_BAR;
	s_add_i32 s42, s55, s10
	v_lshl_add_u64 v[200:201], v[200:201], 0, s[14:15]
	s_mov_b32 m0, s42
	ds_read_b128 v[180:183], v150 offset:49152
	ds_read_b128 v[184:187], v150 offset:50176
	ds_read_b128 v[188:191], v150 offset:51200
	ds_read_b128 v[192:195], v150 offset:52224
	ds_read_b128 v[196:199], v150 offset:53248
	ds_read_b128 v[204:207], v150 offset:54272
	ds_read_b128 v[208:211], v150 offset:55296
	ds_read_b128 v[212:215], v150 offset:56320
	global_load_lds_dwordx4 v[200:201], off
	s_add_i32 m0, s42, 0x2000
	s_add_u32 s40, s40, 0x40080
	v_lshl_add_u64 v[200:201], v[216:217], 0, s[14:15]
	s_addc_u32 s41, s41, 0
	s_add_i32 s42, s56, s10
	global_load_lds_dwordx4 v[200:201], off
	v_lshl_add_u64 v[200:201], s[40:41], 0, v[130:131]
	s_mov_b32 m0, s42
	s_nop 0
	global_load_lds_dwordx4 v[200:201], off
	v_lshl_add_u64 v[200:201], s[40:41], 0, v[134:135]
	s_add_i32 m0, s42, 0x2000
	s_nop 0
	global_load_lds_dwordx4 v[200:201], off
	v_lshl_add_u64 v[200:201], v[218:219], 0, s[14:15]
	s_mov_b32 m0, s45
	s_nop 0
	global_load_lds_dwordx4 v[200:201], off
	v_lshl_add_u64 v[200:201], v[220:221], 0, s[14:15]
	s_mov_b32 m0, s46
	s_nop 0
	global_load_lds_dwordx4 v[200:201], off
	s_waitcnt vmcnt(8)
	s_waitcnt lgkmcnt(0)
	s_barrier
	s_waitcnt lgkmcnt(0)
	v_mfma_f32_16x16x32_bf16 v[60:63], v[140:143], v[180:183], v[60:63]
	v_mfma_f32_16x16x32_bf16 v[56:59], v[156:159], v[180:183], v[56:59]
	v_mfma_f32_16x16x32_bf16 v[52:55], v[140:143], v[188:191], v[52:55]
	v_mfma_f32_16x16x32_bf16 v[44:47], v[156:159], v[188:191], v[44:47]
	v_mfma_f32_16x16x32_bf16 v[36:39], v[140:143], v[196:199], v[36:39]
	v_mfma_f32_16x16x32_bf16 v[28:31], v[156:159], v[196:199], v[28:31]
	v_mfma_f32_16x16x32_bf16 v[20:23], v[140:143], v[208:211], v[20:23]
	v_mfma_f32_16x16x32_bf16 v[12:15], v[156:159], v[208:211], v[12:15]
	v_mfma_f32_16x16x32_bf16 v[60:63], v[152:155], v[184:187], v[60:63]
	v_mfma_f32_16x16x32_bf16 v[56:59], v[160:163], v[184:187], v[56:59]
	v_mfma_f32_16x16x32_bf16 v[52:55], v[152:155], v[192:195], v[52:55]
	v_mfma_f32_16x16x32_bf16 v[44:47], v[160:163], v[192:195], v[44:47]
	v_mfma_f32_16x16x32_bf16 v[36:39], v[152:155], v[204:207], v[36:39]
	v_mfma_f32_16x16x32_bf16 v[28:31], v[160:163], v[204:207], v[28:31]
	v_mfma_f32_16x16x32_bf16 v[20:23], v[152:155], v[212:215], v[20:23]
	v_mfma_f32_16x16x32_bf16 v[12:15], v[160:163], v[212:215], v[12:15]
	v_mfma_f32_16x16x32_bf16 v[48:51], v[164:167], v[180:183], v[48:51]
	v_mfma_f32_16x16x32_bf16 v[40:43], v[172:175], v[180:183], v[40:43]
	v_mfma_f32_16x16x32_bf16 v[32:35], v[164:167], v[188:191], v[32:35]
	v_mfma_f32_16x16x32_bf16 v[24:27], v[172:175], v[188:191], v[24:27]
	v_mfma_f32_16x16x32_bf16 v[16:19], v[164:167], v[196:199], v[16:19]
	v_mfma_f32_16x16x32_bf16 v[8:11], v[172:175], v[196:199], v[8:11]
	v_mfma_f32_16x16x32_bf16 v[4:7], v[164:167], v[208:211], v[4:7]
	v_mfma_f32_16x16x32_bf16 v[0:3], v[172:175], v[208:211], v[0:3]
	v_mfma_f32_16x16x32_bf16 v[48:51], v[168:171], v[184:187], v[48:51]
	v_mfma_f32_16x16x32_bf16 v[40:43], v[176:179], v[184:187], v[40:43]
	v_mfma_f32_16x16x32_bf16 v[32:35], v[168:171], v[192:195], v[32:35]
	v_mfma_f32_16x16x32_bf16 v[24:27], v[176:179], v[192:195], v[24:27]
	v_mfma_f32_16x16x32_bf16 v[16:19], v[168:171], v[204:207], v[16:19]
	v_mfma_f32_16x16x32_bf16 v[8:11], v[176:179], v[204:207], v[8:11]
	v_mfma_f32_16x16x32_bf16 v[4:7], v[168:171], v[212:215], v[4:7]
	v_mfma_f32_16x16x32_bf16 v[0:3], v[176:179], v[212:215], v[0:3]
	s_add_i32 s54, s54, 2
	s_add_u32 s38, s38, 0x100
	s_addc_u32 s39, s39, 0
	s_add_u32 s52, s52, 0x100
	s_addc_u32 s53, s53, 0
	s_cmp_gt_u32 s54, 13
	s_barrier
	s_cbranch_scc0 .LBB0_1355
	s_and_b64 vcc, exec, s[16:17]
	s_cbranch_vccz .LBB0_1358
	s_barrier

; #define PG8_STAGE(bufoff, gbase, voff) do { _Pragma("unroll") for (int _i = 0; _i < 2; ++_i) \
;         __builtin_amdgcn_global_load_lds((const unsigned*)((const char*)(gbase) + (voff)[_i]), (LAS unsigned*)(lds + (bufoff) + ldsw + _i * 8192), 16, 0, 0); } while (0)
; #define PG8_LDA(dst, b, h) do { _Pragma("unroll") for (int m = 0; m < 4; ++m) _Pragma("unroll") for (int k = 0; k < 2; ++k) dst[m][k] = *(const LAS bf16x8*)(lds + PG8_SA(b, h) + aoff + m * 2048 + k * 1024); } while (0)
; #define PG8_LDB(dst, b, h) do { _Pragma("unroll") for (int n = 0; n < 2; ++n) _Pragma("unroll") for (int k = 0; k < 2; ++k) dst[n][k] = *(const LAS bf16x8*)(lds + PG8_SB(b, h) + boff + n * 2048 + k * 1024); } while (0)
; #define PG8_MMA(ai, bj, At, Bt) do { __builtin_amdgcn_s_setprio(1); _Pragma("unroll") for (int m = 0; m < 4; ++m) _Pragma("unroll") for (int n = 0; n < 2; ++n) _Pragma("unroll") for (int k = 0; k < 2; ++k) \
;         acc[ai][bj][m][n] = __builtin_amdgcn_mfma_f32_16x16x32_bf16(Bt[n][k], At[m][k], acc[ai][bj][m][n], 0, 0, 0); __builtin_amdgcn_s_setprio(0); } while (0)
; #define PG8_BAR __builtin_amdgcn_s_barrier()
; template <class Epi>
; __device__ __forceinline__ void gemm_phase(LAS unsigned char* lds, const Gemm g, const Sched& S, const Epi& E) {
;     ...
;         const bool has_next = S.next(ui + 1, nxt);
;         const char* nA = has_next ? (const char*)g.A + (size_t)S.aoff(nxt) * 2 : cA; const char* nB = has_next ? (const char*)g.Bt + (size_t)S.boff(nxt) * 2 : cB;
;         _Pragma("nounroll")
;         for (int t = 0; t < nt; t += 2) {
;             const bool last = (t == nt - 2);
;             const char* a1 = cA + (size_t)(t + 1) * kstep;
;             const char* a2 = last ? nA : cA + (size_t)(t + 2) * kstep; const char* b2 = last ? nB : cB + (size_t)(t + 2) * kstep;
;             const char* a3 = a2 + kstep; const char* b3 = b2 + kstep;
;             PG8_LDB(B0, 0, 0); PG8_LDB(B1, 0, 1); PG8_SCHED; PG8_LDA(At, 0, 0); PG8_STAGE(PG8_SA(1, 1), a1 + hstepA, voffA);
;             PG8_WAIT_V(8); PG8_WAIT_L(0); PG8_BAR; PG8_MMA(0, 0, At, B0); PG8_MMA(0, 1, At, B1); PG8_BAR; PG8_SCHED;
;             PG8_LDA(At, 0, 1); PG8_STAGE(PG8_SB(0, 0), b2, voffB); PG8_STAGE(PG8_SB(0, 1), b2 + hstepB, voffB); PG8_STAGE(PG8_SA(0, 0), a2, voffA);
;             PG8_WAIT_V(8); PG8_WAIT_L(0); PG8_BAR; PG8_MMA(1, 0, At, B0); PG8_MMA(1, 1, At, B1); PG8_BAR; PG8_SCHED;
.LBB0_1381:
	s_add_u32 s52, s18, s46
	s_addc_u32 s53, s19, s47
	s_add_u32 s50, s52, 0x100
	s_addc_u32 s51, s53, 0
	s_and_b64 s[48:49], s[44:45], exec
	s_cselect_b32 s49, s29, s51
	s_cselect_b32 s48, s70, s50
	s_add_u32 s46, s20, s46
	s_addc_u32 s47, s21, s47
	s_add_u32 s46, s46, 0x100
	s_addc_u32 s47, s47, 0
	s_and_b64 s[44:45], s[44:45], exec
	s_cselect_b32 s51, s39, s47
	s_cselect_b32 s50, s38, s46
	s_add_u32 s54, s52, 0x40080
	s_addc_u32 s55, s53, 0
	s_add_i32 s78, s66, s57
	s_add_i32 m0, s17, 0xc000
	s_add_i32 s81, s17, 0xe000
	s_add_i32 s75, s78, 0x2000
	v_add_u32_e32 v142, s66, v140
	s_add_u32 s52, s50, 0x40000
	ds_read_b128 v[146:149], v142
	ds_read_b128 v[150:153], v142 offset:1024
	ds_read_b128 v[154:157], v142 offset:2048
	ds_read_b128 v[158:161], v142 offset:3072
	v_add_u32_e32 v142, s67, v140
	s_addc_u32 s53, s51, 0
	s_add_i32 s77, s67, s57
	ds_read_b128 v[162:165], v142
	ds_read_b128 v[166:169], v142 offset:1024
	ds_read_b128 v[170:173], v142 offset:2048
	ds_read_b128 v[174:177], v142 offset:3072
	s_add_i32 s76, s77, 0x2000
	s_add_i32 s74, 0, 0x18000
	s_add_i32 s73, 0, 0x1c000
	s_add_u32 s46, s48, 0x40000
	s_addc_u32 s47, s49, 0
	s_add_i32 s72, s74, s57
	s_add_i32 s71, s72, 0x2000
	s_add_u32 s44, s50, 0x40080
	s_addc_u32 s45, s51, 0
	s_add_i32 s80, s73, s57
	s_add_i32 s79, s80, 0x2000
	v_lshl_add_u64 v[142:143], s[54:55], 0, v[128:129]
	ds_read_b128 v[178:181], v141
	ds_read_b128 v[182:185], v141 offset:1024
	ds_read_b128 v[186:189], v141 offset:2048
	ds_read_b128 v[190:193], v141 offset:3072
	ds_read_b128 v[194:197], v141 offset:4096
	ds_read_b128 v[198:201], v141 offset:5120
	ds_read_b128 v[204:207], v141 offset:6144
	ds_read_b128 v[208:211], v141 offset:7168
	global_load_lds_dwordx4 v[142:143], off
	v_lshl_add_u64 v[142:143], s[54:55], 0, v[132:133]
	s_mov_b32 m0, s81
	s_nop 0
	global_load_lds_dwordx4 v[142:143], off
	s_waitcnt vmcnt(8)
	s_waitcnt lgkmcnt(0)
	s_barrier
	s_waitcnt lgkmcnt(0)
	v_mfma_f32_16x16x32_bf16 v[124:127], v[146:149], v[178:181], v[124:127]
	v_mfma_f32_16x16x32_bf16 v[120:123], v[154:157], v[178:181], v[120:123]
	v_mfma_f32_16x16x32_bf16 v[112:115], v[146:149], v[186:189], v[112:115]
	v_mfma_f32_16x16x32_bf16 v[108:111], v[154:157], v[186:189], v[108:111]
	v_mfma_f32_16x16x32_bf16 v[100:103], v[146:149], v[194:197], v[100:103]
	v_mfma_f32_16x16x32_bf16 v[92:95], v[154:157], v[194:197], v[92:95]
	v_mfma_f32_16x16x32_bf16 v[84:87], v[146:149], v[204:207], v[84:87]
	v_mfma_f32_16x16x32_bf16 v[76:79], v[154:157], v[204:207], v[76:79]
	v_mfma_f32_16x16x32_bf16 v[124:127], v[150:153], v[182:185], v[124:127]
	v_mfma_f32_16x16x32_bf16 v[120:123], v[158:161], v[182:185], v[120:123]
	v_mfma_f32_16x16x32_bf16 v[112:115], v[150:153], v[190:193], v[112:115]
	v_mfma_f32_16x16x32_bf16 v[108:111], v[158:161], v[190:193], v[108:111]
	v_mfma_f32_16x16x32_bf16 v[100:103], v[150:153], v[198:201], v[100:103]
	v_mfma_f32_16x16x32_bf16 v[92:95], v[158:161], v[198:201], v[92:95]
	v_mfma_f32_16x16x32_bf16 v[84:87], v[150:153], v[208:211], v[84:87]
	v_mfma_f32_16x16x32_bf16 v[76:79], v[158:161], v[208:211], v[76:79]
	v_mfma_f32_16x16x32_bf16 v[116:119], v[162:165], v[178:181], v[116:119]
	v_mfma_f32_16x16x32_bf16 v[104:107], v[170:173], v[178:181], v[104:107]
	v_mfma_f32_16x16x32_bf16 v[96:99], v[162:165], v[186:189], v[96:99]
	v_mfma_f32_16x16x32_bf16 v[88:91], v[170:173], v[186:189], v[88:91]
	v_mfma_f32_16x16x32_bf16 v[80:83], v[162:165], v[194:197], v[80:83]
	v_mfma_f32_16x16x32_bf16 v[72:75], v[170:173], v[194:197], v[72:75]
	v_mfma_f32_16x16x32_bf16 v[68:71], v[162:165], v[204:207], v[68:71]
	v_mfma_f32_16x16x32_bf16 v[64:67], v[170:173], v[204:207], v[64:67]
	v_mfma_f32_16x16x32_bf16 v[116:119], v[166:169], v[182:185], v[116:119]
	v_mfma_f32_16x16x32_bf16 v[104:107], v[174:177], v[182:185], v[104:107]
	v_mfma_f32_16x16x32_bf16 v[96:99], v[166:169], v[190:193], v[96:99]
	v_mfma_f32_16x16x32_bf16 v[88:91], v[174:177], v[190:193], v[88:91]
	v_mfma_f32_16x16x32_bf16 v[80:83], v[166:169], v[198:201], v[80:83]
	v_mfma_f32_16x16x32_bf16 v[72:75], v[174:177], v[198:201], v[72:75]
	v_mfma_f32_16x16x32_bf16 v[68:71], v[166:169], v[208:211], v[68:71]
	v_mfma_f32_16x16x32_bf16 v[64:67], v[174:177], v[208:211], v[64:67]
	s_barrier
	s_mov_b32 m0, s78
	v_lshl_add_u64 v[142:143], s[50:51], 0, v[130:131]
	ds_read_b128 v[178:181], v141 offset:16384
	ds_read_b128 v[182:185], v141 offset:17408
	ds_read_b128 v[186:189], v141 offset:18432
	ds_read_b128 v[190:193], v141 offset:19456
	ds_read_b128 v[194:197], v141 offset:20480
	ds_read_b128 v[198:201], v141 offset:21504
	ds_read_b128 v[204:207], v141 offset:22528
	ds_read_b128 v[208:211], v141 offset:23552
	global_load_lds_dwordx4 v[142:143], off
	v_lshl_add_u64 v[212:213], s[50:51], 0, v[134:135]
	s_mov_b32 m0, s75
	v_lshl_add_u64 v[214:215], s[52:53], 0, v[130:131]
	global_load_lds_dwordx4 v[212:213], off
	s_mov_b32 m0, s77
	v_lshl_add_u64 v[216:217], s[48:49], 0, v[132:133]
	global_load_lds_dwordx4 v[214:215], off
	v_lshl_add_u64 v[214:215], s[52:53], 0, v[134:135]
	s_mov_b32 m0, s76
	s_nop 0
	global_load_lds_dwordx4 v[214:215], off
	v_lshl_add_u64 v[214:215], s[48:49], 0, v[128:129]
	s_mov_b32 m0, s17
	s_nop 0
	global_load_lds_dwordx4 v[214:215], off
	s_mov_b32 m0, s60
	s_nop 0
	global_load_lds_dwordx4 v[216:217], off
	s_waitcnt vmcnt(8)
	s_waitcnt lgkmcnt(0)
	s_barrier
; #define PG8_STAGE(bufoff, gbase, voff) do { _Pragma("unroll") for (int _i = 0; _i < 2; ++_i) \
;         __builtin_amdgcn_global_load_lds((const unsigned*)((const char*)(gbase) + (voff)[_i]), (LAS unsigned*)(lds + (bufoff) + ldsw + _i * 8192), 16, 0, 0); } while (0)
; #define PG8_LDA(dst, b, h) do { _Pragma("unroll") for (int m = 0; m < 4; ++m) _Pragma("unroll") for (int k = 0; k < 2; ++k) dst[m][k] = *(const LAS bf16x8*)(lds + PG8_SA(b, h) + aoff + m * 2048 + k * 1024); } while (0)
; #define PG8_LDB(dst, b, h) do { _Pragma("unroll") for (int n = 0; n < 2; ++n) _Pragma("unroll") for (int k = 0; k < 2; ++k) dst[n][k] = *(const LAS bf16x8*)(lds + PG8_SB(b, h) + boff + n * 2048 + k * 1024); } while (0)
; #define PG8_MMA(ai, bj, At, Bt) do { __builtin_amdgcn_s_setprio(1); _Pragma("unroll") for (int m = 0; m < 4; ++m) _Pragma("unroll") for (int n = 0; n < 2; ++n) _Pragma("unroll") for (int k = 0; k < 2; ++k) \
;         acc[ai][bj][m][n] = __builtin_amdgcn_mfma_f32_16x16x32_bf16(Bt[n][k], At[m][k], acc[ai][bj][m][n], 0, 0, 0); __builtin_amdgcn_s_setprio(0); } while (0)
; #define PG8_WAIT_V(n) asm volatile("s_waitcnt vmcnt(" #n ")" ::: "memory")
; #define PG8_WAIT_L(n) asm volatile("s_waitcnt lgkmcnt(" #n ")" ::: "memory")
; #define PG8_BAR __builtin_amdgcn_s_barrier()
; #define PG8_SCHED __builtin_amdgcn_sched_barrier(0)
; template <class Epi>
; __device__ __forceinline__ void gemm_phase(LAS unsigned char* lds, const Gemm g, const Sched& S, const Epi& E) {
;     ...
;             PG8_WAIT_V(8); PG8_WAIT_L(0); PG8_BAR; PG8_MMA(1, 0, At, B0); PG8_MMA(1, 1, At, B1); PG8_BAR; PG8_SCHED;
;             PG8_LDB(B0, 1, 0); PG8_LDB(B1, 1, 1); PG8_SCHED; PG8_LDA(At, 1, 0); PG8_STAGE(PG8_SA(0, 1), a2 + hstepA, voffA);
;             PG8_WAIT_V(8); PG8_WAIT_L(0); PG8_BAR; PG8_MMA(0, 0, At, B0); PG8_MMA(0, 1, At, B1); PG8_BAR; PG8_SCHED;
	s_waitcnt lgkmcnt(0)
	v_mfma_f32_16x16x32_bf16 v[60:63], v[146:149], v[178:181], v[60:63]
	v_mfma_f32_16x16x32_bf16 v[56:59], v[154:157], v[178:181], v[56:59]
	v_mfma_f32_16x16x32_bf16 v[52:55], v[146:149], v[186:189], v[52:55]
	v_mfma_f32_16x16x32_bf16 v[44:47], v[154:157], v[186:189], v[44:47]
	v_mfma_f32_16x16x32_bf16 v[36:39], v[146:149], v[194:197], v[36:39]
	v_mfma_f32_16x16x32_bf16 v[28:31], v[154:157], v[194:197], v[28:31]
	v_mfma_f32_16x16x32_bf16 v[20:23], v[146:149], v[204:207], v[20:23]
	v_mfma_f32_16x16x32_bf16 v[12:15], v[154:157], v[204:207], v[12:15]
	v_mfma_f32_16x16x32_bf16 v[60:63], v[150:153], v[182:185], v[60:63]
	v_mfma_f32_16x16x32_bf16 v[56:59], v[158:161], v[182:185], v[56:59]
	v_mfma_f32_16x16x32_bf16 v[52:55], v[150:153], v[190:193], v[52:55]
	v_mfma_f32_16x16x32_bf16 v[44:47], v[158:161], v[190:193], v[44:47]
	v_mfma_f32_16x16x32_bf16 v[36:39], v[150:153], v[198:201], v[36:39]
	v_mfma_f32_16x16x32_bf16 v[28:31], v[158:161], v[198:201], v[28:31]
	v_mfma_f32_16x16x32_bf16 v[20:23], v[150:153], v[208:211], v[20:23]
	v_mfma_f32_16x16x32_bf16 v[12:15], v[158:161], v[208:211], v[12:15]
	v_mfma_f32_16x16x32_bf16 v[48:51], v[162:165], v[178:181], v[48:51]
	v_mfma_f32_16x16x32_bf16 v[40:43], v[170:173], v[178:181], v[40:43]
	v_mfma_f32_16x16x32_bf16 v[32:35], v[162:165], v[186:189], v[32:35]
	v_mfma_f32_16x16x32_bf16 v[24:27], v[170:173], v[186:189], v[24:27]
	v_mfma_f32_16x16x32_bf16 v[16:19], v[162:165], v[194:197], v[16:19]
	v_mfma_f32_16x16x32_bf16 v[8:11], v[170:173], v[194:197], v[8:11]
	v_mfma_f32_16x16x32_bf16 v[4:7], v[162:165], v[204:207], v[4:7]
	v_mfma_f32_16x16x32_bf16 v[0:3], v[170:173], v[204:207], v[0:3]
	v_mfma_f32_16x16x32_bf16 v[48:51], v[166:169], v[182:185], v[48:51]
	v_mfma_f32_16x16x32_bf16 v[40:43], v[174:177], v[182:185], v[40:43]
	v_mfma_f32_16x16x32_bf16 v[32:35], v[166:169], v[190:193], v[32:35]
	v_mfma_f32_16x16x32_bf16 v[24:27], v[174:177], v[190:193], v[24:27]
	v_mfma_f32_16x16x32_bf16 v[16:19], v[166:169], v[198:201], v[16:19]
	v_mfma_f32_16x16x32_bf16 v[8:11], v[174:177], v[198:201], v[8:11]
	v_mfma_f32_16x16x32_bf16 v[4:7], v[166:169], v[208:211], v[4:7]
	v_mfma_f32_16x16x32_bf16 v[0:3], v[174:177], v[208:211], v[0:3]
	s_barrier
	v_add_u32_e32 v145, s74, v140
	ds_read_b128 v[146:149], v145
	ds_read_b128 v[150:153], v145 offset:1024
	ds_read_b128 v[154:157], v145 offset:2048
	ds_read_b128 v[158:161], v145 offset:3072
	v_add_u32_e32 v145, s73, v140
	ds_read_b128 v[162:165], v145
	ds_read_b128 v[166:169], v145 offset:1024
	ds_read_b128 v[170:173], v145 offset:2048
	ds_read_b128 v[174:177], v145 offset:3072
	s_mov_b32 m0, s61
	v_lshl_add_u64 v[218:219], s[46:47], 0, v[128:129]
	ds_read_b128 v[178:181], v141 offset:32768
	ds_read_b128 v[182:185], v141 offset:33792
	ds_read_b128 v[186:189], v141 offset:34816
	ds_read_b128 v[190:193], v141 offset:35840
	ds_read_b128 v[194:197], v141 offset:36864
	ds_read_b128 v[198:201], v141 offset:37888
	ds_read_b128 v[204:207], v141 offset:38912
	ds_read_b128 v[208:211], v141 offset:39936
	global_load_lds_dwordx4 v[218:219], off
	v_lshl_add_u64 v[218:219], s[46:47], 0, v[132:133]
	s_mov_b32 m0, s62
	s_nop 0
	global_load_lds_dwordx4 v[218:219], off
	s_waitcnt vmcnt(8)
	s_waitcnt lgkmcnt(0)
	s_barrier
	s_waitcnt lgkmcnt(0)
	v_mfma_f32_16x16x32_bf16 v[124:127], v[146:149], v[178:181], v[124:127]
	v_mfma_f32_16x16x32_bf16 v[120:123], v[154:157], v[178:181], v[120:123]
	v_mfma_f32_16x16x32_bf16 v[112:115], v[146:149], v[186:189], v[112:115]
	v_mfma_f32_16x16x32_bf16 v[108:111], v[154:157], v[186:189], v[108:111]
	v_mfma_f32_16x16x32_bf16 v[100:103], v[146:149], v[194:197], v[100:103]
	v_mfma_f32_16x16x32_bf16 v[92:95], v[154:157], v[194:197], v[92:95]
	v_mfma_f32_16x16x32_bf16 v[84:87], v[146:149], v[204:207], v[84:87]
	v_mfma_f32_16x16x32_bf16 v[76:79], v[154:157], v[204:207], v[76:79]
	v_mfma_f32_16x16x32_bf16 v[124:127], v[150:153], v[182:185], v[124:127]
	v_mfma_f32_16x16x32_bf16 v[120:123], v[158:161], v[182:185], v[120:123]
	v_mfma_f32_16x16x32_bf16 v[112:115], v[150:153], v[190:193], v[112:115]
	v_mfma_f32_16x16x32_bf16 v[108:111], v[158:161], v[190:193], v[108:111]
	v_mfma_f32_16x16x32_bf16 v[100:103], v[150:153], v[198:201], v[100:103]
	v_mfma_f32_16x16x32_bf16 v[92:95], v[158:161], v[198:201], v[92:95]
	v_mfma_f32_16x16x32_bf16 v[84:87], v[150:153], v[208:211], v[84:87]
	v_mfma_f32_16x16x32_bf16 v[76:79], v[158:161], v[208:211], v[76:79]
	v_mfma_f32_16x16x32_bf16 v[116:119], v[162:165], v[178:181], v[116:119]
	v_mfma_f32_16x16x32_bf16 v[104:107], v[170:173], v[178:181], v[104:107]
	v_mfma_f32_16x16x32_bf16 v[96:99], v[162:165], v[186:189], v[96:99]
	v_mfma_f32_16x16x32_bf16 v[88:91], v[170:173], v[186:189], v[88:91]
	v_mfma_f32_16x16x32_bf16 v[80:83], v[162:165], v[194:197], v[80:83]
	v_mfma_f32_16x16x32_bf16 v[72:75], v[170:173], v[194:197], v[72:75]
	v_mfma_f32_16x16x32_bf16 v[68:71], v[162:165], v[204:207], v[68:71]
	v_mfma_f32_16x16x32_bf16 v[64:67], v[170:173], v[204:207], v[64:67]
	v_mfma_f32_16x16x32_bf16 v[116:119], v[166:169], v[182:185], v[116:119]
	v_mfma_f32_16x16x32_bf16 v[104:107], v[174:177], v[182:185], v[104:107]
	v_mfma_f32_16x16x32_bf16 v[96:99], v[166:169], v[190:193], v[96:99]
	v_mfma_f32_16x16x32_bf16 v[88:91], v[174:177], v[190:193], v[88:91]
	v_mfma_f32_16x16x32_bf16 v[80:83], v[166:169], v[198:201], v[80:83]
	v_mfma_f32_16x16x32_bf16 v[72:75], v[174:177], v[198:201], v[72:75]
	v_mfma_f32_16x16x32_bf16 v[68:71], v[166:169], v[208:211], v[68:71]
	v_mfma_f32_16x16x32_bf16 v[64:67], v[174:177], v[208:211], v[64:67]
	s_barrier
; #define PG8_STAGE(bufoff, gbase, voff) do { _Pragma("unroll") for (int _i = 0; _i < 2; ++_i) \
;         __builtin_amdgcn_global_load_lds((const unsigned*)((const char*)(gbase) + (voff)[_i]), (LAS unsigned*)(lds + (bufoff) + ldsw + _i * 8192), 16, 0, 0); } while (0)
; #define PG8_LDA(dst, b, h) do { _Pragma("unroll") for (int m = 0; m < 4; ++m) _Pragma("unroll") for (int k = 0; k < 2; ++k) dst[m][k] = *(const LAS bf16x8*)(lds + PG8_SA(b, h) + aoff + m * 2048 + k * 1024); } while (0)
; #define PG8_MMA(ai, bj, At, Bt) do { __builtin_amdgcn_s_setprio(1); _Pragma("unroll") for (int m = 0; m < 4; ++m) _Pragma("unroll") for (int n = 0; n < 2; ++n) _Pragma("unroll") for (int k = 0; k < 2; ++k) \
;         acc[ai][bj][m][n] = __builtin_amdgcn_mfma_f32_16x16x32_bf16(Bt[n][k], At[m][k], acc[ai][bj][m][n], 0, 0, 0); __builtin_amdgcn_s_setprio(0); } while (0)
; #define PG8_WAIT_V(n) asm volatile("s_waitcnt vmcnt(" #n ")" ::: "memory")
; #define PG8_WAIT_L(n) asm volatile("s_waitcnt lgkmcnt(" #n ")" ::: "memory")
; #define PG8_BAR __builtin_amdgcn_s_barrier()
; #define PG8_SCHED __builtin_amdgcn_sched_barrier(0)
; template <class Epi>
; __device__ __forceinline__ void gemm_phase(LAS unsigned char* lds, const Gemm g, const Sched& S, const Epi& E) {
;     ...
;             PG8_LDA(At, 1, 1); PG8_STAGE(PG8_SB(1, 0), b3, voffB); PG8_STAGE(PG8_SB(1, 1), b3 + hstepB, voffB); PG8_STAGE(PG8_SA(1, 0), a3, voffA);
;             PG8_WAIT_V(8); PG8_WAIT_L(0); PG8_BAR; PG8_MMA(1, 0, At, B0); PG8_MMA(1, 1, At, B1); PG8_BAR; PG8_SCHED;
;         }
;         if (wr == 0) PG8_BAR;
;         if constexpr (!Epi::AFTER_DRAIN) { E(acc, cur, wr, wc, fr, fq); }
;         if (!has_next) break;
; #pragma unroll
;         for (int a = 0; a < 2; ++a)
; #pragma unroll
;             for (int b = 0; b < 2; ++b)
; #pragma unroll
;                 for (int m = 0; m < 4; ++m)
; #pragma unroll
;                     for (int n = 0; n < 2; ++n) acc[a][b][m][n] = (f32x4){0.f, 0.f, 0.f, 0.f};
;         cur = nxt; cA = nA; cB = nB; ++ui;
;         if (wr == 1) PG8_BAR;
	s_mov_b32 m0, s72
	v_lshl_add_u64 v[142:143], v[142:143], 0, s[24:25]
	ds_read_b128 v[178:181], v141 offset:49152
	ds_read_b128 v[182:185], v141 offset:50176
	ds_read_b128 v[186:189], v141 offset:51200
	ds_read_b128 v[190:193], v141 offset:52224
	ds_read_b128 v[194:197], v141 offset:53248
	ds_read_b128 v[198:201], v141 offset:54272
	ds_read_b128 v[204:207], v141 offset:55296
	ds_read_b128 v[208:211], v141 offset:56320
	global_load_lds_dwordx4 v[142:143], off
	v_lshl_add_u64 v[142:143], v[212:213], 0, s[24:25]
	s_mov_b32 m0, s71
	s_nop 0
	global_load_lds_dwordx4 v[142:143], off
	v_lshl_add_u64 v[142:143], s[44:45], 0, v[130:131]
	s_mov_b32 m0, s80
	s_nop 0
	global_load_lds_dwordx4 v[142:143], off
	v_lshl_add_u64 v[142:143], s[44:45], 0, v[134:135]
	s_mov_b32 m0, s79
	s_nop 0
	global_load_lds_dwordx4 v[142:143], off
	v_lshl_add_u64 v[142:143], v[214:215], 0, s[24:25]
	s_mov_b32 m0, s64
	s_nop 0
	global_load_lds_dwordx4 v[142:143], off
	v_lshl_add_u64 v[142:143], v[216:217], 0, s[24:25]
	s_mov_b32 m0, s65
	s_nop 0
	global_load_lds_dwordx4 v[142:143], off
	s_waitcnt vmcnt(8)
	s_waitcnt lgkmcnt(0)
	s_barrier
	s_waitcnt lgkmcnt(0)
	v_mfma_f32_16x16x32_bf16 v[60:63], v[146:149], v[178:181], v[60:63]
	v_mfma_f32_16x16x32_bf16 v[56:59], v[154:157], v[178:181], v[56:59]
	v_mfma_f32_16x16x32_bf16 v[52:55], v[146:149], v[186:189], v[52:55]
	v_mfma_f32_16x16x32_bf16 v[44:47], v[154:157], v[186:189], v[44:47]
	v_mfma_f32_16x16x32_bf16 v[36:39], v[146:149], v[194:197], v[36:39]
	v_mfma_f32_16x16x32_bf16 v[28:31], v[154:157], v[194:197], v[28:31]
	v_mfma_f32_16x16x32_bf16 v[20:23], v[146:149], v[204:207], v[20:23]
	v_mfma_f32_16x16x32_bf16 v[12:15], v[154:157], v[204:207], v[12:15]
	v_mfma_f32_16x16x32_bf16 v[60:63], v[150:153], v[182:185], v[60:63]
	v_mfma_f32_16x16x32_bf16 v[56:59], v[158:161], v[182:185], v[56:59]
	v_mfma_f32_16x16x32_bf16 v[52:55], v[150:153], v[190:193], v[52:55]
	v_mfma_f32_16x16x32_bf16 v[44:47], v[158:161], v[190:193], v[44:47]
	v_mfma_f32_16x16x32_bf16 v[36:39], v[150:153], v[198:201], v[36:39]
	v_mfma_f32_16x16x32_bf16 v[28:31], v[158:161], v[198:201], v[28:31]
	v_mfma_f32_16x16x32_bf16 v[20:23], v[150:153], v[208:211], v[20:23]
	v_mfma_f32_16x16x32_bf16 v[12:15], v[158:161], v[208:211], v[12:15]
	v_mfma_f32_16x16x32_bf16 v[48:51], v[162:165], v[178:181], v[48:51]
	v_mfma_f32_16x16x32_bf16 v[40:43], v[170:173], v[178:181], v[40:43]
	v_mfma_f32_16x16x32_bf16 v[32:35], v[162:165], v[186:189], v[32:35]
	v_mfma_f32_16x16x32_bf16 v[24:27], v[170:173], v[186:189], v[24:27]
	v_mfma_f32_16x16x32_bf16 v[16:19], v[162:165], v[194:197], v[16:19]
	v_mfma_f32_16x16x32_bf16 v[8:11], v[170:173], v[194:197], v[8:11]
	v_mfma_f32_16x16x32_bf16 v[4:7], v[162:165], v[204:207], v[4:7]
	v_mfma_f32_16x16x32_bf16 v[0:3], v[170:173], v[204:207], v[0:3]
	v_mfma_f32_16x16x32_bf16 v[48:51], v[166:169], v[182:185], v[48:51]
	v_mfma_f32_16x16x32_bf16 v[40:43], v[174:177], v[182:185], v[40:43]
	v_mfma_f32_16x16x32_bf16 v[32:35], v[166:169], v[190:193], v[32:35]
	v_mfma_f32_16x16x32_bf16 v[24:27], v[174:177], v[190:193], v[24:27]
	v_mfma_f32_16x16x32_bf16 v[16:19], v[166:169], v[198:201], v[16:19]
	v_mfma_f32_16x16x32_bf16 v[8:11], v[174:177], v[198:201], v[8:11]
	v_mfma_f32_16x16x32_bf16 v[4:7], v[166:169], v[208:211], v[4:7]
	v_mfma_f32_16x16x32_bf16 v[0:3], v[174:177], v[208:211], v[0:3]
	s_andn2_b64 vcc, exec, s[42:43]
	s_mov_b64 s[44:45], -1
	s_mov_b64 s[42:43], 0
	s_mov_b64 s[46:47], 0x100
	s_barrier
	s_cbranch_vccz .LBB0_1381
	s_and_b64 vcc, exec, s[26:27]
	s_cbranch_vccnz .LBB0_1384
	s_and_b64 vcc, exec, s[4:5]
	s_mov_b32 s81, s12
	s_cbranch_vccnz .LBB0_1371
	s_branch .LBB0_1385

; #define PG8_STAGE(bufoff, gbase, voff) do { _Pragma("unroll") for (int _i = 0; _i < 2; ++_i) \
;         __builtin_amdgcn_global_load_lds((const unsigned*)((const char*)(gbase) + (voff)[_i]), (LAS unsigned*)(lds + (bufoff) + ldsw + _i * 8192), 16, 0, 0); } while (0)
; #define PG8_LDA(dst, b, h) do { _Pragma("unroll") for (int m = 0; m < 4; ++m) _Pragma("unroll") for (int k = 0; k < 2; ++k) dst[m][k] = *(const LAS bf16x8*)(lds + PG8_SA(b, h) + aoff + m * 2048 + k * 1024); } while (0)
; #define PG8_LDB(dst, b, h) do { _Pragma("unroll") for (int n = 0; n < 2; ++n) _Pragma("unroll") for (int k = 0; k < 2; ++k) dst[n][k] = *(const LAS bf16x8*)(lds + PG8_SB(b, h) + boff + n * 2048 + k * 1024); } while (0)
; #define PG8_MMA(ai, bj, At, Bt) do { __builtin_amdgcn_s_setprio(1); _Pragma("unroll") for (int m = 0; m < 4; ++m) _Pragma("unroll") for (int n = 0; n < 2; ++n) _Pragma("unroll") for (int k = 0; k < 2; ++k) \
;         acc[ai][bj][m][n] = __builtin_amdgcn_mfma_f32_16x16x32_bf16(Bt[n][k], At[m][k], acc[ai][bj][m][n], 0, 0, 0); __builtin_amdgcn_s_setprio(0); } while (0)
; #define PG8_BAR __builtin_amdgcn_s_barrier()
; template <class Epi>
; __device__ __forceinline__ void gemm_phase(LAS unsigned char* lds, const Gemm g, const Sched& S, const Epi& E) {
;     ...
;         const bool has_next = S.next(ui + 1, nxt);
;         const char* nA = has_next ? (const char*)g.A + (size_t)S.aoff(nxt) * 2 : cA; const char* nB = has_next ? (const char*)g.Bt + (size_t)S.boff(nxt) * 2 : cB;
;         _Pragma("nounroll")
;         for (int t = 0; t < nt; t += 2) {
;             const bool last = (t == nt - 2);
;             const char* a1 = cA + (size_t)(t + 1) * kstep;
;             const char* a2 = last ? nA : cA + (size_t)(t + 2) * kstep; const char* b2 = last ? nB : cB + (size_t)(t + 2) * kstep;
;             const char* a3 = a2 + kstep; const char* b3 = b2 + kstep;
;             PG8_LDB(B0, 0, 0); PG8_LDB(B1, 0, 1); PG8_SCHED; PG8_LDA(At, 0, 0); PG8_STAGE(PG8_SA(1, 1), a1 + hstepA, voffA);
;             PG8_WAIT_V(8); PG8_WAIT_L(0); PG8_BAR; PG8_MMA(0, 0, At, B0); PG8_MMA(0, 1, At, B1); PG8_BAR; PG8_SCHED;
;             PG8_LDA(At, 0, 1); PG8_STAGE(PG8_SB(0, 0), b2, voffB); PG8_STAGE(PG8_SB(0, 1), b2 + hstepB, voffB); PG8_STAGE(PG8_SA(0, 0), a2, voffA);
;             PG8_WAIT_V(8); PG8_WAIT_L(0); PG8_BAR; PG8_MMA(1, 0, At, B0); PG8_MMA(1, 1, At, B1); PG8_BAR; PG8_SCHED;
.LBB0_1439:
	s_add_u32 s47, s28, s46
	s_addc_u32 s52, s29, 0
	s_add_u32 s50, s47, 0x100
	s_addc_u32 s51, s52, 0
	s_and_b64 s[48:49], s[44:45], exec
	s_cselect_b32 s49, s23, s51
	s_cselect_b32 s48, s25, s50
	s_add_u32 s46, s36, s46
	s_addc_u32 s50, s37, 0
	s_add_u32 s46, s46, 0x100
	s_addc_u32 s50, s50, 0
	s_and_b64 s[44:45], s[44:45], exec
	s_cselect_b32 s51, s39, s50
	s_cselect_b32 s50, s38, s46
	s_add_u32 s54, s47, 0x40080
	ds_read_b128 v[146:149], v139
	ds_read_b128 v[150:153], v139 offset:1024
	ds_read_b128 v[154:157], v139 offset:2048
	ds_read_b128 v[158:161], v139 offset:3072
	ds_read_b128 v[162:165], v140
	ds_read_b128 v[166:169], v140 offset:1024
	ds_read_b128 v[170:173], v140 offset:2048
	ds_read_b128 v[174:177], v140 offset:3072
	s_addc_u32 s55, s52, 0
	s_add_i32 s72, s62, s10
	s_add_i32 m0, s27, 0xc000
	s_add_i32 s75, s27, 0xe000
	s_add_i32 s69, s72, 0x2000
	s_add_u32 s52, s50, 0x80000
	s_addc_u32 s53, s51, 0
	s_add_i32 s71, s63, s10
	s_add_i32 s70, s71, 0x2000
	s_add_i32 s68, 0, 0x18000
	s_add_i32 s67, 0, 0x1c000
	s_add_u32 s46, s48, 0x40000
	s_addc_u32 s47, s49, 0
	s_add_i32 s66, s68, s10
	s_add_i32 s65, s66, 0x2000
	s_add_u32 s44, s50, 0x80080
	s_addc_u32 s45, s51, 0
	s_add_i32 s74, s67, s10
	s_add_i32 s73, s74, 0x2000
	v_lshl_add_u64 v[142:143], s[54:55], 0, v[128:129]
	ds_read_b128 v[178:181], v141
	ds_read_b128 v[182:185], v141 offset:1024
	ds_read_b128 v[186:189], v141 offset:2048
	ds_read_b128 v[190:193], v141 offset:3072
	ds_read_b128 v[194:197], v141 offset:4096
	ds_read_b128 v[198:201], v141 offset:5120
	ds_read_b128 v[204:207], v141 offset:6144
	ds_read_b128 v[208:211], v141 offset:7168
	global_load_lds_dwordx4 v[142:143], off
	v_lshl_add_u64 v[142:143], s[54:55], 0, v[132:133]
	s_mov_b32 m0, s75
	s_nop 0
	global_load_lds_dwordx4 v[142:143], off
	s_waitcnt vmcnt(8)
	s_waitcnt lgkmcnt(0)
	s_barrier
	s_waitcnt lgkmcnt(0)
	v_mfma_f32_16x16x32_bf16 v[124:127], v[146:149], v[178:181], v[124:127]
	v_mfma_f32_16x16x32_bf16 v[120:123], v[154:157], v[178:181], v[120:123]
	v_mfma_f32_16x16x32_bf16 v[116:119], v[146:149], v[186:189], v[116:119]
	v_mfma_f32_16x16x32_bf16 v[112:115], v[154:157], v[186:189], v[112:115]
	v_mfma_f32_16x16x32_bf16 v[100:103], v[146:149], v[194:197], v[100:103]
	v_mfma_f32_16x16x32_bf16 v[96:99], v[154:157], v[194:197], v[96:99]
	v_mfma_f32_16x16x32_bf16 v[84:87], v[146:149], v[204:207], v[84:87]
	v_mfma_f32_16x16x32_bf16 v[80:83], v[154:157], v[204:207], v[80:83]
	v_mfma_f32_16x16x32_bf16 v[124:127], v[150:153], v[182:185], v[124:127]
	v_mfma_f32_16x16x32_bf16 v[120:123], v[158:161], v[182:185], v[120:123]
	v_mfma_f32_16x16x32_bf16 v[116:119], v[150:153], v[190:193], v[116:119]
	v_mfma_f32_16x16x32_bf16 v[112:115], v[158:161], v[190:193], v[112:115]
	v_mfma_f32_16x16x32_bf16 v[100:103], v[150:153], v[198:201], v[100:103]
	v_mfma_f32_16x16x32_bf16 v[96:99], v[158:161], v[198:201], v[96:99]
	v_mfma_f32_16x16x32_bf16 v[84:87], v[150:153], v[208:211], v[84:87]
	v_mfma_f32_16x16x32_bf16 v[80:83], v[158:161], v[208:211], v[80:83]
	v_mfma_f32_16x16x32_bf16 v[108:111], v[162:165], v[178:181], v[108:111]
	v_mfma_f32_16x16x32_bf16 v[104:107], v[170:173], v[178:181], v[104:107]
	v_mfma_f32_16x16x32_bf16 v[92:95], v[162:165], v[186:189], v[92:95]
	v_mfma_f32_16x16x32_bf16 v[88:91], v[170:173], v[186:189], v[88:91]
	v_mfma_f32_16x16x32_bf16 v[76:79], v[162:165], v[194:197], v[76:79]
	v_mfma_f32_16x16x32_bf16 v[72:75], v[170:173], v[194:197], v[72:75]
	v_mfma_f32_16x16x32_bf16 v[68:71], v[162:165], v[204:207], v[68:71]
	v_mfma_f32_16x16x32_bf16 v[64:67], v[170:173], v[204:207], v[64:67]
	v_mfma_f32_16x16x32_bf16 v[108:111], v[166:169], v[182:185], v[108:111]
	v_mfma_f32_16x16x32_bf16 v[104:107], v[174:177], v[182:185], v[104:107]
	v_mfma_f32_16x16x32_bf16 v[92:95], v[166:169], v[190:193], v[92:95]
	v_mfma_f32_16x16x32_bf16 v[88:91], v[174:177], v[190:193], v[88:91]
	v_mfma_f32_16x16x32_bf16 v[76:79], v[166:169], v[198:201], v[76:79]
	v_mfma_f32_16x16x32_bf16 v[72:75], v[174:177], v[198:201], v[72:75]
	v_mfma_f32_16x16x32_bf16 v[68:71], v[166:169], v[208:211], v[68:71]
	v_mfma_f32_16x16x32_bf16 v[64:67], v[174:177], v[208:211], v[64:67]
	s_barrier
	s_mov_b32 m0, s72
	v_lshl_add_u64 v[142:143], s[50:51], 0, v[130:131]
	ds_read_b128 v[178:181], v141 offset:16384
	ds_read_b128 v[182:185], v141 offset:17408
	ds_read_b128 v[186:189], v141 offset:18432
	ds_read_b128 v[190:193], v141 offset:19456
	ds_read_b128 v[194:197], v141 offset:20480
	ds_read_b128 v[198:201], v141 offset:21504
	ds_read_b128 v[204:207], v141 offset:22528
	ds_read_b128 v[208:211], v141 offset:23552
	global_load_lds_dwordx4 v[142:143], off
	v_lshl_add_u64 v[212:213], s[50:51], 0, v[134:135]
	s_mov_b32 m0, s69
	v_lshl_add_u64 v[214:215], s[52:53], 0, v[130:131]
	global_load_lds_dwordx4 v[212:213], off
	s_mov_b32 m0, s71
	v_lshl_add_u64 v[216:217], s[48:49], 0, v[132:133]
	global_load_lds_dwordx4 v[214:215], off
	v_lshl_add_u64 v[214:215], s[52:53], 0, v[134:135]
	s_mov_b32 m0, s70
	s_nop 0
	global_load_lds_dwordx4 v[214:215], off
	v_lshl_add_u64 v[214:215], s[48:49], 0, v[128:129]
	s_mov_b32 m0, s27
	s_nop 0
	global_load_lds_dwordx4 v[214:215], off
	s_mov_b32 m0, s56
	s_nop 0
	global_load_lds_dwordx4 v[216:217], off
	s_waitcnt vmcnt(8)
	s_waitcnt lgkmcnt(0)
	s_barrier
; #define PG8_STAGE(bufoff, gbase, voff) do { _Pragma("unroll") for (int _i = 0; _i < 2; ++_i) \
;         __builtin_amdgcn_global_load_lds((const unsigned*)((const char*)(gbase) + (voff)[_i]), (LAS unsigned*)(lds + (bufoff) + ldsw + _i * 8192), 16, 0, 0); } while (0)
; #define PG8_LDA(dst, b, h) do { _Pragma("unroll") for (int m = 0; m < 4; ++m) _Pragma("unroll") for (int k = 0; k < 2; ++k) dst[m][k] = *(const LAS bf16x8*)(lds + PG8_SA(b, h) + aoff + m * 2048 + k * 1024); } while (0)
; #define PG8_LDB(dst, b, h) do { _Pragma("unroll") for (int n = 0; n < 2; ++n) _Pragma("unroll") for (int k = 0; k < 2; ++k) dst[n][k] = *(const LAS bf16x8*)(lds + PG8_SB(b, h) + boff + n * 2048 + k * 1024); } while (0)
; #define PG8_MMA(ai, bj, At, Bt) do { __builtin_amdgcn_s_setprio(1); _Pragma("unroll") for (int m = 0; m < 4; ++m) _Pragma("unroll") for (int n = 0; n < 2; ++n) _Pragma("unroll") for (int k = 0; k < 2; ++k) \
;         acc[ai][bj][m][n] = __builtin_amdgcn_mfma_f32_16x16x32_bf16(Bt[n][k], At[m][k], acc[ai][bj][m][n], 0, 0, 0); __builtin_amdgcn_s_setprio(0); } while (0)
; #define PG8_WAIT_V(n) asm volatile("s_waitcnt vmcnt(" #n ")" ::: "memory")
; #define PG8_WAIT_L(n) asm volatile("s_waitcnt lgkmcnt(" #n ")" ::: "memory")
; #define PG8_BAR __builtin_amdgcn_s_barrier()
; #define PG8_SCHED __builtin_amdgcn_sched_barrier(0)
; template <class Epi>
; __device__ __forceinline__ void gemm_phase(LAS unsigned char* lds, const Gemm g, const Sched& S, const Epi& E) {
;     ...
;             PG8_WAIT_V(8); PG8_WAIT_L(0); PG8_BAR; PG8_MMA(1, 0, At, B0); PG8_MMA(1, 1, At, B1); PG8_BAR; PG8_SCHED;
;             PG8_LDB(B0, 1, 0); PG8_LDB(B1, 1, 1); PG8_SCHED; PG8_LDA(At, 1, 0); PG8_STAGE(PG8_SA(0, 1), a2 + hstepA, voffA);
;             PG8_WAIT_V(8); PG8_WAIT_L(0); PG8_BAR; PG8_MMA(0, 0, At, B0); PG8_MMA(0, 1, At, B1); PG8_BAR; PG8_SCHED;
	s_waitcnt lgkmcnt(0)
	v_mfma_f32_16x16x32_bf16 v[60:63], v[146:149], v[178:181], v[60:63]
	v_mfma_f32_16x16x32_bf16 v[56:59], v[154:157], v[178:181], v[56:59]
	v_mfma_f32_16x16x32_bf16 v[52:55], v[146:149], v[186:189], v[52:55]
	v_mfma_f32_16x16x32_bf16 v[48:51], v[154:157], v[186:189], v[48:51]
	v_mfma_f32_16x16x32_bf16 v[36:39], v[146:149], v[194:197], v[36:39]
	v_mfma_f32_16x16x32_bf16 v[32:35], v[154:157], v[194:197], v[32:35]
	v_mfma_f32_16x16x32_bf16 v[20:23], v[146:149], v[204:207], v[20:23]
	v_mfma_f32_16x16x32_bf16 v[16:19], v[154:157], v[204:207], v[16:19]
	v_mfma_f32_16x16x32_bf16 v[60:63], v[150:153], v[182:185], v[60:63]
	v_mfma_f32_16x16x32_bf16 v[56:59], v[158:161], v[182:185], v[56:59]
	v_mfma_f32_16x16x32_bf16 v[52:55], v[150:153], v[190:193], v[52:55]
	v_mfma_f32_16x16x32_bf16 v[48:51], v[158:161], v[190:193], v[48:51]
	v_mfma_f32_16x16x32_bf16 v[36:39], v[150:153], v[198:201], v[36:39]
	v_mfma_f32_16x16x32_bf16 v[32:35], v[158:161], v[198:201], v[32:35]
	v_mfma_f32_16x16x32_bf16 v[20:23], v[150:153], v[208:211], v[20:23]
	v_mfma_f32_16x16x32_bf16 v[16:19], v[158:161], v[208:211], v[16:19]
	v_mfma_f32_16x16x32_bf16 v[44:47], v[162:165], v[178:181], v[44:47]
	v_mfma_f32_16x16x32_bf16 v[40:43], v[170:173], v[178:181], v[40:43]
	v_mfma_f32_16x16x32_bf16 v[28:31], v[162:165], v[186:189], v[28:31]
	v_mfma_f32_16x16x32_bf16 v[24:27], v[170:173], v[186:189], v[24:27]
	v_mfma_f32_16x16x32_bf16 v[12:15], v[162:165], v[194:197], v[12:15]
	v_mfma_f32_16x16x32_bf16 v[8:11], v[170:173], v[194:197], v[8:11]
	v_mfma_f32_16x16x32_bf16 v[4:7], v[162:165], v[204:207], v[4:7]
	v_mfma_f32_16x16x32_bf16 v[0:3], v[170:173], v[204:207], v[0:3]
	v_mfma_f32_16x16x32_bf16 v[44:47], v[166:169], v[182:185], v[44:47]
	v_mfma_f32_16x16x32_bf16 v[40:43], v[174:177], v[182:185], v[40:43]
	v_mfma_f32_16x16x32_bf16 v[28:31], v[166:169], v[190:193], v[28:31]
	v_mfma_f32_16x16x32_bf16 v[24:27], v[174:177], v[190:193], v[24:27]
	v_mfma_f32_16x16x32_bf16 v[12:15], v[166:169], v[198:201], v[12:15]
	v_mfma_f32_16x16x32_bf16 v[8:11], v[174:177], v[198:201], v[8:11]
	v_mfma_f32_16x16x32_bf16 v[4:7], v[166:169], v[208:211], v[4:7]
	v_mfma_f32_16x16x32_bf16 v[0:3], v[174:177], v[208:211], v[0:3]
	s_barrier
	v_add_u32_e32 v145, s68, v137
	ds_read_b128 v[146:149], v145
	ds_read_b128 v[150:153], v145 offset:1024
	ds_read_b128 v[154:157], v145 offset:2048
	ds_read_b128 v[158:161], v145 offset:3072
	v_add_u32_e32 v145, s67, v137
	ds_read_b128 v[162:165], v145
	ds_read_b128 v[166:169], v145 offset:1024
	ds_read_b128 v[170:173], v145 offset:2048
	ds_read_b128 v[174:177], v145 offset:3072
	s_mov_b32 m0, s57
	v_lshl_add_u64 v[218:219], s[46:47], 0, v[128:129]
	ds_read_b128 v[178:181], v141 offset:32768
	ds_read_b128 v[182:185], v141 offset:33792
	ds_read_b128 v[186:189], v141 offset:34816
	ds_read_b128 v[190:193], v141 offset:35840
	ds_read_b128 v[194:197], v141 offset:36864
	ds_read_b128 v[198:201], v141 offset:37888
	ds_read_b128 v[204:207], v141 offset:38912
	ds_read_b128 v[208:211], v141 offset:39936
	global_load_lds_dwordx4 v[218:219], off
	v_lshl_add_u64 v[218:219], s[46:47], 0, v[132:133]
	s_mov_b32 m0, s58
	s_nop 0
	global_load_lds_dwordx4 v[218:219], off
	s_waitcnt vmcnt(8)
	s_waitcnt lgkmcnt(0)
	s_barrier
	s_waitcnt lgkmcnt(0)
	v_mfma_f32_16x16x32_bf16 v[124:127], v[146:149], v[178:181], v[124:127]
	v_mfma_f32_16x16x32_bf16 v[120:123], v[154:157], v[178:181], v[120:123]
	v_mfma_f32_16x16x32_bf16 v[116:119], v[146:149], v[186:189], v[116:119]
	v_mfma_f32_16x16x32_bf16 v[112:115], v[154:157], v[186:189], v[112:115]
	v_mfma_f32_16x16x32_bf16 v[100:103], v[146:149], v[194:197], v[100:103]
	v_mfma_f32_16x16x32_bf16 v[96:99], v[154:157], v[194:197], v[96:99]
	v_mfma_f32_16x16x32_bf16 v[84:87], v[146:149], v[204:207], v[84:87]
	v_mfma_f32_16x16x32_bf16 v[80:83], v[154:157], v[204:207], v[80:83]
	v_mfma_f32_16x16x32_bf16 v[124:127], v[150:153], v[182:185], v[124:127]
	v_mfma_f32_16x16x32_bf16 v[120:123], v[158:161], v[182:185], v[120:123]
	v_mfma_f32_16x16x32_bf16 v[116:119], v[150:153], v[190:193], v[116:119]
	v_mfma_f32_16x16x32_bf16 v[112:115], v[158:161], v[190:193], v[112:115]
	v_mfma_f32_16x16x32_bf16 v[100:103], v[150:153], v[198:201], v[100:103]
	v_mfma_f32_16x16x32_bf16 v[96:99], v[158:161], v[198:201], v[96:99]
	v_mfma_f32_16x16x32_bf16 v[84:87], v[150:153], v[208:211], v[84:87]
	v_mfma_f32_16x16x32_bf16 v[80:83], v[158:161], v[208:211], v[80:83]
	v_mfma_f32_16x16x32_bf16 v[108:111], v[162:165], v[178:181], v[108:111]
	v_mfma_f32_16x16x32_bf16 v[104:107], v[170:173], v[178:181], v[104:107]
	v_mfma_f32_16x16x32_bf16 v[92:95], v[162:165], v[186:189], v[92:95]
	v_mfma_f32_16x16x32_bf16 v[88:91], v[170:173], v[186:189], v[88:91]
	v_mfma_f32_16x16x32_bf16 v[76:79], v[162:165], v[194:197], v[76:79]
	v_mfma_f32_16x16x32_bf16 v[72:75], v[170:173], v[194:197], v[72:75]
	v_mfma_f32_16x16x32_bf16 v[68:71], v[162:165], v[204:207], v[68:71]
	v_mfma_f32_16x16x32_bf16 v[64:67], v[170:173], v[204:207], v[64:67]
	v_mfma_f32_16x16x32_bf16 v[108:111], v[166:169], v[182:185], v[108:111]
	v_mfma_f32_16x16x32_bf16 v[104:107], v[174:177], v[182:185], v[104:107]
	v_mfma_f32_16x16x32_bf16 v[92:95], v[166:169], v[190:193], v[92:95]
	v_mfma_f32_16x16x32_bf16 v[88:91], v[174:177], v[190:193], v[88:91]
	v_mfma_f32_16x16x32_bf16 v[76:79], v[166:169], v[198:201], v[76:79]
	v_mfma_f32_16x16x32_bf16 v[72:75], v[174:177], v[198:201], v[72:75]
	v_mfma_f32_16x16x32_bf16 v[68:71], v[166:169], v[208:211], v[68:71]
	v_mfma_f32_16x16x32_bf16 v[64:67], v[174:177], v[208:211], v[64:67]
	s_barrier
; #define PG8_STAGE(bufoff, gbase, voff) do { _Pragma("unroll") for (int _i = 0; _i < 2; ++_i) \
;         __builtin_amdgcn_global_load_lds((const unsigned*)((const char*)(gbase) + (voff)[_i]), (LAS unsigned*)(lds + (bufoff) + ldsw + _i * 8192), 16, 0, 0); } while (0)
; #define PG8_LDA(dst, b, h) do { _Pragma("unroll") for (int m = 0; m < 4; ++m) _Pragma("unroll") for (int k = 0; k < 2; ++k) dst[m][k] = *(const LAS bf16x8*)(lds + PG8_SA(b, h) + aoff + m * 2048 + k * 1024); } while (0)
; #define PG8_MMA(ai, bj, At, Bt) do { __builtin_amdgcn_s_setprio(1); _Pragma("unroll") for (int m = 0; m < 4; ++m) _Pragma("unroll") for (int n = 0; n < 2; ++n) _Pragma("unroll") for (int k = 0; k < 2; ++k) \
;         acc[ai][bj][m][n] = __builtin_amdgcn_mfma_f32_16x16x32_bf16(Bt[n][k], At[m][k], acc[ai][bj][m][n], 0, 0, 0); __builtin_amdgcn_s_setprio(0); } while (0)
; #define PG8_WAIT_V(n) asm volatile("s_waitcnt vmcnt(" #n ")" ::: "memory")
; #define PG8_WAIT_L(n) asm volatile("s_waitcnt lgkmcnt(" #n ")" ::: "memory")
; #define PG8_BAR __builtin_amdgcn_s_barrier()
; #define PG8_SCHED __builtin_amdgcn_sched_barrier(0)
; template <class Epi>
; __device__ __forceinline__ void gemm_phase(LAS unsigned char* lds, const Gemm g, const Sched& S, const Epi& E) {
;     ...
;             PG8_LDA(At, 1, 1); PG8_STAGE(PG8_SB(1, 0), b3, voffB); PG8_STAGE(PG8_SB(1, 1), b3 + hstepB, voffB); PG8_STAGE(PG8_SA(1, 0), a3, voffA);
;             PG8_WAIT_V(8); PG8_WAIT_L(0); PG8_BAR; PG8_MMA(1, 0, At, B0); PG8_MMA(1, 1, At, B1); PG8_BAR; PG8_SCHED;
;         }
;         if (wr == 0) PG8_BAR;
;         if constexpr (!Epi::AFTER_DRAIN) { E(acc, cur, wr, wc, fr, fq); }
;         if (!has_next) break;
	s_mov_b32 m0, s66
	v_lshl_add_u64 v[142:143], v[142:143], 0, s[18:19]
	ds_read_b128 v[178:181], v141 offset:49152
	ds_read_b128 v[182:185], v141 offset:50176
	ds_read_b128 v[186:189], v141 offset:51200
	ds_read_b128 v[190:193], v141 offset:52224
	ds_read_b128 v[194:197], v141 offset:53248
	ds_read_b128 v[198:201], v141 offset:54272
	ds_read_b128 v[204:207], v141 offset:55296
	ds_read_b128 v[208:211], v141 offset:56320
	global_load_lds_dwordx4 v[142:143], off
	v_lshl_add_u64 v[142:143], v[212:213], 0, s[18:19]
	s_mov_b32 m0, s65
	s_nop 0
	global_load_lds_dwordx4 v[142:143], off
	v_lshl_add_u64 v[142:143], s[44:45], 0, v[130:131]
	s_mov_b32 m0, s74
	s_nop 0
	global_load_lds_dwordx4 v[142:143], off
	v_lshl_add_u64 v[142:143], s[44:45], 0, v[134:135]
	s_mov_b32 m0, s73
	s_nop 0
	global_load_lds_dwordx4 v[142:143], off
	v_lshl_add_u64 v[142:143], v[214:215], 0, s[18:19]
	s_mov_b32 m0, s60
	s_nop 0
	global_load_lds_dwordx4 v[142:143], off
	v_lshl_add_u64 v[142:143], v[216:217], 0, s[18:19]
	s_mov_b32 m0, s61
	s_nop 0
	global_load_lds_dwordx4 v[142:143], off
	s_waitcnt vmcnt(8)
	s_waitcnt lgkmcnt(0)
	s_barrier
	s_waitcnt lgkmcnt(0)
	v_mfma_f32_16x16x32_bf16 v[60:63], v[146:149], v[178:181], v[60:63]
	v_mfma_f32_16x16x32_bf16 v[56:59], v[154:157], v[178:181], v[56:59]
	v_mfma_f32_16x16x32_bf16 v[52:55], v[146:149], v[186:189], v[52:55]
	v_mfma_f32_16x16x32_bf16 v[48:51], v[154:157], v[186:189], v[48:51]
	v_mfma_f32_16x16x32_bf16 v[36:39], v[146:149], v[194:197], v[36:39]
	v_mfma_f32_16x16x32_bf16 v[32:35], v[154:157], v[194:197], v[32:35]
	v_mfma_f32_16x16x32_bf16 v[20:23], v[146:149], v[204:207], v[20:23]
	v_mfma_f32_16x16x32_bf16 v[16:19], v[154:157], v[204:207], v[16:19]
	v_mfma_f32_16x16x32_bf16 v[60:63], v[150:153], v[182:185], v[60:63]
	v_mfma_f32_16x16x32_bf16 v[56:59], v[158:161], v[182:185], v[56:59]
	v_mfma_f32_16x16x32_bf16 v[52:55], v[150:153], v[190:193], v[52:55]
	v_mfma_f32_16x16x32_bf16 v[48:51], v[158:161], v[190:193], v[48:51]
	v_mfma_f32_16x16x32_bf16 v[36:39], v[150:153], v[198:201], v[36:39]
	v_mfma_f32_16x16x32_bf16 v[32:35], v[158:161], v[198:201], v[32:35]
	v_mfma_f32_16x16x32_bf16 v[20:23], v[150:153], v[208:211], v[20:23]
	v_mfma_f32_16x16x32_bf16 v[16:19], v[158:161], v[208:211], v[16:19]
	v_mfma_f32_16x16x32_bf16 v[44:47], v[162:165], v[178:181], v[44:47]
	v_mfma_f32_16x16x32_bf16 v[40:43], v[170:173], v[178:181], v[40:43]
	v_mfma_f32_16x16x32_bf16 v[28:31], v[162:165], v[186:189], v[28:31]
	v_mfma_f32_16x16x32_bf16 v[24:27], v[170:173], v[186:189], v[24:27]
	v_mfma_f32_16x16x32_bf16 v[12:15], v[162:165], v[194:197], v[12:15]
	v_mfma_f32_16x16x32_bf16 v[8:11], v[170:173], v[194:197], v[8:11]
	v_mfma_f32_16x16x32_bf16 v[4:7], v[162:165], v[204:207], v[4:7]
	v_mfma_f32_16x16x32_bf16 v[0:3], v[170:173], v[204:207], v[0:3]
	v_mfma_f32_16x16x32_bf16 v[44:47], v[166:169], v[182:185], v[44:47]
	v_mfma_f32_16x16x32_bf16 v[40:43], v[174:177], v[182:185], v[40:43]
	v_mfma_f32_16x16x32_bf16 v[28:31], v[166:169], v[190:193], v[28:31]
	v_mfma_f32_16x16x32_bf16 v[24:27], v[174:177], v[190:193], v[24:27]
	v_mfma_f32_16x16x32_bf16 v[12:15], v[166:169], v[198:201], v[12:15]
	v_mfma_f32_16x16x32_bf16 v[8:11], v[174:177], v[198:201], v[8:11]
	v_mfma_f32_16x16x32_bf16 v[4:7], v[166:169], v[208:211], v[4:7]
	v_mfma_f32_16x16x32_bf16 v[0:3], v[174:177], v[208:211], v[0:3]
	s_movk_i32 s46, 0x100
	s_andn2_b64 vcc, exec, s[42:43]
	s_mov_b64 s[44:45], -1
	s_mov_b64 s[42:43], 0
	s_barrier
	s_cbranch_vccz .LBB0_1439
	s_and_b64 vcc, exec, s[20:21]
	s_cbranch_vccz .LBB0_1442
	s_barrier

; #define PG8_STAGE(bufoff, gbase, voff) do { _Pragma("unroll") for (int _i = 0; _i < 2; ++_i) \
;         __builtin_amdgcn_global_load_lds((const unsigned*)((const char*)(gbase) + (voff)[_i]), (LAS unsigned*)(lds + (bufoff) + ldsw + _i * 8192), 16, 0, 0); } while (0)
; #define PG8_LDA(dst, b, h) do { _Pragma("unroll") for (int m = 0; m < 4; ++m) _Pragma("unroll") for (int k = 0; k < 2; ++k) dst[m][k] = *(const LAS bf16x8*)(lds + PG8_SA(b, h) + aoff + m * 2048 + k * 1024); } while (0)
; #define PG8_LDB(dst, b, h) do { _Pragma("unroll") for (int n = 0; n < 2; ++n) _Pragma("unroll") for (int k = 0; k < 2; ++k) dst[n][k] = *(const LAS bf16x8*)(lds + PG8_SB(b, h) + boff + n * 2048 + k * 1024); } while (0)
; #define PG8_MMA(ai, bj, At, Bt) do { __builtin_amdgcn_s_setprio(1); _Pragma("unroll") for (int m = 0; m < 4; ++m) _Pragma("unroll") for (int n = 0; n < 2; ++n) _Pragma("unroll") for (int k = 0; k < 2; ++k) \
;         acc[ai][bj][m][n] = __builtin_amdgcn_mfma_f32_16x16x32_bf16(Bt[n][k], At[m][k], acc[ai][bj][m][n], 0, 0, 0); __builtin_amdgcn_s_setprio(0); } while (0)
; #define PG8_WAIT_V(n) asm volatile("s_waitcnt vmcnt(" #n ")" ::: "memory")
; #define PG8_WAIT_L(n) asm volatile("s_waitcnt lgkmcnt(" #n ")" ::: "memory")
; #define PG8_BAR __builtin_amdgcn_s_barrier()
; #define PG8_SCHED __builtin_amdgcn_sched_barrier(0)
; template <class Epi>
; __device__ __forceinline__ void gemm_phase(LAS unsigned char* lds, const Gemm g, const Sched& S, const Epi& E) {
;     ...
;         for (int t = 0; t < nt; t += 2) {
;             const bool last = (t == nt - 2);
;             const char* a1 = cA + (size_t)(t + 1) * kstep;
;             const char* a2 = last ? nA : cA + (size_t)(t + 2) * kstep; const char* b2 = last ? nB : cB + (size_t)(t + 2) * kstep;
;             const char* a3 = a2 + kstep; const char* b3 = b2 + kstep;
;             PG8_LDB(B0, 0, 0); PG8_LDB(B1, 0, 1); PG8_SCHED; PG8_LDA(At, 0, 0); PG8_STAGE(PG8_SA(1, 1), a1 + hstepA, voffA);
;             PG8_WAIT_V(8); PG8_WAIT_L(0); PG8_BAR; PG8_MMA(0, 0, At, B0); PG8_MMA(0, 1, At, B1); PG8_BAR; PG8_SCHED;
;             PG8_LDA(At, 0, 1); PG8_STAGE(PG8_SB(0, 0), b2, voffB); PG8_STAGE(PG8_SB(0, 1), b2 + hstepB, voffB); PG8_STAGE(PG8_SA(0, 0), a2, voffA);
;             PG8_WAIT_V(8); PG8_WAIT_L(0); PG8_BAR; PG8_MMA(1, 0, At, B0); PG8_MMA(1, 1, At, B1); PG8_BAR; PG8_SCHED;
.LBB0_1731:
	ds_read_b128 v[148:151], v145
	ds_read_b128 v[152:155], v145 offset:1024
	ds_read_b128 v[156:159], v145 offset:2048
	ds_read_b128 v[160:163], v145 offset:3072
	ds_read_b128 v[164:167], v146
	ds_read_b128 v[168:171], v146 offset:1024
	ds_read_b128 v[172:175], v146 offset:2048
	ds_read_b128 v[176:179], v146 offset:3072
	s_add_u32 s28, s26, 0xfffc0080
	s_addc_u32 s29, s27, -1
	s_cmp_eq_u32 s53, 12
	s_cselect_b32 s37, s17, s29
	s_cselect_b32 s36, s23, s28
	s_cselect_b32 s29, s15, s52
	s_cselect_b32 s28, s50, s51
	v_lshl_add_u64 v[140:141], s[26:27], 0, v[136:137]
	s_add_i32 m0, s25, 0xc000
	ds_read_b128 v[180:183], v147
	ds_read_b128 v[184:187], v147 offset:1024
	ds_read_b128 v[188:191], v147 offset:2048
	ds_read_b128 v[192:195], v147 offset:3072
	ds_read_b128 v[196:199], v147 offset:4096
	ds_read_b128 v[204:207], v147 offset:5120
	ds_read_b128 v[208:211], v147 offset:6144
	ds_read_b128 v[212:215], v147 offset:7168
	global_load_lds_dwordx4 v[140:141], off
	v_lshl_add_u64 v[140:141], s[26:27], 0, v[138:139]
	s_add_i32 m0, s25, 0xe000
	s_nop 0
	global_load_lds_dwordx4 v[140:141], off
	s_waitcnt vmcnt(8)
	s_waitcnt lgkmcnt(0)
	s_barrier
	s_waitcnt lgkmcnt(0)
	v_mfma_f32_16x16x32_bf16 v[116:119], v[148:151], v[180:183], v[116:119]
	v_mfma_f32_16x16x32_bf16 v[124:127], v[156:159], v[180:183], v[124:127]
	v_mfma_f32_16x16x32_bf16 v[100:103], v[148:151], v[188:191], v[100:103]
	v_mfma_f32_16x16x32_bf16 v[108:111], v[156:159], v[188:191], v[108:111]
	v_mfma_f32_16x16x32_bf16 v[84:87], v[148:151], v[196:199], v[84:87]
	v_mfma_f32_16x16x32_bf16 v[92:95], v[156:159], v[196:199], v[92:95]
	v_mfma_f32_16x16x32_bf16 v[68:71], v[148:151], v[208:211], v[68:71]
	v_mfma_f32_16x16x32_bf16 v[76:79], v[156:159], v[208:211], v[76:79]
	v_mfma_f32_16x16x32_bf16 v[116:119], v[152:155], v[184:187], v[116:119]
	v_mfma_f32_16x16x32_bf16 v[124:127], v[160:163], v[184:187], v[124:127]
	v_mfma_f32_16x16x32_bf16 v[100:103], v[152:155], v[192:195], v[100:103]
	v_mfma_f32_16x16x32_bf16 v[108:111], v[160:163], v[192:195], v[108:111]
	v_mfma_f32_16x16x32_bf16 v[84:87], v[152:155], v[204:207], v[84:87]
	v_mfma_f32_16x16x32_bf16 v[92:95], v[160:163], v[204:207], v[92:95]
	v_mfma_f32_16x16x32_bf16 v[68:71], v[152:155], v[212:215], v[68:71]
	v_mfma_f32_16x16x32_bf16 v[76:79], v[160:163], v[212:215], v[76:79]
	v_mfma_f32_16x16x32_bf16 v[112:115], v[164:167], v[180:183], v[112:115]
	v_mfma_f32_16x16x32_bf16 v[120:123], v[172:175], v[180:183], v[120:123]
	v_mfma_f32_16x16x32_bf16 v[96:99], v[164:167], v[188:191], v[96:99]
	v_mfma_f32_16x16x32_bf16 v[104:107], v[172:175], v[188:191], v[104:107]
	v_mfma_f32_16x16x32_bf16 v[80:83], v[164:167], v[196:199], v[80:83]
	v_mfma_f32_16x16x32_bf16 v[88:91], v[172:175], v[196:199], v[88:91]
	v_mfma_f32_16x16x32_bf16 v[64:67], v[164:167], v[208:211], v[64:67]
	v_mfma_f32_16x16x32_bf16 v[72:75], v[172:175], v[208:211], v[72:75]
	v_mfma_f32_16x16x32_bf16 v[112:115], v[168:171], v[184:187], v[112:115]
	v_mfma_f32_16x16x32_bf16 v[120:123], v[176:179], v[184:187], v[120:123]
	v_mfma_f32_16x16x32_bf16 v[96:99], v[168:171], v[192:195], v[96:99]
	v_mfma_f32_16x16x32_bf16 v[104:107], v[176:179], v[192:195], v[104:107]
	v_mfma_f32_16x16x32_bf16 v[80:83], v[168:171], v[204:207], v[80:83]
	v_mfma_f32_16x16x32_bf16 v[88:91], v[176:179], v[204:207], v[88:91]
	v_mfma_f32_16x16x32_bf16 v[64:67], v[168:171], v[212:215], v[64:67]
	v_mfma_f32_16x16x32_bf16 v[72:75], v[176:179], v[212:215], v[72:75]
	s_barrier
	s_add_i32 s54, s46, s39
	v_lshl_add_u64 v[140:141], s[28:29], 0, v[130:131]
	s_mov_b32 m0, s54
	ds_read_b128 v[180:183], v147 offset:16384
	ds_read_b128 v[184:187], v147 offset:17408
	ds_read_b128 v[188:191], v147 offset:18432
	ds_read_b128 v[192:195], v147 offset:19456
	ds_read_b128 v[196:199], v147 offset:20480
	ds_read_b128 v[204:207], v147 offset:21504
	ds_read_b128 v[208:211], v147 offset:22528
	ds_read_b128 v[212:215], v147 offset:23552
	global_load_lds_dwordx4 v[140:141], off
	s_add_i32 m0, s54, 0x2000
	s_add_u32 s54, s28, 0x40000
	v_lshl_add_u64 v[200:201], s[28:29], 0, v[134:135]
	s_addc_u32 s55, s29, 0
	s_add_i32 s56, s47, s39
	global_load_lds_dwordx4 v[200:201], off
	v_lshl_add_u64 v[216:217], s[54:55], 0, v[130:131]
	s_mov_b32 m0, s56
	v_lshl_add_u64 v[218:219], s[36:37], 0, v[132:133]
	global_load_lds_dwordx4 v[216:217], off
	v_lshl_add_u64 v[216:217], s[54:55], 0, v[134:135]
	s_add_i32 m0, s56, 0x2000
	s_nop 0
	global_load_lds_dwordx4 v[216:217], off
	v_lshl_add_u64 v[216:217], s[36:37], 0, v[128:129]
	s_mov_b32 m0, s25
	s_nop 0
	global_load_lds_dwordx4 v[216:217], off
	s_mov_b32 m0, s40
	s_nop 0
	global_load_lds_dwordx4 v[218:219], off
	s_waitcnt vmcnt(8)
	s_waitcnt lgkmcnt(0)
	s_barrier
; #define PG8_STAGE(bufoff, gbase, voff) do { _Pragma("unroll") for (int _i = 0; _i < 2; ++_i) \
;         __builtin_amdgcn_global_load_lds((const unsigned*)((const char*)(gbase) + (voff)[_i]), (LAS unsigned*)(lds + (bufoff) + ldsw + _i * 8192), 16, 0, 0); } while (0)
; #define PG8_LDA(dst, b, h) do { _Pragma("unroll") for (int m = 0; m < 4; ++m) _Pragma("unroll") for (int k = 0; k < 2; ++k) dst[m][k] = *(const LAS bf16x8*)(lds + PG8_SA(b, h) + aoff + m * 2048 + k * 1024); } while (0)
; #define PG8_LDB(dst, b, h) do { _Pragma("unroll") for (int n = 0; n < 2; ++n) _Pragma("unroll") for (int k = 0; k < 2; ++k) dst[n][k] = *(const LAS bf16x8*)(lds + PG8_SB(b, h) + boff + n * 2048 + k * 1024); } while (0)
; #define PG8_MMA(ai, bj, At, Bt) do { __builtin_amdgcn_s_setprio(1); _Pragma("unroll") for (int m = 0; m < 4; ++m) _Pragma("unroll") for (int n = 0; n < 2; ++n) _Pragma("unroll") for (int k = 0; k < 2; ++k) \
;         acc[ai][bj][m][n] = __builtin_amdgcn_mfma_f32_16x16x32_bf16(Bt[n][k], At[m][k], acc[ai][bj][m][n], 0, 0, 0); __builtin_amdgcn_s_setprio(0); } while (0)
; #define PG8_WAIT_V(n) asm volatile("s_waitcnt vmcnt(" #n ")" ::: "memory")
; #define PG8_WAIT_L(n) asm volatile("s_waitcnt lgkmcnt(" #n ")" ::: "memory")
; #define PG8_BAR __builtin_amdgcn_s_barrier()
; #define PG8_SCHED __builtin_amdgcn_sched_barrier(0)
; template <class Epi>
; __device__ __forceinline__ void gemm_phase(LAS unsigned char* lds, const Gemm g, const Sched& S, const Epi& E) {
;     ...
;             PG8_WAIT_V(8); PG8_WAIT_L(0); PG8_BAR; PG8_MMA(1, 0, At, B0); PG8_MMA(1, 1, At, B1); PG8_BAR; PG8_SCHED;
;             PG8_LDB(B0, 1, 0); PG8_LDB(B1, 1, 1); PG8_SCHED; PG8_LDA(At, 1, 0); PG8_STAGE(PG8_SA(0, 1), a2 + hstepA, voffA);
;             PG8_WAIT_V(8); PG8_WAIT_L(0); PG8_BAR; PG8_MMA(0, 0, At, B0); PG8_MMA(0, 1, At, B1); PG8_BAR; PG8_SCHED;
	s_waitcnt lgkmcnt(0)
	v_mfma_f32_16x16x32_bf16 v[52:55], v[148:151], v[180:183], v[52:55]
	v_mfma_f32_16x16x32_bf16 v[60:63], v[156:159], v[180:183], v[60:63]
	v_mfma_f32_16x16x32_bf16 v[36:39], v[148:151], v[188:191], v[36:39]
	v_mfma_f32_16x16x32_bf16 v[44:47], v[156:159], v[188:191], v[44:47]
	v_mfma_f32_16x16x32_bf16 v[20:23], v[148:151], v[196:199], v[20:23]
	v_mfma_f32_16x16x32_bf16 v[28:31], v[156:159], v[196:199], v[28:31]
	v_mfma_f32_16x16x32_bf16 v[4:7], v[148:151], v[208:211], v[4:7]
	v_mfma_f32_16x16x32_bf16 v[12:15], v[156:159], v[208:211], v[12:15]
	v_mfma_f32_16x16x32_bf16 v[52:55], v[152:155], v[184:187], v[52:55]
	v_mfma_f32_16x16x32_bf16 v[60:63], v[160:163], v[184:187], v[60:63]
	v_mfma_f32_16x16x32_bf16 v[36:39], v[152:155], v[192:195], v[36:39]
	v_mfma_f32_16x16x32_bf16 v[44:47], v[160:163], v[192:195], v[44:47]
	v_mfma_f32_16x16x32_bf16 v[20:23], v[152:155], v[204:207], v[20:23]
	v_mfma_f32_16x16x32_bf16 v[28:31], v[160:163], v[204:207], v[28:31]
	v_mfma_f32_16x16x32_bf16 v[4:7], v[152:155], v[212:215], v[4:7]
	v_mfma_f32_16x16x32_bf16 v[12:15], v[160:163], v[212:215], v[12:15]
	v_mfma_f32_16x16x32_bf16 v[48:51], v[164:167], v[180:183], v[48:51]
	v_mfma_f32_16x16x32_bf16 v[56:59], v[172:175], v[180:183], v[56:59]
	v_mfma_f32_16x16x32_bf16 v[32:35], v[164:167], v[188:191], v[32:35]
	v_mfma_f32_16x16x32_bf16 v[40:43], v[172:175], v[188:191], v[40:43]
	v_mfma_f32_16x16x32_bf16 v[16:19], v[164:167], v[196:199], v[16:19]
	v_mfma_f32_16x16x32_bf16 v[24:27], v[172:175], v[196:199], v[24:27]
	v_mfma_f32_16x16x32_bf16 v[0:3], v[164:167], v[208:211], v[0:3]
	v_mfma_f32_16x16x32_bf16 v[8:11], v[172:175], v[208:211], v[8:11]
	v_mfma_f32_16x16x32_bf16 v[48:51], v[168:171], v[184:187], v[48:51]
	v_mfma_f32_16x16x32_bf16 v[56:59], v[176:179], v[184:187], v[56:59]
	v_mfma_f32_16x16x32_bf16 v[32:35], v[168:171], v[192:195], v[32:35]
	v_mfma_f32_16x16x32_bf16 v[40:43], v[176:179], v[192:195], v[40:43]
	v_mfma_f32_16x16x32_bf16 v[16:19], v[168:171], v[204:207], v[16:19]
	v_mfma_f32_16x16x32_bf16 v[24:27], v[176:179], v[204:207], v[24:27]
	v_mfma_f32_16x16x32_bf16 v[0:3], v[168:171], v[212:215], v[0:3]
	v_mfma_f32_16x16x32_bf16 v[8:11], v[176:179], v[212:215], v[8:11]
	s_barrier
	s_add_i32 s54, 0, 0x18000
	s_add_i32 s55, 0, 0x1c000
	v_add_u32_e32 v160, s54, v143
	v_add_u32_e32 v176, s55, v143
	ds_read_b128 v[148:151], v160
	ds_read_b128 v[152:155], v160 offset:1024
	ds_read_b128 v[156:159], v160 offset:2048
	ds_read_b128 v[160:163], v160 offset:3072
	ds_read_b128 v[164:167], v176
	ds_read_b128 v[168:171], v176 offset:1024
	ds_read_b128 v[172:175], v176 offset:2048
	ds_read_b128 v[176:179], v176 offset:3072
	s_add_u32 s36, s36, 0x40000
	s_addc_u32 s37, s37, 0
	s_mov_b32 m0, s41
	v_lshl_add_u64 v[220:221], s[36:37], 0, v[128:129]
	ds_read_b128 v[180:183], v147 offset:32768
	ds_read_b128 v[184:187], v147 offset:33792
	ds_read_b128 v[188:191], v147 offset:34816
	ds_read_b128 v[192:195], v147 offset:35840
	ds_read_b128 v[196:199], v147 offset:36864
	ds_read_b128 v[204:207], v147 offset:37888
	ds_read_b128 v[208:211], v147 offset:38912
	ds_read_b128 v[212:215], v147 offset:39936
	global_load_lds_dwordx4 v[220:221], off
	v_lshl_add_u64 v[220:221], s[36:37], 0, v[132:133]
	s_mov_b32 m0, s42
	s_nop 0
	global_load_lds_dwordx4 v[220:221], off
	s_waitcnt vmcnt(8)
	s_waitcnt lgkmcnt(0)
	s_barrier
	s_waitcnt lgkmcnt(0)
	v_mfma_f32_16x16x32_bf16 v[116:119], v[148:151], v[180:183], v[116:119]
	v_mfma_f32_16x16x32_bf16 v[124:127], v[156:159], v[180:183], v[124:127]
	v_mfma_f32_16x16x32_bf16 v[100:103], v[148:151], v[188:191], v[100:103]
	v_mfma_f32_16x16x32_bf16 v[108:111], v[156:159], v[188:191], v[108:111]
	v_mfma_f32_16x16x32_bf16 v[84:87], v[148:151], v[196:199], v[84:87]
	v_mfma_f32_16x16x32_bf16 v[92:95], v[156:159], v[196:199], v[92:95]
	v_mfma_f32_16x16x32_bf16 v[68:71], v[148:151], v[208:211], v[68:71]
	v_mfma_f32_16x16x32_bf16 v[76:79], v[156:159], v[208:211], v[76:79]
	v_mfma_f32_16x16x32_bf16 v[116:119], v[152:155], v[184:187], v[116:119]
	v_mfma_f32_16x16x32_bf16 v[124:127], v[160:163], v[184:187], v[124:127]
	v_mfma_f32_16x16x32_bf16 v[100:103], v[152:155], v[192:195], v[100:103]
	v_mfma_f32_16x16x32_bf16 v[108:111], v[160:163], v[192:195], v[108:111]
	v_mfma_f32_16x16x32_bf16 v[84:87], v[152:155], v[204:207], v[84:87]
	v_mfma_f32_16x16x32_bf16 v[92:95], v[160:163], v[204:207], v[92:95]
	v_mfma_f32_16x16x32_bf16 v[68:71], v[152:155], v[212:215], v[68:71]
	v_mfma_f32_16x16x32_bf16 v[76:79], v[160:163], v[212:215], v[76:79]
	v_mfma_f32_16x16x32_bf16 v[112:115], v[164:167], v[180:183], v[112:115]
	v_mfma_f32_16x16x32_bf16 v[120:123], v[172:175], v[180:183], v[120:123]
	v_mfma_f32_16x16x32_bf16 v[96:99], v[164:167], v[188:191], v[96:99]
	v_mfma_f32_16x16x32_bf16 v[104:107], v[172:175], v[188:191], v[104:107]
	v_mfma_f32_16x16x32_bf16 v[80:83], v[164:167], v[196:199], v[80:83]
	v_mfma_f32_16x16x32_bf16 v[88:91], v[172:175], v[196:199], v[88:91]
	v_mfma_f32_16x16x32_bf16 v[64:67], v[164:167], v[208:211], v[64:67]
	v_mfma_f32_16x16x32_bf16 v[72:75], v[172:175], v[208:211], v[72:75]
	v_mfma_f32_16x16x32_bf16 v[112:115], v[168:171], v[184:187], v[112:115]
	v_mfma_f32_16x16x32_bf16 v[120:123], v[176:179], v[184:187], v[120:123]
	v_mfma_f32_16x16x32_bf16 v[96:99], v[168:171], v[192:195], v[96:99]
	v_mfma_f32_16x16x32_bf16 v[104:107], v[176:179], v[192:195], v[104:107]
	v_mfma_f32_16x16x32_bf16 v[80:83], v[168:171], v[204:207], v[80:83]
	v_mfma_f32_16x16x32_bf16 v[88:91], v[176:179], v[204:207], v[88:91]
	v_mfma_f32_16x16x32_bf16 v[64:67], v[168:171], v[212:215], v[64:67]
	v_mfma_f32_16x16x32_bf16 v[72:75], v[176:179], v[212:215], v[72:75]
	s_barrier
; #define PG8_STAGE(bufoff, gbase, voff) do { _Pragma("unroll") for (int _i = 0; _i < 2; ++_i) \
;         __builtin_amdgcn_global_load_lds((const unsigned*)((const char*)(gbase) + (voff)[_i]), (LAS unsigned*)(lds + (bufoff) + ldsw + _i * 8192), 16, 0, 0); } while (0)
; #define PG8_LDA(dst, b, h) do { _Pragma("unroll") for (int m = 0; m < 4; ++m) _Pragma("unroll") for (int k = 0; k < 2; ++k) dst[m][k] = *(const LAS bf16x8*)(lds + PG8_SA(b, h) + aoff + m * 2048 + k * 1024); } while (0)
; #define PG8_MMA(ai, bj, At, Bt) do { __builtin_amdgcn_s_setprio(1); _Pragma("unroll") for (int m = 0; m < 4; ++m) _Pragma("unroll") for (int n = 0; n < 2; ++n) _Pragma("unroll") for (int k = 0; k < 2; ++k) \
;         acc[ai][bj][m][n] = __builtin_amdgcn_mfma_f32_16x16x32_bf16(Bt[n][k], At[m][k], acc[ai][bj][m][n], 0, 0, 0); __builtin_amdgcn_s_setprio(0); } while (0)
; #define PG8_WAIT_V(n) asm volatile("s_waitcnt vmcnt(" #n ")" ::: "memory")
; #define PG8_WAIT_L(n) asm volatile("s_waitcnt lgkmcnt(" #n ")" ::: "memory")
; #define PG8_BAR __builtin_amdgcn_s_barrier()
; #define PG8_SCHED __builtin_amdgcn_sched_barrier(0)
; template <class Epi>
; __device__ __forceinline__ void gemm_phase(LAS unsigned char* lds, const Gemm g, const Sched& S, const Epi& E) {
;     ...
;         for (int t = 0; t < nt; t += 2) {
;     ...
;             PG8_LDA(At, 1, 1); PG8_STAGE(PG8_SB(1, 0), b3, voffB); PG8_STAGE(PG8_SB(1, 1), b3 + hstepB, voffB); PG8_STAGE(PG8_SA(1, 0), a3, voffA);
;             PG8_WAIT_V(8); PG8_WAIT_L(0); PG8_BAR; PG8_MMA(1, 0, At, B0); PG8_MMA(1, 1, At, B1); PG8_BAR; PG8_SCHED;
;         }
	s_add_i32 s36, s54, s39
	v_lshl_add_u64 v[140:141], v[140:141], 0, s[4:5]
	s_mov_b32 m0, s36
	ds_read_b128 v[180:183], v147 offset:49152
	ds_read_b128 v[184:187], v147 offset:50176
	ds_read_b128 v[188:191], v147 offset:51200
	ds_read_b128 v[192:195], v147 offset:52224
	ds_read_b128 v[196:199], v147 offset:53248
	ds_read_b128 v[204:207], v147 offset:54272
	ds_read_b128 v[208:211], v147 offset:55296
	ds_read_b128 v[212:215], v147 offset:56320
	global_load_lds_dwordx4 v[140:141], off
	s_add_i32 m0, s36, 0x2000
	s_add_u32 s28, s28, 0x40080
	v_lshl_add_u64 v[140:141], v[200:201], 0, s[4:5]
	s_addc_u32 s29, s29, 0
	s_add_i32 s36, s55, s39
	global_load_lds_dwordx4 v[140:141], off
	v_lshl_add_u64 v[140:141], s[28:29], 0, v[130:131]
	s_mov_b32 m0, s36
	s_nop 0
	global_load_lds_dwordx4 v[140:141], off
	v_lshl_add_u64 v[140:141], s[28:29], 0, v[134:135]
	s_add_i32 m0, s36, 0x2000
	s_nop 0
	global_load_lds_dwordx4 v[140:141], off
	v_lshl_add_u64 v[140:141], v[216:217], 0, s[4:5]
	s_mov_b32 m0, s44
	s_nop 0
	global_load_lds_dwordx4 v[140:141], off
	v_lshl_add_u64 v[140:141], v[218:219], 0, s[4:5]
	s_mov_b32 m0, s45
	s_nop 0
	global_load_lds_dwordx4 v[140:141], off
	s_waitcnt vmcnt(8)
	s_waitcnt lgkmcnt(0)
	s_barrier
	s_waitcnt lgkmcnt(0)
	v_mfma_f32_16x16x32_bf16 v[52:55], v[148:151], v[180:183], v[52:55]
	v_mfma_f32_16x16x32_bf16 v[60:63], v[156:159], v[180:183], v[60:63]
	v_mfma_f32_16x16x32_bf16 v[36:39], v[148:151], v[188:191], v[36:39]
	v_mfma_f32_16x16x32_bf16 v[44:47], v[156:159], v[188:191], v[44:47]
	v_mfma_f32_16x16x32_bf16 v[20:23], v[148:151], v[196:199], v[20:23]
	v_mfma_f32_16x16x32_bf16 v[28:31], v[156:159], v[196:199], v[28:31]
	v_mfma_f32_16x16x32_bf16 v[4:7], v[148:151], v[208:211], v[4:7]
	v_mfma_f32_16x16x32_bf16 v[12:15], v[156:159], v[208:211], v[12:15]
	v_mfma_f32_16x16x32_bf16 v[52:55], v[152:155], v[184:187], v[52:55]
	v_mfma_f32_16x16x32_bf16 v[60:63], v[160:163], v[184:187], v[60:63]
	v_mfma_f32_16x16x32_bf16 v[36:39], v[152:155], v[192:195], v[36:39]
	v_mfma_f32_16x16x32_bf16 v[44:47], v[160:163], v[192:195], v[44:47]
	v_mfma_f32_16x16x32_bf16 v[20:23], v[152:155], v[204:207], v[20:23]
	v_mfma_f32_16x16x32_bf16 v[28:31], v[160:163], v[204:207], v[28:31]
	v_mfma_f32_16x16x32_bf16 v[4:7], v[152:155], v[212:215], v[4:7]
	v_mfma_f32_16x16x32_bf16 v[12:15], v[160:163], v[212:215], v[12:15]
	v_mfma_f32_16x16x32_bf16 v[48:51], v[164:167], v[180:183], v[48:51]
	v_mfma_f32_16x16x32_bf16 v[56:59], v[172:175], v[180:183], v[56:59]
	v_mfma_f32_16x16x32_bf16 v[32:35], v[164:167], v[188:191], v[32:35]
	v_mfma_f32_16x16x32_bf16 v[40:43], v[172:175], v[188:191], v[40:43]
	v_mfma_f32_16x16x32_bf16 v[16:19], v[164:167], v[196:199], v[16:19]
	v_mfma_f32_16x16x32_bf16 v[24:27], v[172:175], v[196:199], v[24:27]
	v_mfma_f32_16x16x32_bf16 v[0:3], v[164:167], v[208:211], v[0:3]
	v_mfma_f32_16x16x32_bf16 v[8:11], v[172:175], v[208:211], v[8:11]
	v_mfma_f32_16x16x32_bf16 v[48:51], v[168:171], v[184:187], v[48:51]
	v_mfma_f32_16x16x32_bf16 v[56:59], v[176:179], v[184:187], v[56:59]
	v_mfma_f32_16x16x32_bf16 v[32:35], v[168:171], v[192:195], v[32:35]
	v_mfma_f32_16x16x32_bf16 v[40:43], v[176:179], v[192:195], v[40:43]
	v_mfma_f32_16x16x32_bf16 v[16:19], v[168:171], v[204:207], v[16:19]
	v_mfma_f32_16x16x32_bf16 v[24:27], v[176:179], v[204:207], v[24:27]
	v_mfma_f32_16x16x32_bf16 v[0:3], v[168:171], v[212:215], v[0:3]
	v_mfma_f32_16x16x32_bf16 v[8:11], v[176:179], v[212:215], v[8:11]
	s_add_i32 s53, s53, 2
	s_add_u32 s26, s26, 0x100
	s_addc_u32 s27, s27, 0
	s_add_u32 s51, s51, 0x100
	s_addc_u32 s52, s52, 0
	s_cmp_gt_u32 s53, 13
	s_barrier
	s_cbranch_scc0 .LBB0_1731
	s_and_b64 vcc, exec, s[6:7]
	s_cbranch_vccz .LBB0_1734
	s_barrier

; #define PG8_STAGE(bufoff, gbase, voff) do { _Pragma("unroll") for (int _i = 0; _i < 2; ++_i) \
;         __builtin_amdgcn_global_load_lds((const unsigned*)((const char*)(gbase) + (voff)[_i]), (LAS unsigned*)(lds + (bufoff) + ldsw + _i * 8192), 16, 0, 0); } while (0)
; #define PG8_LDA(dst, b, h) do { _Pragma("unroll") for (int m = 0; m < 4; ++m) _Pragma("unroll") for (int k = 0; k < 2; ++k) dst[m][k] = *(const LAS bf16x8*)(lds + PG8_SA(b, h) + aoff + m * 2048 + k * 1024); } while (0)
; #define PG8_LDB(dst, b, h) do { _Pragma("unroll") for (int n = 0; n < 2; ++n) _Pragma("unroll") for (int k = 0; k < 2; ++k) dst[n][k] = *(const LAS bf16x8*)(lds + PG8_SB(b, h) + boff + n * 2048 + k * 1024); } while (0)
; #define PG8_MMA(ai, bj, At, Bt) do { __builtin_amdgcn_s_setprio(1); _Pragma("unroll") for (int m = 0; m < 4; ++m) _Pragma("unroll") for (int n = 0; n < 2; ++n) _Pragma("unroll") for (int k = 0; k < 2; ++k) \
;         acc[ai][bj][m][n] = __builtin_amdgcn_mfma_f32_16x16x32_bf16(Bt[n][k], At[m][k], acc[ai][bj][m][n], 0, 0, 0); __builtin_amdgcn_s_setprio(0); } while (0)
; #define PG8_WAIT_V(n) asm volatile("s_waitcnt vmcnt(" #n ")" ::: "memory")
; #define PG8_WAIT_L(n) asm volatile("s_waitcnt lgkmcnt(" #n ")" ::: "memory")
; #define PG8_BAR __builtin_amdgcn_s_barrier()
; #define PG8_SCHED __builtin_amdgcn_sched_barrier(0)
; template <class Epi>
; __device__ __forceinline__ void gemm_phase(LAS unsigned char* lds, const Gemm g, const Sched& S, const Epi& E) {
;     ...
;             PG8_LDB(B0, 0, 0); PG8_LDB(B1, 0, 1); PG8_SCHED; PG8_LDA(At, 0, 0); PG8_STAGE(PG8_SA(1, 1), a1 + hstepA, voffA);
;             PG8_WAIT_V(8); PG8_WAIT_L(0); PG8_BAR; PG8_MMA(0, 0, At, B0); PG8_MMA(0, 1, At, B1); PG8_BAR; PG8_SCHED;
;             PG8_LDA(At, 0, 1); PG8_STAGE(PG8_SB(0, 0), b2, voffB); PG8_STAGE(PG8_SB(0, 1), b2 + hstepB, voffB); PG8_STAGE(PG8_SA(0, 0), a2, voffA);
;             PG8_WAIT_V(8); PG8_WAIT_L(0); PG8_BAR; PG8_MMA(1, 0, At, B0); PG8_MMA(1, 1, At, B1); PG8_BAR; PG8_SCHED;
.LBB0_1827:
	v_add_u32_e32 v158, s54, v144
	v_add_u32_e32 v174, s55, v144
	s_add_u32 s36, s26, s28
	ds_read_b128 v[146:149], v158
	ds_read_b128 v[150:153], v158 offset:1024
	ds_read_b128 v[154:157], v158 offset:2048
	ds_read_b128 v[158:161], v158 offset:3072
	ds_read_b128 v[162:165], v174
	ds_read_b128 v[166:169], v174 offset:1024
	ds_read_b128 v[170:173], v174 offset:2048
	ds_read_b128 v[174:177], v174 offset:3072
	s_addc_u32 s37, s27, s29
	s_add_u32 s36, s36, 0x100
	s_addc_u32 s37, s37, 0
	s_add_u32 s66, s63, s28
	s_addc_u32 s67, s64, s29
	s_cmpk_eq_i32 s28, 0x1500
	s_cselect_b32 s39, s23, s37
	s_cselect_b32 s38, s22, s36
	s_cselect_b32 s37, s25, s67
	s_cselect_b32 s36, s24, s66
	s_mov_b32 m0, s56
	v_lshl_add_u64 v[214:215], v[140:141], 0, s[28:29]
	ds_read_b128 v[178:181], v145
	ds_read_b128 v[182:185], v145 offset:1024
	ds_read_b128 v[186:189], v145 offset:2048
	ds_read_b128 v[190:193], v145 offset:3072
	ds_read_b128 v[194:197], v145 offset:4096
	ds_read_b128 v[198:201], v145 offset:5120
	ds_read_b128 v[206:209], v145 offset:6144
	ds_read_b128 v[210:213], v145 offset:7168
	global_load_lds_dwordx4 v[214:215], off
	v_lshl_add_u64 v[214:215], v[142:143], 0, s[28:29]
	s_mov_b32 m0, s57
	s_nop 0
	global_load_lds_dwordx4 v[214:215], off
	s_waitcnt vmcnt(8)
	s_waitcnt lgkmcnt(0)
	s_barrier
	s_waitcnt lgkmcnt(0)
	v_mfma_f32_16x16x32_bf16 v[124:127], v[146:149], v[178:181], v[124:127]
	v_mfma_f32_16x16x32_bf16 v[120:123], v[154:157], v[178:181], v[120:123]
	v_mfma_f32_16x16x32_bf16 v[108:111], v[146:149], v[186:189], v[108:111]
	v_mfma_f32_16x16x32_bf16 v[104:107], v[154:157], v[186:189], v[104:107]
	v_mfma_f32_16x16x32_bf16 v[92:95], v[146:149], v[194:197], v[92:95]
	v_mfma_f32_16x16x32_bf16 v[88:91], v[154:157], v[194:197], v[88:91]
	v_mfma_f32_16x16x32_bf16 v[76:79], v[146:149], v[206:209], v[76:79]
	v_mfma_f32_16x16x32_bf16 v[72:75], v[154:157], v[206:209], v[72:75]
	v_mfma_f32_16x16x32_bf16 v[124:127], v[150:153], v[182:185], v[124:127]
	v_mfma_f32_16x16x32_bf16 v[120:123], v[158:161], v[182:185], v[120:123]
	v_mfma_f32_16x16x32_bf16 v[108:111], v[150:153], v[190:193], v[108:111]
	v_mfma_f32_16x16x32_bf16 v[104:107], v[158:161], v[190:193], v[104:107]
	v_mfma_f32_16x16x32_bf16 v[92:95], v[150:153], v[198:201], v[92:95]
	v_mfma_f32_16x16x32_bf16 v[88:91], v[158:161], v[198:201], v[88:91]
	v_mfma_f32_16x16x32_bf16 v[76:79], v[150:153], v[210:213], v[76:79]
	v_mfma_f32_16x16x32_bf16 v[72:75], v[158:161], v[210:213], v[72:75]
	v_mfma_f32_16x16x32_bf16 v[116:119], v[162:165], v[178:181], v[116:119]
	v_mfma_f32_16x16x32_bf16 v[112:115], v[170:173], v[178:181], v[112:115]
	v_mfma_f32_16x16x32_bf16 v[100:103], v[162:165], v[186:189], v[100:103]
	v_mfma_f32_16x16x32_bf16 v[96:99], v[170:173], v[186:189], v[96:99]
	v_mfma_f32_16x16x32_bf16 v[84:87], v[162:165], v[194:197], v[84:87]
	v_mfma_f32_16x16x32_bf16 v[80:83], v[170:173], v[194:197], v[80:83]
	v_mfma_f32_16x16x32_bf16 v[68:71], v[162:165], v[206:209], v[68:71]
	v_mfma_f32_16x16x32_bf16 v[64:67], v[170:173], v[206:209], v[64:67]
	v_mfma_f32_16x16x32_bf16 v[116:119], v[166:169], v[182:185], v[116:119]
	v_mfma_f32_16x16x32_bf16 v[112:115], v[174:177], v[182:185], v[112:115]
	v_mfma_f32_16x16x32_bf16 v[100:103], v[166:169], v[190:193], v[100:103]
	v_mfma_f32_16x16x32_bf16 v[96:99], v[174:177], v[190:193], v[96:99]
	v_mfma_f32_16x16x32_bf16 v[84:87], v[166:169], v[198:201], v[84:87]
	v_mfma_f32_16x16x32_bf16 v[80:83], v[174:177], v[198:201], v[80:83]
	v_mfma_f32_16x16x32_bf16 v[68:71], v[166:169], v[210:213], v[68:71]
	v_mfma_f32_16x16x32_bf16 v[64:67], v[174:177], v[210:213], v[64:67]
	s_barrier
	s_mov_b32 m0, s58
	v_lshl_add_u64 v[214:215], s[36:37], 0, v[130:131]
	ds_read_b128 v[178:181], v145 offset:16384
	ds_read_b128 v[182:185], v145 offset:17408
	ds_read_b128 v[186:189], v145 offset:18432
	ds_read_b128 v[190:193], v145 offset:19456
	ds_read_b128 v[194:197], v145 offset:20480
	ds_read_b128 v[198:201], v145 offset:21504
	ds_read_b128 v[206:209], v145 offset:22528
	ds_read_b128 v[210:213], v145 offset:23552
	global_load_lds_dwordx4 v[214:215], off
	s_add_i32 m0, s58, 0x2000
	s_add_u32 s66, s36, 0xb0000
	v_lshl_add_u64 v[216:217], s[36:37], 0, v[134:135]
	s_addc_u32 s67, s37, 0
	s_add_i32 s68, s55, s46
	global_load_lds_dwordx4 v[216:217], off
	v_lshl_add_u64 v[218:219], s[66:67], 0, v[130:131]
	s_mov_b32 m0, s68
	v_lshl_add_u64 v[220:221], s[38:39], 0, v[132:133]
	global_load_lds_dwordx4 v[218:219], off
	v_lshl_add_u64 v[218:219], s[66:67], 0, v[134:135]
	s_add_i32 m0, s68, 0x2000
	s_nop 0
	global_load_lds_dwordx4 v[218:219], off
	v_lshl_add_u64 v[218:219], s[38:39], 0, v[128:129]
	s_mov_b32 m0, s47
	s_nop 0
	global_load_lds_dwordx4 v[218:219], off
	s_mov_b32 m0, s48
	s_nop 0
	global_load_lds_dwordx4 v[220:221], off
	s_waitcnt vmcnt(8)
	s_waitcnt lgkmcnt(0)
	s_barrier
; #define PG8_STAGE(bufoff, gbase, voff) do { _Pragma("unroll") for (int _i = 0; _i < 2; ++_i) \
;         __builtin_amdgcn_global_load_lds((const unsigned*)((const char*)(gbase) + (voff)[_i]), (LAS unsigned*)(lds + (bufoff) + ldsw + _i * 8192), 16, 0, 0); } while (0)
; #define PG8_LDA(dst, b, h) do { _Pragma("unroll") for (int m = 0; m < 4; ++m) _Pragma("unroll") for (int k = 0; k < 2; ++k) dst[m][k] = *(const LAS bf16x8*)(lds + PG8_SA(b, h) + aoff + m * 2048 + k * 1024); } while (0)
; #define PG8_LDB(dst, b, h) do { _Pragma("unroll") for (int n = 0; n < 2; ++n) _Pragma("unroll") for (int k = 0; k < 2; ++k) dst[n][k] = *(const LAS bf16x8*)(lds + PG8_SB(b, h) + boff + n * 2048 + k * 1024); } while (0)
; #define PG8_MMA(ai, bj, At, Bt) do { __builtin_amdgcn_s_setprio(1); _Pragma("unroll") for (int m = 0; m < 4; ++m) _Pragma("unroll") for (int n = 0; n < 2; ++n) _Pragma("unroll") for (int k = 0; k < 2; ++k) \
;         acc[ai][bj][m][n] = __builtin_amdgcn_mfma_f32_16x16x32_bf16(Bt[n][k], At[m][k], acc[ai][bj][m][n], 0, 0, 0); __builtin_amdgcn_s_setprio(0); } while (0)
; #define PG8_WAIT_V(n) asm volatile("s_waitcnt vmcnt(" #n ")" ::: "memory")
; #define PG8_WAIT_L(n) asm volatile("s_waitcnt lgkmcnt(" #n ")" ::: "memory")
; #define PG8_BAR __builtin_amdgcn_s_barrier()
; #define PG8_SCHED __builtin_amdgcn_sched_barrier(0)
; template <class Epi>
; __device__ __forceinline__ void gemm_phase(LAS unsigned char* lds, const Gemm g, const Sched& S, const Epi& E) {
;     ...
;             PG8_WAIT_V(8); PG8_WAIT_L(0); PG8_BAR; PG8_MMA(1, 0, At, B0); PG8_MMA(1, 1, At, B1); PG8_BAR; PG8_SCHED;
;             PG8_LDB(B0, 1, 0); PG8_LDB(B1, 1, 1); PG8_SCHED; PG8_LDA(At, 1, 0); PG8_STAGE(PG8_SA(0, 1), a2 + hstepA, voffA);
;             PG8_WAIT_V(8); PG8_WAIT_L(0); PG8_BAR; PG8_MMA(0, 0, At, B0); PG8_MMA(0, 1, At, B1); PG8_BAR; PG8_SCHED;
	s_waitcnt lgkmcnt(0)
	v_mfma_f32_16x16x32_bf16 v[60:63], v[146:149], v[178:181], v[60:63]
	v_mfma_f32_16x16x32_bf16 v[56:59], v[154:157], v[178:181], v[56:59]
	v_mfma_f32_16x16x32_bf16 v[44:47], v[146:149], v[186:189], v[44:47]
	v_mfma_f32_16x16x32_bf16 v[40:43], v[154:157], v[186:189], v[40:43]
	v_mfma_f32_16x16x32_bf16 v[28:31], v[146:149], v[194:197], v[28:31]
	v_mfma_f32_16x16x32_bf16 v[24:27], v[154:157], v[194:197], v[24:27]
	v_mfma_f32_16x16x32_bf16 v[12:15], v[146:149], v[206:209], v[12:15]
	v_mfma_f32_16x16x32_bf16 v[8:11], v[154:157], v[206:209], v[8:11]
	v_mfma_f32_16x16x32_bf16 v[60:63], v[150:153], v[182:185], v[60:63]
	v_mfma_f32_16x16x32_bf16 v[56:59], v[158:161], v[182:185], v[56:59]
	v_mfma_f32_16x16x32_bf16 v[44:47], v[150:153], v[190:193], v[44:47]
	v_mfma_f32_16x16x32_bf16 v[40:43], v[158:161], v[190:193], v[40:43]
	v_mfma_f32_16x16x32_bf16 v[28:31], v[150:153], v[198:201], v[28:31]
	v_mfma_f32_16x16x32_bf16 v[24:27], v[158:161], v[198:201], v[24:27]
	v_mfma_f32_16x16x32_bf16 v[12:15], v[150:153], v[210:213], v[12:15]
	v_mfma_f32_16x16x32_bf16 v[8:11], v[158:161], v[210:213], v[8:11]
	v_mfma_f32_16x16x32_bf16 v[52:55], v[162:165], v[178:181], v[52:55]
	v_mfma_f32_16x16x32_bf16 v[48:51], v[170:173], v[178:181], v[48:51]
	v_mfma_f32_16x16x32_bf16 v[36:39], v[162:165], v[186:189], v[36:39]
	v_mfma_f32_16x16x32_bf16 v[32:35], v[170:173], v[186:189], v[32:35]
	v_mfma_f32_16x16x32_bf16 v[20:23], v[162:165], v[194:197], v[20:23]
	v_mfma_f32_16x16x32_bf16 v[16:19], v[170:173], v[194:197], v[16:19]
	v_mfma_f32_16x16x32_bf16 v[4:7], v[162:165], v[206:209], v[4:7]
	v_mfma_f32_16x16x32_bf16 v[0:3], v[170:173], v[206:209], v[0:3]
	v_mfma_f32_16x16x32_bf16 v[52:55], v[166:169], v[182:185], v[52:55]
	v_mfma_f32_16x16x32_bf16 v[48:51], v[174:177], v[182:185], v[48:51]
	v_mfma_f32_16x16x32_bf16 v[36:39], v[166:169], v[190:193], v[36:39]
	v_mfma_f32_16x16x32_bf16 v[32:35], v[174:177], v[190:193], v[32:35]
	v_mfma_f32_16x16x32_bf16 v[20:23], v[166:169], v[198:201], v[20:23]
	v_mfma_f32_16x16x32_bf16 v[16:19], v[174:177], v[198:201], v[16:19]
	v_mfma_f32_16x16x32_bf16 v[4:7], v[166:169], v[210:213], v[4:7]
	v_mfma_f32_16x16x32_bf16 v[0:3], v[174:177], v[210:213], v[0:3]
	s_barrier
	s_add_i32 s66, 0, 0x18000
	s_add_i32 s67, 0, 0x1c000
	v_add_u32_e32 v158, s66, v144
	v_add_u32_e32 v174, s67, v144
	ds_read_b128 v[146:149], v158
	ds_read_b128 v[150:153], v158 offset:1024
	ds_read_b128 v[154:157], v158 offset:2048
	ds_read_b128 v[158:161], v158 offset:3072
	ds_read_b128 v[162:165], v174
	ds_read_b128 v[166:169], v174 offset:1024
	ds_read_b128 v[170:173], v174 offset:2048
	ds_read_b128 v[174:177], v174 offset:3072
	s_add_u32 s38, s38, 0xb0000
	s_addc_u32 s39, s39, 0
	s_mov_b32 m0, s49
	v_lshl_add_u64 v[222:223], s[38:39], 0, v[128:129]
	ds_read_b128 v[178:181], v145 offset:32768
	ds_read_b128 v[182:185], v145 offset:33792
	ds_read_b128 v[186:189], v145 offset:34816
	ds_read_b128 v[190:193], v145 offset:35840
	ds_read_b128 v[194:197], v145 offset:36864
	ds_read_b128 v[198:201], v145 offset:37888
	ds_read_b128 v[206:209], v145 offset:38912
	ds_read_b128 v[210:213], v145 offset:39936
	global_load_lds_dwordx4 v[222:223], off
	v_lshl_add_u64 v[222:223], s[38:39], 0, v[132:133]
	s_mov_b32 m0, s50
	s_nop 0
	global_load_lds_dwordx4 v[222:223], off
	s_waitcnt vmcnt(8)
	s_waitcnt lgkmcnt(0)
	s_barrier
	s_waitcnt lgkmcnt(0)
	v_mfma_f32_16x16x32_bf16 v[124:127], v[146:149], v[178:181], v[124:127]
	v_mfma_f32_16x16x32_bf16 v[120:123], v[154:157], v[178:181], v[120:123]
	v_mfma_f32_16x16x32_bf16 v[108:111], v[146:149], v[186:189], v[108:111]
	v_mfma_f32_16x16x32_bf16 v[104:107], v[154:157], v[186:189], v[104:107]
	v_mfma_f32_16x16x32_bf16 v[92:95], v[146:149], v[194:197], v[92:95]
	v_mfma_f32_16x16x32_bf16 v[88:91], v[154:157], v[194:197], v[88:91]
	v_mfma_f32_16x16x32_bf16 v[76:79], v[146:149], v[206:209], v[76:79]
	v_mfma_f32_16x16x32_bf16 v[72:75], v[154:157], v[206:209], v[72:75]
	v_mfma_f32_16x16x32_bf16 v[124:127], v[150:153], v[182:185], v[124:127]
	v_mfma_f32_16x16x32_bf16 v[120:123], v[158:161], v[182:185], v[120:123]
	v_mfma_f32_16x16x32_bf16 v[108:111], v[150:153], v[190:193], v[108:111]
	v_mfma_f32_16x16x32_bf16 v[104:107], v[158:161], v[190:193], v[104:107]
	v_mfma_f32_16x16x32_bf16 v[92:95], v[150:153], v[198:201], v[92:95]
	v_mfma_f32_16x16x32_bf16 v[88:91], v[158:161], v[198:201], v[88:91]
	v_mfma_f32_16x16x32_bf16 v[76:79], v[150:153], v[210:213], v[76:79]
	v_mfma_f32_16x16x32_bf16 v[72:75], v[158:161], v[210:213], v[72:75]
	v_mfma_f32_16x16x32_bf16 v[116:119], v[162:165], v[178:181], v[116:119]
	v_mfma_f32_16x16x32_bf16 v[112:115], v[170:173], v[178:181], v[112:115]
	v_mfma_f32_16x16x32_bf16 v[100:103], v[162:165], v[186:189], v[100:103]
	v_mfma_f32_16x16x32_bf16 v[96:99], v[170:173], v[186:189], v[96:99]
	v_mfma_f32_16x16x32_bf16 v[84:87], v[162:165], v[194:197], v[84:87]
	v_mfma_f32_16x16x32_bf16 v[80:83], v[170:173], v[194:197], v[80:83]
	v_mfma_f32_16x16x32_bf16 v[68:71], v[162:165], v[206:209], v[68:71]
	v_mfma_f32_16x16x32_bf16 v[64:67], v[170:173], v[206:209], v[64:67]
	v_mfma_f32_16x16x32_bf16 v[116:119], v[166:169], v[182:185], v[116:119]
	v_mfma_f32_16x16x32_bf16 v[112:115], v[174:177], v[182:185], v[112:115]
	v_mfma_f32_16x16x32_bf16 v[100:103], v[166:169], v[190:193], v[100:103]
	v_mfma_f32_16x16x32_bf16 v[96:99], v[174:177], v[190:193], v[96:99]
	v_mfma_f32_16x16x32_bf16 v[84:87], v[166:169], v[198:201], v[84:87]
	v_mfma_f32_16x16x32_bf16 v[80:83], v[174:177], v[198:201], v[80:83]
	v_mfma_f32_16x16x32_bf16 v[68:71], v[166:169], v[210:213], v[68:71]
	v_mfma_f32_16x16x32_bf16 v[64:67], v[174:177], v[210:213], v[64:67]
	s_barrier
; #define PG8_STAGE(bufoff, gbase, voff) do { _Pragma("unroll") for (int _i = 0; _i < 2; ++_i) \
;         __builtin_amdgcn_global_load_lds((const unsigned*)((const char*)(gbase) + (voff)[_i]), (LAS unsigned*)(lds + (bufoff) + ldsw + _i * 8192), 16, 0, 0); } while (0)
; #define PG8_LDA(dst, b, h) do { _Pragma("unroll") for (int m = 0; m < 4; ++m) _Pragma("unroll") for (int k = 0; k < 2; ++k) dst[m][k] = *(const LAS bf16x8*)(lds + PG8_SA(b, h) + aoff + m * 2048 + k * 1024); } while (0)
; #define PG8_MMA(ai, bj, At, Bt) do { __builtin_amdgcn_s_setprio(1); _Pragma("unroll") for (int m = 0; m < 4; ++m) _Pragma("unroll") for (int n = 0; n < 2; ++n) _Pragma("unroll") for (int k = 0; k < 2; ++k) \
;         acc[ai][bj][m][n] = __builtin_amdgcn_mfma_f32_16x16x32_bf16(Bt[n][k], At[m][k], acc[ai][bj][m][n], 0, 0, 0); __builtin_amdgcn_s_setprio(0); } while (0)
; #define PG8_WAIT_V(n) asm volatile("s_waitcnt vmcnt(" #n ")" ::: "memory")
; #define PG8_WAIT_L(n) asm volatile("s_waitcnt lgkmcnt(" #n ")" ::: "memory")
; #define PG8_BAR __builtin_amdgcn_s_barrier()
; #define PG8_SCHED __builtin_amdgcn_sched_barrier(0)
; template <class Epi>
; __device__ __forceinline__ void gemm_phase(LAS unsigned char* lds, const Gemm g, const Sched& S, const Epi& E) {
;     ...
;         for (int t = 0; t < nt; t += 2) {
;     ...
;             PG8_LDA(At, 1, 1); PG8_STAGE(PG8_SB(1, 0), b3, voffB); PG8_STAGE(PG8_SB(1, 1), b3 + hstepB, voffB); PG8_STAGE(PG8_SA(1, 0), a3, voffA);
;             PG8_WAIT_V(8); PG8_WAIT_L(0); PG8_BAR; PG8_MMA(1, 0, At, B0); PG8_MMA(1, 1, At, B1); PG8_BAR; PG8_SCHED;
;         }
	s_add_i32 s38, s66, s46
	v_lshl_add_u64 v[214:215], v[214:215], 0, s[16:17]
	s_mov_b32 m0, s38
	ds_read_b128 v[178:181], v145 offset:49152
	ds_read_b128 v[182:185], v145 offset:50176
	ds_read_b128 v[186:189], v145 offset:51200
	ds_read_b128 v[190:193], v145 offset:52224
	ds_read_b128 v[194:197], v145 offset:53248
	ds_read_b128 v[198:201], v145 offset:54272
	ds_read_b128 v[206:209], v145 offset:55296
	ds_read_b128 v[210:213], v145 offset:56320
	global_load_lds_dwordx4 v[214:215], off
	s_add_i32 m0, s38, 0x2000
	s_add_u32 s36, s36, 0xb0080
	v_lshl_add_u64 v[214:215], v[216:217], 0, s[16:17]
	s_addc_u32 s37, s37, 0
	s_add_i32 s38, s67, s46
	global_load_lds_dwordx4 v[214:215], off
	v_lshl_add_u64 v[214:215], s[36:37], 0, v[130:131]
	s_mov_b32 m0, s38
	s_nop 0
	global_load_lds_dwordx4 v[214:215], off
	v_lshl_add_u64 v[214:215], s[36:37], 0, v[134:135]
	s_add_i32 m0, s38, 0x2000
	s_nop 0
	global_load_lds_dwordx4 v[214:215], off
	v_lshl_add_u64 v[214:215], v[218:219], 0, s[16:17]
	s_mov_b32 m0, s52
	s_nop 0
	global_load_lds_dwordx4 v[214:215], off
	v_lshl_add_u64 v[214:215], v[220:221], 0, s[16:17]
	s_mov_b32 m0, s53
	s_nop 0
	global_load_lds_dwordx4 v[214:215], off
	s_waitcnt vmcnt(8)
	s_waitcnt lgkmcnt(0)
	s_barrier
	s_waitcnt lgkmcnt(0)
	v_mfma_f32_16x16x32_bf16 v[60:63], v[146:149], v[178:181], v[60:63]
	v_mfma_f32_16x16x32_bf16 v[56:59], v[154:157], v[178:181], v[56:59]
	v_mfma_f32_16x16x32_bf16 v[44:47], v[146:149], v[186:189], v[44:47]
	v_mfma_f32_16x16x32_bf16 v[40:43], v[154:157], v[186:189], v[40:43]
	v_mfma_f32_16x16x32_bf16 v[28:31], v[146:149], v[194:197], v[28:31]
	v_mfma_f32_16x16x32_bf16 v[24:27], v[154:157], v[194:197], v[24:27]
	v_mfma_f32_16x16x32_bf16 v[12:15], v[146:149], v[206:209], v[12:15]
	v_mfma_f32_16x16x32_bf16 v[8:11], v[154:157], v[206:209], v[8:11]
	v_mfma_f32_16x16x32_bf16 v[60:63], v[150:153], v[182:185], v[60:63]
	v_mfma_f32_16x16x32_bf16 v[56:59], v[158:161], v[182:185], v[56:59]
	v_mfma_f32_16x16x32_bf16 v[44:47], v[150:153], v[190:193], v[44:47]
	v_mfma_f32_16x16x32_bf16 v[40:43], v[158:161], v[190:193], v[40:43]
	v_mfma_f32_16x16x32_bf16 v[28:31], v[150:153], v[198:201], v[28:31]
	v_mfma_f32_16x16x32_bf16 v[24:27], v[158:161], v[198:201], v[24:27]
	v_mfma_f32_16x16x32_bf16 v[12:15], v[150:153], v[210:213], v[12:15]
	v_mfma_f32_16x16x32_bf16 v[8:11], v[158:161], v[210:213], v[8:11]
	v_mfma_f32_16x16x32_bf16 v[52:55], v[162:165], v[178:181], v[52:55]
	v_mfma_f32_16x16x32_bf16 v[48:51], v[170:173], v[178:181], v[48:51]
	v_mfma_f32_16x16x32_bf16 v[36:39], v[162:165], v[186:189], v[36:39]
	v_mfma_f32_16x16x32_bf16 v[32:35], v[170:173], v[186:189], v[32:35]
	v_mfma_f32_16x16x32_bf16 v[20:23], v[162:165], v[194:197], v[20:23]
	v_mfma_f32_16x16x32_bf16 v[16:19], v[170:173], v[194:197], v[16:19]
	v_mfma_f32_16x16x32_bf16 v[4:7], v[162:165], v[206:209], v[4:7]
	v_mfma_f32_16x16x32_bf16 v[0:3], v[170:173], v[206:209], v[0:3]
	v_mfma_f32_16x16x32_bf16 v[52:55], v[166:169], v[182:185], v[52:55]
	v_mfma_f32_16x16x32_bf16 v[48:51], v[174:177], v[182:185], v[48:51]
	v_mfma_f32_16x16x32_bf16 v[36:39], v[166:169], v[190:193], v[36:39]
	v_mfma_f32_16x16x32_bf16 v[32:35], v[174:177], v[190:193], v[32:35]
	v_mfma_f32_16x16x32_bf16 v[20:23], v[166:169], v[198:201], v[20:23]
	v_mfma_f32_16x16x32_bf16 v[16:19], v[174:177], v[198:201], v[16:19]
	v_mfma_f32_16x16x32_bf16 v[4:7], v[166:169], v[210:213], v[4:7]
	v_mfma_f32_16x16x32_bf16 v[0:3], v[174:177], v[210:213], v[0:3]
	s_add_i32 s65, s65, 2
	s_add_u32 s28, s28, 0x100
	s_addc_u32 s29, s29, 0
	s_cmp_gt_u32 s65, 41
	s_barrier
	s_cbranch_scc0 .LBB0_1827
	s_and_b64 vcc, exec, s[18:19]
	s_cbranch_vccz .LBB0_1830
	s_barrier
